# GEMM K-loops: 4 of the 6 LDS-DMA issues of the heavy load segments moved between the MFMAs of the following compute segment (vmcnt 8->4)
# baseline (speedup 1.0000x reference)
; #define PG8_STAGE(bufoff, gbase, voff) do { _Pragma("unroll") for (int _i = 0; _i < 2; ++_i) \
;         __builtin_amdgcn_global_load_lds((const unsigned*)((const char*)(gbase) + (voff)[_i]), (LAS unsigned*)(lds + (bufoff) + ldsw + _i * 8192), 16, 0, 0); } while (0)
; #define PG8_LDA(dst, b, h) do { _Pragma("unroll") for (int m = 0; m < 4; ++m) _Pragma("unroll") for (int k = 0; k < 2; ++k) dst[m][k] = *(const LAS bf16x8*)(lds + PG8_SA(b, h) + aoff + m * 2048 + k * 1024); } while (0)
; #define PG8_LDB(dst, b, h) do { _Pragma("unroll") for (int n = 0; n < 2; ++n) _Pragma("unroll") for (int k = 0; k < 2; ++k) dst[n][k] = *(const LAS bf16x8*)(lds + PG8_SB(b, h) + boff + n * 2048 + k * 1024); } while (0)
; #define PG8_MMA(ai, bj, At, Bt) do { __builtin_amdgcn_s_setprio(1); _Pragma("unroll") for (int m = 0; m < 4; ++m) _Pragma("unroll") for (int n = 0; n < 2; ++n) _Pragma("unroll") for (int k = 0; k < 2; ++k) \
;         acc[ai][bj][m][n] = __builtin_amdgcn_mfma_f32_16x16x32_bf16(Bt[n][k], At[m][k], acc[ai][bj][m][n], 0, 0, 0); __builtin_amdgcn_s_setprio(0); } while (0)
; #define PG8_WAIT_V(n) asm volatile("s_waitcnt vmcnt(" #n ")" ::: "memory")
; #define PG8_WAIT_L(n) asm volatile("s_waitcnt lgkmcnt(" #n ")" ::: "memory")
; #define PG8_BAR __builtin_amdgcn_s_barrier()
; #define PG8_SCHED __builtin_amdgcn_sched_barrier(0)
; template <class Epi, bool ALIGN_EPI>
; __device__ __forceinline__ void gemm_phase(LAS unsigned char* lds, const Gemm g, const StaticOrder& S, const Epi& E) {
;     ...
;             PG8_LDB(B0, 0, 0); PG8_LDB(B1, 0, 1); PG8_SCHED; PG8_LDA(At, 0, 0); PG8_STAGE(PG8_SA(1, 1), a1 + hA, voffA);
;             PG8_WAIT_V(8); PG8_WAIT_L(0); PG8_BAR; PG8_MMA(0, 0, At, B0); PG8_MMA(0, 1, At, B1); PG8_BAR; PG8_SCHED;
;             PG8_LDA(At, 0, 1); PG8_STAGE(PG8_SB(0, 0), b2, voffB); PG8_STAGE(PG8_SB(0, 1), b2 + hB, voffB); PG8_STAGE(PG8_SA(0, 0), a2, voffA);
;             PG8_WAIT_V(8); PG8_WAIT_L(0); PG8_BAR; PG8_MMA(1, 0, At, B0); PG8_MMA(1, 1, At, B1); PG8_BAR; PG8_SCHED;
.LBB0_252:
	ds_read_b128 v[168:171], v153
	ds_read_b128 v[172:175], v153 offset:1024
	ds_read_b128 v[176:179], v153 offset:2048
	ds_read_b128 v[180:183], v153 offset:3072
	ds_read_b128 v[184:187], v154
	ds_read_b128 v[188:191], v154 offset:1024
	ds_read_b128 v[194:197], v154 offset:2048
	ds_read_b128 v[198:201], v154 offset:3072
	s_add_u32 s8, s6, 0xfff80080
	s_addc_u32 s9, s7, -1
	s_cmp_eq_u32 s71, 28
	s_cselect_b32 s55, s47, s9
	s_cselect_b32 s54, s67, s8
	s_cselect_b32 s9, s45, s70
	s_cselect_b32 s8, s68, s69
	v_lshl_add_u64 v[234:235], s[6:7], 0, v[136:137]
	s_add_i32 m0, s39, 0xc000
	ds_read_b128 v[202:205], v155
	ds_read_b128 v[206:209], v155 offset:1024
	ds_read_b128 v[210:213], v155 offset:2048
	ds_read_b128 v[214:217], v155 offset:3072
	ds_read_b128 v[218:221], v155 offset:4096
	ds_read_b128 v[222:225], v155 offset:5120
	ds_read_b128 v[226:229], v155 offset:6144
	ds_read_b128 v[230:233], v155 offset:7168
	global_load_lds_dwordx4 v[234:235], off
	v_lshl_add_u64 v[234:235], s[6:7], 0, v[138:139]
	s_add_i32 m0, s39, 0xe000
	s_nop 0
	global_load_lds_dwordx4 v[234:235], off
	s_waitcnt vmcnt(8)
	s_waitcnt lgkmcnt(0)
	s_barrier
	s_setprio 1
	s_waitcnt lgkmcnt(0)
	v_mfma_f32_16x16x32_bf16 v[124:127], v[168:171], v[202:205], v[124:127]
	v_mfma_f32_16x16x32_bf16 v[124:127], v[172:175], v[206:209], v[124:127]
	v_mfma_f32_16x16x32_bf16 v[120:123], v[176:179], v[202:205], v[120:123]
	v_mfma_f32_16x16x32_bf16 v[120:123], v[180:183], v[206:209], v[120:123]
	v_mfma_f32_16x16x32_bf16 v[108:111], v[168:171], v[210:213], v[108:111]
	v_mfma_f32_16x16x32_bf16 v[108:111], v[172:175], v[214:217], v[108:111]
	v_mfma_f32_16x16x32_bf16 v[104:107], v[176:179], v[210:213], v[104:107]
	v_mfma_f32_16x16x32_bf16 v[104:107], v[180:183], v[214:217], v[104:107]
	v_mfma_f32_16x16x32_bf16 v[92:95], v[168:171], v[218:221], v[92:95]
	v_mfma_f32_16x16x32_bf16 v[92:95], v[172:175], v[222:225], v[92:95]
	v_mfma_f32_16x16x32_bf16 v[88:91], v[176:179], v[218:221], v[88:91]
	v_mfma_f32_16x16x32_bf16 v[88:91], v[180:183], v[222:225], v[88:91]
	v_mfma_f32_16x16x32_bf16 v[76:79], v[168:171], v[226:229], v[76:79]
	v_mfma_f32_16x16x32_bf16 v[76:79], v[172:175], v[230:233], v[76:79]
	v_mfma_f32_16x16x32_bf16 v[72:75], v[176:179], v[226:229], v[72:75]
	v_mfma_f32_16x16x32_bf16 v[72:75], v[180:183], v[230:233], v[72:75]
	s_setprio 0
	s_setprio 1
	v_mfma_f32_16x16x32_bf16 v[116:119], v[184:187], v[202:205], v[116:119]
	v_mfma_f32_16x16x32_bf16 v[116:119], v[188:191], v[206:209], v[116:119]
	v_mfma_f32_16x16x32_bf16 v[112:115], v[194:197], v[202:205], v[112:115]
	v_mfma_f32_16x16x32_bf16 v[112:115], v[198:201], v[206:209], v[112:115]
	v_mfma_f32_16x16x32_bf16 v[100:103], v[184:187], v[210:213], v[100:103]
	v_mfma_f32_16x16x32_bf16 v[100:103], v[188:191], v[214:217], v[100:103]
	v_mfma_f32_16x16x32_bf16 v[96:99], v[194:197], v[210:213], v[96:99]
	v_mfma_f32_16x16x32_bf16 v[96:99], v[198:201], v[214:217], v[96:99]
	v_mfma_f32_16x16x32_bf16 v[84:87], v[184:187], v[218:221], v[84:87]
	v_mfma_f32_16x16x32_bf16 v[84:87], v[188:191], v[222:225], v[84:87]
	v_mfma_f32_16x16x32_bf16 v[80:83], v[194:197], v[218:221], v[80:83]
	v_mfma_f32_16x16x32_bf16 v[80:83], v[198:201], v[222:225], v[80:83]
	v_mfma_f32_16x16x32_bf16 v[68:71], v[184:187], v[226:229], v[68:71]
	v_mfma_f32_16x16x32_bf16 v[68:71], v[188:191], v[230:233], v[68:71]
	v_mfma_f32_16x16x32_bf16 v[64:67], v[194:197], v[226:229], v[64:67]
	v_mfma_f32_16x16x32_bf16 v[64:67], v[198:201], v[230:233], v[64:67]
	s_setprio 0
	s_barrier
	s_add_i32 s72, s63, s33
	v_lshl_add_u64 v[234:235], s[8:9], 0, v[132:133]
	s_mov_b32 m0, s72
	ds_read_b128 v[202:205], v155 offset:16384
	ds_read_b128 v[206:209], v155 offset:17408
	ds_read_b128 v[210:213], v155 offset:18432
	ds_read_b128 v[214:217], v155 offset:19456
	ds_read_b128 v[218:221], v155 offset:20480
	ds_read_b128 v[222:225], v155 offset:21504
	ds_read_b128 v[226:229], v155 offset:22528
	ds_read_b128 v[230:233], v155 offset:23552
	global_load_lds_dwordx4 v[234:235], off
	s_add_i32 m0, s72, 0x2000
	s_add_u32 s72, s8, 0x80000
	v_lshl_add_u64 v[236:237], s[8:9], 0, v[128:129]
	s_addc_u32 s73, s9, 0
	s_add_i32 s74, s64, s33
	global_load_lds_dwordx4 v[236:237], off
	s_waitcnt vmcnt(4)
	s_waitcnt lgkmcnt(0)
	s_barrier
	s_setprio 1
	s_waitcnt lgkmcnt(0)
	v_mfma_f32_16x16x32_bf16 v[60:63], v[168:171], v[202:205], v[60:63]
	v_mfma_f32_16x16x32_bf16 v[60:63], v[172:175], v[206:209], v[60:63]
	v_mfma_f32_16x16x32_bf16 v[56:59], v[176:179], v[202:205], v[56:59]
	v_mfma_f32_16x16x32_bf16 v[56:59], v[180:183], v[206:209], v[56:59]
	v_lshl_add_u64 v[238:239], s[72:73], 0, v[132:133]
	s_mov_b32 m0, s74
	v_lshl_add_u64 v[240:241], s[54:55], 0, v[130:131]
	global_load_lds_dwordx4 v[238:239], off
	v_mfma_f32_16x16x32_bf16 v[48:51], v[168:171], v[210:213], v[48:51]
	v_mfma_f32_16x16x32_bf16 v[48:51], v[172:175], v[214:217], v[48:51]
	v_mfma_f32_16x16x32_bf16 v[40:43], v[176:179], v[210:213], v[40:43]
	v_mfma_f32_16x16x32_bf16 v[40:43], v[180:183], v[214:217], v[40:43]
	v_mfma_f32_16x16x32_bf16 v[32:35], v[168:171], v[218:221], v[32:35]
	v_mfma_f32_16x16x32_bf16 v[32:35], v[172:175], v[222:225], v[32:35]
	v_lshl_add_u64 v[238:239], s[72:73], 0, v[128:129]
	s_add_i32 m0, s74, 0x2000
	s_nop 0
	global_load_lds_dwordx4 v[238:239], off
	v_mfma_f32_16x16x32_bf16 v[24:27], v[176:179], v[218:221], v[24:27]
	v_mfma_f32_16x16x32_bf16 v[24:27], v[180:183], v[222:225], v[24:27]
	v_mfma_f32_16x16x32_bf16 v[16:19], v[168:171], v[226:229], v[16:19]
	v_mfma_f32_16x16x32_bf16 v[16:19], v[172:175], v[230:233], v[16:19]
	v_mfma_f32_16x16x32_bf16 v[8:11], v[176:179], v[226:229], v[8:11]
	v_mfma_f32_16x16x32_bf16 v[8:11], v[180:183], v[230:233], v[8:11]
	s_setprio 0
	s_setprio 1
	v_mfma_f32_16x16x32_bf16 v[52:55], v[184:187], v[202:205], v[52:55]
	v_mfma_f32_16x16x32_bf16 v[52:55], v[188:191], v[206:209], v[52:55]
	v_lshl_add_u64 v[238:239], s[54:55], 0, v[134:135]
	s_mov_b32 m0, s39
	s_nop 0
	global_load_lds_dwordx4 v[238:239], off
	v_mfma_f32_16x16x32_bf16 v[44:47], v[194:197], v[202:205], v[44:47]
	v_mfma_f32_16x16x32_bf16 v[44:47], v[198:201], v[206:209], v[44:47]
	v_mfma_f32_16x16x32_bf16 v[36:39], v[184:187], v[210:213], v[36:39]
	v_mfma_f32_16x16x32_bf16 v[36:39], v[188:191], v[214:217], v[36:39]
	v_mfma_f32_16x16x32_bf16 v[28:31], v[194:197], v[210:213], v[28:31]
	v_mfma_f32_16x16x32_bf16 v[28:31], v[198:201], v[214:217], v[28:31]
	s_mov_b32 m0, s53
	s_nop 0
	global_load_lds_dwordx4 v[240:241], off
	v_mfma_f32_16x16x32_bf16 v[20:23], v[184:187], v[218:221], v[20:23]
	v_mfma_f32_16x16x32_bf16 v[20:23], v[188:191], v[222:225], v[20:23]
	v_mfma_f32_16x16x32_bf16 v[12:15], v[194:197], v[218:221], v[12:15]
	v_mfma_f32_16x16x32_bf16 v[12:15], v[198:201], v[222:225], v[12:15]
	v_mfma_f32_16x16x32_bf16 v[4:7], v[184:187], v[226:229], v[4:7]
	v_mfma_f32_16x16x32_bf16 v[4:7], v[188:191], v[230:233], v[4:7]
	v_mfma_f32_16x16x32_bf16 v[0:3], v[194:197], v[226:229], v[0:3]
	v_mfma_f32_16x16x32_bf16 v[0:3], v[198:201], v[230:233], v[0:3]
	s_setprio 0
	s_barrier
; #define PG8_STAGE(bufoff, gbase, voff) do { _Pragma("unroll") for (int _i = 0; _i < 2; ++_i) \
;         __builtin_amdgcn_global_load_lds((const unsigned*)((const char*)(gbase) + (voff)[_i]), (LAS unsigned*)(lds + (bufoff) + ldsw + _i * 8192), 16, 0, 0); } while (0)
; #define PG8_LDA(dst, b, h) do { _Pragma("unroll") for (int m = 0; m < 4; ++m) _Pragma("unroll") for (int k = 0; k < 2; ++k) dst[m][k] = *(const LAS bf16x8*)(lds + PG8_SA(b, h) + aoff + m * 2048 + k * 1024); } while (0)
; #define PG8_LDB(dst, b, h) do { _Pragma("unroll") for (int n = 0; n < 2; ++n) _Pragma("unroll") for (int k = 0; k < 2; ++k) dst[n][k] = *(const LAS bf16x8*)(lds + PG8_SB(b, h) + boff + n * 2048 + k * 1024); } while (0)
; #define PG8_MMA(ai, bj, At, Bt) do { __builtin_amdgcn_s_setprio(1); _Pragma("unroll") for (int m = 0; m < 4; ++m) _Pragma("unroll") for (int n = 0; n < 2; ++n) _Pragma("unroll") for (int k = 0; k < 2; ++k) \
;         acc[ai][bj][m][n] = __builtin_amdgcn_mfma_f32_16x16x32_bf16(Bt[n][k], At[m][k], acc[ai][bj][m][n], 0, 0, 0); __builtin_amdgcn_s_setprio(0); } while (0)
; #define PG8_WAIT_V(n) asm volatile("s_waitcnt vmcnt(" #n ")" ::: "memory")
; #define PG8_WAIT_L(n) asm volatile("s_waitcnt lgkmcnt(" #n ")" ::: "memory")
; #define PG8_BAR __builtin_amdgcn_s_barrier()
; #define PG8_SCHED __builtin_amdgcn_sched_barrier(0)
; template <class Epi, bool ALIGN_EPI>
; __device__ __forceinline__ void gemm_phase(LAS unsigned char* lds, const Gemm g, const StaticOrder& S, const Epi& E) {
;     ...
;             PG8_LDB(B0, 1, 0); PG8_LDB(B1, 1, 1); PG8_SCHED; PG8_LDA(At, 1, 0); PG8_STAGE(PG8_SA(0, 1), a2 + hA, voffA);
;             PG8_WAIT_V(8); PG8_WAIT_L(0); PG8_BAR; PG8_MMA(0, 0, At, B0); PG8_MMA(0, 1, At, B1); PG8_BAR; PG8_SCHED;
	s_add_i32 s72, 0, 0x18000
	v_add_u32_e32 v167, s72, v149
	s_add_i32 s73, 0, 0x1c000
	ds_read_b128 v[168:171], v167
	ds_read_b128 v[172:175], v167 offset:1024
	ds_read_b128 v[176:179], v167 offset:2048
	ds_read_b128 v[180:183], v167 offset:3072
	v_add_u32_e32 v167, s73, v149
	ds_read_b128 v[184:187], v167
	ds_read_b128 v[188:191], v167 offset:1024
	ds_read_b128 v[194:197], v167 offset:2048
	ds_read_b128 v[198:201], v167 offset:3072
	s_add_u32 s54, s54, 0x80000
	s_addc_u32 s55, s55, 0
	s_mov_b32 m0, s56
	v_lshl_add_u64 v[242:243], s[54:55], 0, v[134:135]
	ds_read_b128 v[202:205], v155 offset:32768
	ds_read_b128 v[206:209], v155 offset:33792
	ds_read_b128 v[210:213], v155 offset:34816
	ds_read_b128 v[214:217], v155 offset:35840
	ds_read_b128 v[218:221], v155 offset:36864
	ds_read_b128 v[222:225], v155 offset:37888
	ds_read_b128 v[226:229], v155 offset:38912
	ds_read_b128 v[230:233], v155 offset:39936
	global_load_lds_dwordx4 v[242:243], off
	v_lshl_add_u64 v[242:243], s[54:55], 0, v[130:131]
	s_mov_b32 m0, s57
	s_nop 0
	global_load_lds_dwordx4 v[242:243], off
	s_waitcnt vmcnt(8)
	s_waitcnt lgkmcnt(0)
	s_barrier
	s_setprio 1
	s_waitcnt lgkmcnt(0)
	v_mfma_f32_16x16x32_bf16 v[124:127], v[168:171], v[202:205], v[124:127]
	v_mfma_f32_16x16x32_bf16 v[124:127], v[172:175], v[206:209], v[124:127]
	v_mfma_f32_16x16x32_bf16 v[120:123], v[176:179], v[202:205], v[120:123]
	v_mfma_f32_16x16x32_bf16 v[120:123], v[180:183], v[206:209], v[120:123]
	v_mfma_f32_16x16x32_bf16 v[108:111], v[168:171], v[210:213], v[108:111]
	v_mfma_f32_16x16x32_bf16 v[108:111], v[172:175], v[214:217], v[108:111]
	v_mfma_f32_16x16x32_bf16 v[104:107], v[176:179], v[210:213], v[104:107]
	v_mfma_f32_16x16x32_bf16 v[104:107], v[180:183], v[214:217], v[104:107]
	v_mfma_f32_16x16x32_bf16 v[92:95], v[168:171], v[218:221], v[92:95]
	v_mfma_f32_16x16x32_bf16 v[92:95], v[172:175], v[222:225], v[92:95]
	v_mfma_f32_16x16x32_bf16 v[88:91], v[176:179], v[218:221], v[88:91]
	v_mfma_f32_16x16x32_bf16 v[88:91], v[180:183], v[222:225], v[88:91]
	v_mfma_f32_16x16x32_bf16 v[76:79], v[168:171], v[226:229], v[76:79]
	v_mfma_f32_16x16x32_bf16 v[76:79], v[172:175], v[230:233], v[76:79]
	v_mfma_f32_16x16x32_bf16 v[72:75], v[176:179], v[226:229], v[72:75]
	v_mfma_f32_16x16x32_bf16 v[72:75], v[180:183], v[230:233], v[72:75]
	s_setprio 0
	s_setprio 1
	v_mfma_f32_16x16x32_bf16 v[116:119], v[184:187], v[202:205], v[116:119]
	v_mfma_f32_16x16x32_bf16 v[116:119], v[188:191], v[206:209], v[116:119]
	v_mfma_f32_16x16x32_bf16 v[112:115], v[194:197], v[202:205], v[112:115]
	v_mfma_f32_16x16x32_bf16 v[112:115], v[198:201], v[206:209], v[112:115]
	v_mfma_f32_16x16x32_bf16 v[100:103], v[184:187], v[210:213], v[100:103]
	v_mfma_f32_16x16x32_bf16 v[100:103], v[188:191], v[214:217], v[100:103]
	v_mfma_f32_16x16x32_bf16 v[96:99], v[194:197], v[210:213], v[96:99]
	v_mfma_f32_16x16x32_bf16 v[96:99], v[198:201], v[214:217], v[96:99]
	v_mfma_f32_16x16x32_bf16 v[84:87], v[184:187], v[218:221], v[84:87]
	v_mfma_f32_16x16x32_bf16 v[84:87], v[188:191], v[222:225], v[84:87]
	v_mfma_f32_16x16x32_bf16 v[80:83], v[194:197], v[218:221], v[80:83]
	v_mfma_f32_16x16x32_bf16 v[80:83], v[198:201], v[222:225], v[80:83]
	v_mfma_f32_16x16x32_bf16 v[68:71], v[184:187], v[226:229], v[68:71]
	v_mfma_f32_16x16x32_bf16 v[68:71], v[188:191], v[230:233], v[68:71]
	v_mfma_f32_16x16x32_bf16 v[64:67], v[194:197], v[226:229], v[64:67]
	v_mfma_f32_16x16x32_bf16 v[64:67], v[198:201], v[230:233], v[64:67]
	s_setprio 0
	s_barrier
; #define PG8_STAGE(bufoff, gbase, voff) do { _Pragma("unroll") for (int _i = 0; _i < 2; ++_i) \
;         __builtin_amdgcn_global_load_lds((const unsigned*)((const char*)(gbase) + (voff)[_i]), (LAS unsigned*)(lds + (bufoff) + ldsw + _i * 8192), 16, 0, 0); } while (0)
; #define PG8_LDA(dst, b, h) do { _Pragma("unroll") for (int m = 0; m < 4; ++m) _Pragma("unroll") for (int k = 0; k < 2; ++k) dst[m][k] = *(const LAS bf16x8*)(lds + PG8_SA(b, h) + aoff + m * 2048 + k * 1024); } while (0)
; #define PG8_MMA(ai, bj, At, Bt) do { __builtin_amdgcn_s_setprio(1); _Pragma("unroll") for (int m = 0; m < 4; ++m) _Pragma("unroll") for (int n = 0; n < 2; ++n) _Pragma("unroll") for (int k = 0; k < 2; ++k) \
;         acc[ai][bj][m][n] = __builtin_amdgcn_mfma_f32_16x16x32_bf16(Bt[n][k], At[m][k], acc[ai][bj][m][n], 0, 0, 0); __builtin_amdgcn_s_setprio(0); } while (0)
; #define PG8_WAIT_V(n) asm volatile("s_waitcnt vmcnt(" #n ")" ::: "memory")
; #define PG8_WAIT_L(n) asm volatile("s_waitcnt lgkmcnt(" #n ")" ::: "memory")
; #define PG8_BAR __builtin_amdgcn_s_barrier()
; #define PG8_SCHED __builtin_amdgcn_sched_barrier(0)
; template <class Epi, bool ALIGN_EPI>
; __device__ __forceinline__ void gemm_phase(LAS unsigned char* lds, const Gemm g, const StaticOrder& S, const Epi& E) {
;     ...
;         for (int t = 0; t < nt; t += 2) {
;     ...
;             PG8_LDA(At, 1, 1); PG8_STAGE(PG8_SB(1, 0), b3, voffB); PG8_STAGE(PG8_SB(1, 1), b3 + hB, voffB); PG8_STAGE(PG8_SA(1, 0), a3, voffA);
;             PG8_WAIT_V(8); PG8_WAIT_L(0); PG8_BAR; PG8_MMA(1, 0, At, B0); PG8_MMA(1, 1, At, B1); PG8_BAR; PG8_SCHED;
	s_add_i32 s54, s72, s33
	v_lshl_add_u64 v[234:235], v[234:235], 0, s[20:21]
	s_mov_b32 m0, s54
	ds_read_b128 v[202:205], v155 offset:49152
	ds_read_b128 v[206:209], v155 offset:50176
	ds_read_b128 v[210:213], v155 offset:51200
	ds_read_b128 v[214:217], v155 offset:52224
	ds_read_b128 v[218:221], v155 offset:53248
	ds_read_b128 v[222:225], v155 offset:54272
	ds_read_b128 v[226:229], v155 offset:55296
	ds_read_b128 v[230:233], v155 offset:56320
	global_load_lds_dwordx4 v[234:235], off
	s_add_i32 m0, s54, 0x2000
	s_add_u32 s8, s8, 0x80080
	v_lshl_add_u64 v[234:235], v[236:237], 0, s[20:21]
	s_addc_u32 s9, s9, 0
	s_add_i32 s54, s73, s33
	global_load_lds_dwordx4 v[234:235], off
	s_waitcnt vmcnt(4)
	s_waitcnt lgkmcnt(0)
	s_barrier
	s_setprio 1
	s_waitcnt lgkmcnt(0)
	v_mfma_f32_16x16x32_bf16 v[60:63], v[168:171], v[202:205], v[60:63]
	v_mfma_f32_16x16x32_bf16 v[60:63], v[172:175], v[206:209], v[60:63]
	v_mfma_f32_16x16x32_bf16 v[56:59], v[176:179], v[202:205], v[56:59]
	v_mfma_f32_16x16x32_bf16 v[56:59], v[180:183], v[206:209], v[56:59]
	v_lshl_add_u64 v[234:235], s[8:9], 0, v[132:133]
	s_mov_b32 m0, s54
	s_nop 0
	global_load_lds_dwordx4 v[234:235], off
	v_mfma_f32_16x16x32_bf16 v[48:51], v[168:171], v[210:213], v[48:51]
	v_mfma_f32_16x16x32_bf16 v[48:51], v[172:175], v[214:217], v[48:51]
	v_mfma_f32_16x16x32_bf16 v[40:43], v[176:179], v[210:213], v[40:43]
	v_mfma_f32_16x16x32_bf16 v[40:43], v[180:183], v[214:217], v[40:43]
	v_mfma_f32_16x16x32_bf16 v[32:35], v[168:171], v[218:221], v[32:35]
	v_mfma_f32_16x16x32_bf16 v[32:35], v[172:175], v[222:225], v[32:35]
	v_lshl_add_u64 v[234:235], s[8:9], 0, v[128:129]
	s_add_i32 m0, s54, 0x2000
	s_nop 0
	global_load_lds_dwordx4 v[234:235], off
	v_mfma_f32_16x16x32_bf16 v[24:27], v[176:179], v[218:221], v[24:27]
	v_mfma_f32_16x16x32_bf16 v[24:27], v[180:183], v[222:225], v[24:27]
	v_mfma_f32_16x16x32_bf16 v[16:19], v[168:171], v[226:229], v[16:19]
	v_mfma_f32_16x16x32_bf16 v[16:19], v[172:175], v[230:233], v[16:19]
	v_mfma_f32_16x16x32_bf16 v[8:11], v[176:179], v[226:229], v[8:11]
	v_mfma_f32_16x16x32_bf16 v[8:11], v[180:183], v[230:233], v[8:11]
	s_setprio 0
	s_setprio 1
	v_mfma_f32_16x16x32_bf16 v[52:55], v[184:187], v[202:205], v[52:55]
	v_mfma_f32_16x16x32_bf16 v[52:55], v[188:191], v[206:209], v[52:55]
	v_lshl_add_u64 v[234:235], v[238:239], 0, s[20:21]
	s_mov_b32 m0, s60
	s_nop 0
	global_load_lds_dwordx4 v[234:235], off
	v_mfma_f32_16x16x32_bf16 v[44:47], v[194:197], v[202:205], v[44:47]
	v_mfma_f32_16x16x32_bf16 v[44:47], v[198:201], v[206:209], v[44:47]
	v_mfma_f32_16x16x32_bf16 v[36:39], v[184:187], v[210:213], v[36:39]
	v_mfma_f32_16x16x32_bf16 v[36:39], v[188:191], v[214:217], v[36:39]
	v_mfma_f32_16x16x32_bf16 v[28:31], v[194:197], v[210:213], v[28:31]
	v_mfma_f32_16x16x32_bf16 v[28:31], v[198:201], v[214:217], v[28:31]
	v_lshl_add_u64 v[234:235], v[240:241], 0, s[20:21]
	s_mov_b32 m0, s61
	s_nop 0
	global_load_lds_dwordx4 v[234:235], off
	v_mfma_f32_16x16x32_bf16 v[20:23], v[184:187], v[218:221], v[20:23]
	v_mfma_f32_16x16x32_bf16 v[20:23], v[188:191], v[222:225], v[20:23]
	v_mfma_f32_16x16x32_bf16 v[12:15], v[194:197], v[218:221], v[12:15]
	v_mfma_f32_16x16x32_bf16 v[12:15], v[198:201], v[222:225], v[12:15]
	v_mfma_f32_16x16x32_bf16 v[4:7], v[184:187], v[226:229], v[4:7]
	v_mfma_f32_16x16x32_bf16 v[4:7], v[188:191], v[230:233], v[4:7]
	v_mfma_f32_16x16x32_bf16 v[0:3], v[194:197], v[226:229], v[0:3]
	v_mfma_f32_16x16x32_bf16 v[0:3], v[198:201], v[230:233], v[0:3]
	s_setprio 0
	s_barrier
	s_add_i32 s71, s71, 2
	s_add_u32 s6, s6, 0x100
	s_addc_u32 s7, s7, 0
	s_add_u32 s69, s69, 0x100
	s_addc_u32 s70, s70, 0
	s_cmp_gt_u32 s71, 29
	s_cbranch_scc0 .LBB0_252
	s_and_b64 vcc, exec, s[22:23]
	s_cbranch_vccz .LBB0_255
	s_barrier

; #define PG8_STAGE(bufoff, gbase, voff) do { _Pragma("unroll") for (int _i = 0; _i < 2; ++_i) \
;         __builtin_amdgcn_global_load_lds((const unsigned*)((const char*)(gbase) + (voff)[_i]), (LAS unsigned*)(lds + (bufoff) + ldsw + _i * 8192), 16, 0, 0); } while (0)
; #define PG8_LDA(dst, b, h) do { _Pragma("unroll") for (int m = 0; m < 4; ++m) _Pragma("unroll") for (int k = 0; k < 2; ++k) dst[m][k] = *(const LAS bf16x8*)(lds + PG8_SA(b, h) + aoff + m * 2048 + k * 1024); } while (0)
; #define PG8_LDB(dst, b, h) do { _Pragma("unroll") for (int n = 0; n < 2; ++n) _Pragma("unroll") for (int k = 0; k < 2; ++k) dst[n][k] = *(const LAS bf16x8*)(lds + PG8_SB(b, h) + boff + n * 2048 + k * 1024); } while (0)
; #define PG8_MMA(ai, bj, At, Bt) do { __builtin_amdgcn_s_setprio(1); _Pragma("unroll") for (int m = 0; m < 4; ++m) _Pragma("unroll") for (int n = 0; n < 2; ++n) _Pragma("unroll") for (int k = 0; k < 2; ++k) \
;         acc[ai][bj][m][n] = __builtin_amdgcn_mfma_f32_16x16x32_bf16(Bt[n][k], At[m][k], acc[ai][bj][m][n], 0, 0, 0); __builtin_amdgcn_s_setprio(0); } while (0)
; #define PG8_WAIT_V(n) asm volatile("s_waitcnt vmcnt(" #n ")" ::: "memory")
; #define PG8_WAIT_L(n) asm volatile("s_waitcnt lgkmcnt(" #n ")" ::: "memory")
; #define PG8_BAR __builtin_amdgcn_s_barrier()
; #define PG8_SCHED __builtin_amdgcn_sched_barrier(0)
; template <class Epi, bool ALIGN_EPI>
; __device__ __forceinline__ void gemm_phase(LAS unsigned char* lds, const Gemm g, const StaticOrder& S, const Epi& E) {
;     ...
;             PG8_LDB(B0, 0, 0); PG8_LDB(B1, 0, 1); PG8_SCHED; PG8_LDA(At, 0, 0); PG8_STAGE(PG8_SA(1, 1), a1 + hA, voffA);
;             PG8_WAIT_V(8); PG8_WAIT_L(0); PG8_BAR; PG8_MMA(0, 0, At, B0); PG8_MMA(0, 1, At, B1); PG8_BAR; PG8_SCHED;
;             PG8_LDA(At, 0, 1); PG8_STAGE(PG8_SB(0, 0), b2, voffB); PG8_STAGE(PG8_SB(0, 1), b2 + hB, voffB); PG8_STAGE(PG8_SA(0, 0), a2, voffA);
;             PG8_WAIT_V(8); PG8_WAIT_L(0); PG8_BAR; PG8_MMA(1, 0, At, B0); PG8_MMA(1, 1, At, B1); PG8_BAR; PG8_SCHED;
.LBB0_385:
	ds_read_b128 v[152:155], v149
	ds_read_b128 v[156:159], v149 offset:1024
	ds_read_b128 v[160:163], v149 offset:2048
	ds_read_b128 v[164:167], v149 offset:3072
	ds_read_b128 v[168:171], v150
	ds_read_b128 v[172:175], v150 offset:1024
	ds_read_b128 v[176:179], v150 offset:2048
	ds_read_b128 v[180:183], v150 offset:3072
	s_add_u32 s40, s36, 0xfff80080
	s_addc_u32 s41, s37, -1
	s_cmp_eq_u32 s61, 4
	s_cselect_b32 s43, s27, s41
	s_cselect_b32 s42, s57, s40
	s_cselect_b32 s41, s25, s60
	s_cselect_b32 s40, s58, s59
	v_lshl_add_u64 v[144:145], s[36:37], 0, v[136:137]
	s_add_i32 m0, s35, 0xc000
	ds_read_b128 v[184:187], v151
	ds_read_b128 v[188:191], v151 offset:1024
	ds_read_b128 v[194:197], v151 offset:2048
	ds_read_b128 v[198:201], v151 offset:3072
	ds_read_b128 v[202:205], v151 offset:4096
	ds_read_b128 v[206:209], v151 offset:5120
	ds_read_b128 v[210:213], v151 offset:6144
	ds_read_b128 v[214:217], v151 offset:7168
	global_load_lds_dwordx4 v[144:145], off
	v_lshl_add_u64 v[144:145], s[36:37], 0, v[138:139]
	s_add_i32 m0, s35, 0xe000
	s_nop 0
	global_load_lds_dwordx4 v[144:145], off
	s_waitcnt vmcnt(8)
	s_waitcnt lgkmcnt(0)
	s_barrier
	s_setprio 1
	s_waitcnt lgkmcnt(0)
	v_mfma_f32_16x16x32_bf16 v[124:127], v[152:155], v[184:187], v[124:127]
	v_mfma_f32_16x16x32_bf16 v[124:127], v[156:159], v[188:191], v[124:127]
	v_mfma_f32_16x16x32_bf16 v[120:123], v[160:163], v[184:187], v[120:123]
	v_mfma_f32_16x16x32_bf16 v[120:123], v[164:167], v[188:191], v[120:123]
	v_mfma_f32_16x16x32_bf16 v[116:119], v[152:155], v[194:197], v[116:119]
	v_mfma_f32_16x16x32_bf16 v[116:119], v[156:159], v[198:201], v[116:119]
	v_mfma_f32_16x16x32_bf16 v[108:111], v[160:163], v[194:197], v[108:111]
	v_mfma_f32_16x16x32_bf16 v[108:111], v[164:167], v[198:201], v[108:111]
	v_mfma_f32_16x16x32_bf16 v[100:103], v[152:155], v[202:205], v[100:103]
	v_mfma_f32_16x16x32_bf16 v[100:103], v[156:159], v[206:209], v[100:103]
	v_mfma_f32_16x16x32_bf16 v[92:95], v[160:163], v[202:205], v[92:95]
	v_mfma_f32_16x16x32_bf16 v[92:95], v[164:167], v[206:209], v[92:95]
	v_mfma_f32_16x16x32_bf16 v[84:87], v[152:155], v[210:213], v[84:87]
	v_mfma_f32_16x16x32_bf16 v[84:87], v[156:159], v[214:217], v[84:87]
	v_mfma_f32_16x16x32_bf16 v[76:79], v[160:163], v[210:213], v[76:79]
	v_mfma_f32_16x16x32_bf16 v[76:79], v[164:167], v[214:217], v[76:79]
	s_setprio 0
	s_setprio 1
	v_mfma_f32_16x16x32_bf16 v[112:115], v[168:171], v[184:187], v[112:115]
	v_mfma_f32_16x16x32_bf16 v[112:115], v[172:175], v[188:191], v[112:115]
	v_mfma_f32_16x16x32_bf16 v[104:107], v[176:179], v[184:187], v[104:107]
	v_mfma_f32_16x16x32_bf16 v[104:107], v[180:183], v[188:191], v[104:107]
	v_mfma_f32_16x16x32_bf16 v[96:99], v[168:171], v[194:197], v[96:99]
	v_mfma_f32_16x16x32_bf16 v[96:99], v[172:175], v[198:201], v[96:99]
	v_mfma_f32_16x16x32_bf16 v[88:91], v[176:179], v[194:197], v[88:91]
	v_mfma_f32_16x16x32_bf16 v[88:91], v[180:183], v[198:201], v[88:91]
	v_mfma_f32_16x16x32_bf16 v[80:83], v[168:171], v[202:205], v[80:83]
	v_mfma_f32_16x16x32_bf16 v[80:83], v[172:175], v[206:209], v[80:83]
	v_mfma_f32_16x16x32_bf16 v[72:75], v[176:179], v[202:205], v[72:75]
	v_mfma_f32_16x16x32_bf16 v[72:75], v[180:183], v[206:209], v[72:75]
	v_mfma_f32_16x16x32_bf16 v[68:71], v[168:171], v[210:213], v[68:71]
	v_mfma_f32_16x16x32_bf16 v[68:71], v[172:175], v[214:217], v[68:71]
	v_mfma_f32_16x16x32_bf16 v[64:67], v[176:179], v[210:213], v[64:67]
	v_mfma_f32_16x16x32_bf16 v[64:67], v[180:183], v[214:217], v[64:67]
	s_setprio 0
	s_barrier
	s_add_i32 s62, s53, s45
	v_lshl_add_u64 v[144:145], s[40:41], 0, v[132:133]
	s_mov_b32 m0, s62
	ds_read_b128 v[184:187], v151 offset:16384
	ds_read_b128 v[188:191], v151 offset:17408
	ds_read_b128 v[194:197], v151 offset:18432
	ds_read_b128 v[198:201], v151 offset:19456
	ds_read_b128 v[202:205], v151 offset:20480
	ds_read_b128 v[206:209], v151 offset:21504
	ds_read_b128 v[210:213], v151 offset:22528
	ds_read_b128 v[214:217], v151 offset:23552
	global_load_lds_dwordx4 v[144:145], off
	s_add_i32 m0, s62, 0x2000
	s_add_u32 s62, s40, 0x20000
	v_lshl_add_u64 v[218:219], s[40:41], 0, v[128:129]
	s_addc_u32 s63, s41, 0
	s_add_i32 s64, s54, s45
	global_load_lds_dwordx4 v[218:219], off
	s_waitcnt vmcnt(4)
	s_waitcnt lgkmcnt(0)
	s_barrier
	s_setprio 1
	s_waitcnt lgkmcnt(0)
	v_mfma_f32_16x16x32_bf16 v[60:63], v[152:155], v[184:187], v[60:63]
	v_mfma_f32_16x16x32_bf16 v[60:63], v[156:159], v[188:191], v[60:63]
	v_mfma_f32_16x16x32_bf16 v[56:59], v[160:163], v[184:187], v[56:59]
	v_mfma_f32_16x16x32_bf16 v[56:59], v[164:167], v[188:191], v[56:59]
	v_lshl_add_u64 v[220:221], s[62:63], 0, v[132:133]
	s_mov_b32 m0, s64
	v_lshl_add_u64 v[222:223], s[42:43], 0, v[130:131]
	global_load_lds_dwordx4 v[220:221], off
	v_mfma_f32_16x16x32_bf16 v[52:55], v[152:155], v[194:197], v[52:55]
	v_mfma_f32_16x16x32_bf16 v[52:55], v[156:159], v[198:201], v[52:55]
	v_mfma_f32_16x16x32_bf16 v[44:47], v[160:163], v[194:197], v[44:47]
	v_mfma_f32_16x16x32_bf16 v[44:47], v[164:167], v[198:201], v[44:47]
	v_mfma_f32_16x16x32_bf16 v[36:39], v[152:155], v[202:205], v[36:39]
	v_mfma_f32_16x16x32_bf16 v[36:39], v[156:159], v[206:209], v[36:39]
	v_lshl_add_u64 v[220:221], s[62:63], 0, v[128:129]
	s_add_i32 m0, s64, 0x2000
	s_nop 0
	global_load_lds_dwordx4 v[220:221], off
	v_mfma_f32_16x16x32_bf16 v[28:31], v[160:163], v[202:205], v[28:31]
	v_mfma_f32_16x16x32_bf16 v[28:31], v[164:167], v[206:209], v[28:31]
	v_mfma_f32_16x16x32_bf16 v[20:23], v[152:155], v[210:213], v[20:23]
	v_mfma_f32_16x16x32_bf16 v[20:23], v[156:159], v[214:217], v[20:23]
	v_mfma_f32_16x16x32_bf16 v[12:15], v[160:163], v[210:213], v[12:15]
	v_mfma_f32_16x16x32_bf16 v[12:15], v[164:167], v[214:217], v[12:15]
	s_setprio 0
	s_setprio 1
	v_mfma_f32_16x16x32_bf16 v[48:51], v[168:171], v[184:187], v[48:51]
	v_mfma_f32_16x16x32_bf16 v[48:51], v[172:175], v[188:191], v[48:51]
	v_lshl_add_u64 v[220:221], s[42:43], 0, v[134:135]
	s_mov_b32 m0, s35
	s_nop 0
	global_load_lds_dwordx4 v[220:221], off
	v_mfma_f32_16x16x32_bf16 v[40:43], v[176:179], v[184:187], v[40:43]
	v_mfma_f32_16x16x32_bf16 v[40:43], v[180:183], v[188:191], v[40:43]
	v_mfma_f32_16x16x32_bf16 v[32:35], v[168:171], v[194:197], v[32:35]
	v_mfma_f32_16x16x32_bf16 v[32:35], v[172:175], v[198:201], v[32:35]
	v_mfma_f32_16x16x32_bf16 v[24:27], v[176:179], v[194:197], v[24:27]
	v_mfma_f32_16x16x32_bf16 v[24:27], v[180:183], v[198:201], v[24:27]
	s_mov_b32 m0, s47
	s_nop 0
	global_load_lds_dwordx4 v[222:223], off
	v_mfma_f32_16x16x32_bf16 v[16:19], v[168:171], v[202:205], v[16:19]
	v_mfma_f32_16x16x32_bf16 v[16:19], v[172:175], v[206:209], v[16:19]
	v_mfma_f32_16x16x32_bf16 v[8:11], v[176:179], v[202:205], v[8:11]
	v_mfma_f32_16x16x32_bf16 v[8:11], v[180:183], v[206:209], v[8:11]
	v_mfma_f32_16x16x32_bf16 v[4:7], v[168:171], v[210:213], v[4:7]
	v_mfma_f32_16x16x32_bf16 v[4:7], v[172:175], v[214:217], v[4:7]
	v_mfma_f32_16x16x32_bf16 v[0:3], v[176:179], v[210:213], v[0:3]
	v_mfma_f32_16x16x32_bf16 v[0:3], v[180:183], v[214:217], v[0:3]
	s_setprio 0
	s_barrier
; #define PG8_STAGE(bufoff, gbase, voff) do { _Pragma("unroll") for (int _i = 0; _i < 2; ++_i) \
;         __builtin_amdgcn_global_load_lds((const unsigned*)((const char*)(gbase) + (voff)[_i]), (LAS unsigned*)(lds + (bufoff) + ldsw + _i * 8192), 16, 0, 0); } while (0)
; #define PG8_LDA(dst, b, h) do { _Pragma("unroll") for (int m = 0; m < 4; ++m) _Pragma("unroll") for (int k = 0; k < 2; ++k) dst[m][k] = *(const LAS bf16x8*)(lds + PG8_SA(b, h) + aoff + m * 2048 + k * 1024); } while (0)
; #define PG8_LDB(dst, b, h) do { _Pragma("unroll") for (int n = 0; n < 2; ++n) _Pragma("unroll") for (int k = 0; k < 2; ++k) dst[n][k] = *(const LAS bf16x8*)(lds + PG8_SB(b, h) + boff + n * 2048 + k * 1024); } while (0)
; #define PG8_MMA(ai, bj, At, Bt) do { __builtin_amdgcn_s_setprio(1); _Pragma("unroll") for (int m = 0; m < 4; ++m) _Pragma("unroll") for (int n = 0; n < 2; ++n) _Pragma("unroll") for (int k = 0; k < 2; ++k) \
;         acc[ai][bj][m][n] = __builtin_amdgcn_mfma_f32_16x16x32_bf16(Bt[n][k], At[m][k], acc[ai][bj][m][n], 0, 0, 0); __builtin_amdgcn_s_setprio(0); } while (0)
; #define PG8_WAIT_V(n) asm volatile("s_waitcnt vmcnt(" #n ")" ::: "memory")
; #define PG8_WAIT_L(n) asm volatile("s_waitcnt lgkmcnt(" #n ")" ::: "memory")
; #define PG8_BAR __builtin_amdgcn_s_barrier()
; #define PG8_SCHED __builtin_amdgcn_sched_barrier(0)
; template <class Epi, bool ALIGN_EPI>
; __device__ __forceinline__ void gemm_phase(LAS unsigned char* lds, const Gemm g, const StaticOrder& S, const Epi& E) {
;     ...
;             PG8_LDB(B0, 1, 0); PG8_LDB(B1, 1, 1); PG8_SCHED; PG8_LDA(At, 1, 0); PG8_STAGE(PG8_SA(0, 1), a2 + hA, voffA);
;             PG8_WAIT_V(8); PG8_WAIT_L(0); PG8_BAR; PG8_MMA(0, 0, At, B0); PG8_MMA(0, 1, At, B1); PG8_BAR; PG8_SCHED;
	s_add_i32 s62, 0, 0x18000
	s_add_i32 s63, 0, 0x1c000
	v_add_u32_e32 v164, s62, v147
	v_add_u32_e32 v180, s63, v147
	ds_read_b128 v[152:155], v164
	ds_read_b128 v[156:159], v164 offset:1024
	ds_read_b128 v[160:163], v164 offset:2048
	ds_read_b128 v[164:167], v164 offset:3072
	ds_read_b128 v[168:171], v180
	ds_read_b128 v[172:175], v180 offset:1024
	ds_read_b128 v[176:179], v180 offset:2048
	ds_read_b128 v[180:183], v180 offset:3072
	s_add_u32 s42, s42, 0x80000
	s_addc_u32 s43, s43, 0
	s_mov_b32 m0, s48
	v_lshl_add_u64 v[224:225], s[42:43], 0, v[134:135]
	ds_read_b128 v[184:187], v151 offset:32768
	ds_read_b128 v[188:191], v151 offset:33792
	ds_read_b128 v[194:197], v151 offset:34816
	ds_read_b128 v[198:201], v151 offset:35840
	ds_read_b128 v[202:205], v151 offset:36864
	ds_read_b128 v[206:209], v151 offset:37888
	ds_read_b128 v[210:213], v151 offset:38912
	ds_read_b128 v[214:217], v151 offset:39936
	global_load_lds_dwordx4 v[224:225], off
	v_lshl_add_u64 v[224:225], s[42:43], 0, v[130:131]
	s_mov_b32 m0, s49
	s_nop 0
	global_load_lds_dwordx4 v[224:225], off
	s_waitcnt vmcnt(8)
	s_waitcnt lgkmcnt(0)
	s_barrier
	s_setprio 1
	s_waitcnt lgkmcnt(0)
	v_mfma_f32_16x16x32_bf16 v[124:127], v[152:155], v[184:187], v[124:127]
	v_mfma_f32_16x16x32_bf16 v[124:127], v[156:159], v[188:191], v[124:127]
	v_mfma_f32_16x16x32_bf16 v[120:123], v[160:163], v[184:187], v[120:123]
	v_mfma_f32_16x16x32_bf16 v[120:123], v[164:167], v[188:191], v[120:123]
	v_mfma_f32_16x16x32_bf16 v[116:119], v[152:155], v[194:197], v[116:119]
	v_mfma_f32_16x16x32_bf16 v[116:119], v[156:159], v[198:201], v[116:119]
	v_mfma_f32_16x16x32_bf16 v[108:111], v[160:163], v[194:197], v[108:111]
	v_mfma_f32_16x16x32_bf16 v[108:111], v[164:167], v[198:201], v[108:111]
	v_mfma_f32_16x16x32_bf16 v[100:103], v[152:155], v[202:205], v[100:103]
	v_mfma_f32_16x16x32_bf16 v[100:103], v[156:159], v[206:209], v[100:103]
	v_mfma_f32_16x16x32_bf16 v[92:95], v[160:163], v[202:205], v[92:95]
	v_mfma_f32_16x16x32_bf16 v[92:95], v[164:167], v[206:209], v[92:95]
	v_mfma_f32_16x16x32_bf16 v[84:87], v[152:155], v[210:213], v[84:87]
	v_mfma_f32_16x16x32_bf16 v[84:87], v[156:159], v[214:217], v[84:87]
	v_mfma_f32_16x16x32_bf16 v[76:79], v[160:163], v[210:213], v[76:79]
	v_mfma_f32_16x16x32_bf16 v[76:79], v[164:167], v[214:217], v[76:79]
	s_setprio 0
	s_setprio 1
	v_mfma_f32_16x16x32_bf16 v[112:115], v[168:171], v[184:187], v[112:115]
	v_mfma_f32_16x16x32_bf16 v[112:115], v[172:175], v[188:191], v[112:115]
	v_mfma_f32_16x16x32_bf16 v[104:107], v[176:179], v[184:187], v[104:107]
	v_mfma_f32_16x16x32_bf16 v[104:107], v[180:183], v[188:191], v[104:107]
	v_mfma_f32_16x16x32_bf16 v[96:99], v[168:171], v[194:197], v[96:99]
	v_mfma_f32_16x16x32_bf16 v[96:99], v[172:175], v[198:201], v[96:99]
	v_mfma_f32_16x16x32_bf16 v[88:91], v[176:179], v[194:197], v[88:91]
	v_mfma_f32_16x16x32_bf16 v[88:91], v[180:183], v[198:201], v[88:91]
	v_mfma_f32_16x16x32_bf16 v[80:83], v[168:171], v[202:205], v[80:83]
	v_mfma_f32_16x16x32_bf16 v[80:83], v[172:175], v[206:209], v[80:83]
	v_mfma_f32_16x16x32_bf16 v[72:75], v[176:179], v[202:205], v[72:75]
	v_mfma_f32_16x16x32_bf16 v[72:75], v[180:183], v[206:209], v[72:75]
	v_mfma_f32_16x16x32_bf16 v[68:71], v[168:171], v[210:213], v[68:71]
	v_mfma_f32_16x16x32_bf16 v[68:71], v[172:175], v[214:217], v[68:71]
	v_mfma_f32_16x16x32_bf16 v[64:67], v[176:179], v[210:213], v[64:67]
	v_mfma_f32_16x16x32_bf16 v[64:67], v[180:183], v[214:217], v[64:67]
	s_setprio 0
	s_barrier
; #define PG8_STAGE(bufoff, gbase, voff) do { _Pragma("unroll") for (int _i = 0; _i < 2; ++_i) \
;         __builtin_amdgcn_global_load_lds((const unsigned*)((const char*)(gbase) + (voff)[_i]), (LAS unsigned*)(lds + (bufoff) + ldsw + _i * 8192), 16, 0, 0); } while (0)
; #define PG8_LDA(dst, b, h) do { _Pragma("unroll") for (int m = 0; m < 4; ++m) _Pragma("unroll") for (int k = 0; k < 2; ++k) dst[m][k] = *(const LAS bf16x8*)(lds + PG8_SA(b, h) + aoff + m * 2048 + k * 1024); } while (0)
; #define PG8_MMA(ai, bj, At, Bt) do { __builtin_amdgcn_s_setprio(1); _Pragma("unroll") for (int m = 0; m < 4; ++m) _Pragma("unroll") for (int n = 0; n < 2; ++n) _Pragma("unroll") for (int k = 0; k < 2; ++k) \
;         acc[ai][bj][m][n] = __builtin_amdgcn_mfma_f32_16x16x32_bf16(Bt[n][k], At[m][k], acc[ai][bj][m][n], 0, 0, 0); __builtin_amdgcn_s_setprio(0); } while (0)
; #define PG8_WAIT_V(n) asm volatile("s_waitcnt vmcnt(" #n ")" ::: "memory")
; #define PG8_WAIT_L(n) asm volatile("s_waitcnt lgkmcnt(" #n ")" ::: "memory")
; #define PG8_BAR __builtin_amdgcn_s_barrier()
; #define PG8_SCHED __builtin_amdgcn_sched_barrier(0)
; template <class Epi, bool ALIGN_EPI>
; __device__ __forceinline__ void gemm_phase(LAS unsigned char* lds, const Gemm g, const StaticOrder& S, const Epi& E) {
;     ...
;         for (int t = 0; t < nt; t += 2) {
;     ...
;             PG8_LDA(At, 1, 1); PG8_STAGE(PG8_SB(1, 0), b3, voffB); PG8_STAGE(PG8_SB(1, 1), b3 + hB, voffB); PG8_STAGE(PG8_SA(1, 0), a3, voffA);
;             PG8_WAIT_V(8); PG8_WAIT_L(0); PG8_BAR; PG8_MMA(1, 0, At, B0); PG8_MMA(1, 1, At, B1); PG8_BAR; PG8_SCHED;
	s_add_i32 s42, s62, s45
	v_lshl_add_u64 v[144:145], v[144:145], 0, s[18:19]
	s_mov_b32 m0, s42
	ds_read_b128 v[184:187], v151 offset:49152
	ds_read_b128 v[188:191], v151 offset:50176
	ds_read_b128 v[194:197], v151 offset:51200
	ds_read_b128 v[198:201], v151 offset:52224
	ds_read_b128 v[202:205], v151 offset:53248
	ds_read_b128 v[206:209], v151 offset:54272
	ds_read_b128 v[210:213], v151 offset:55296
	ds_read_b128 v[214:217], v151 offset:56320
	global_load_lds_dwordx4 v[144:145], off
	s_add_i32 m0, s42, 0x2000
	s_add_u32 s40, s40, 0x20080
	v_lshl_add_u64 v[144:145], v[218:219], 0, s[18:19]
	s_addc_u32 s41, s41, 0
	s_add_i32 s42, s63, s45
	global_load_lds_dwordx4 v[144:145], off
	s_waitcnt vmcnt(4)
	s_waitcnt lgkmcnt(0)
	s_barrier
	s_setprio 1
	s_waitcnt lgkmcnt(0)
	v_mfma_f32_16x16x32_bf16 v[60:63], v[152:155], v[184:187], v[60:63]
	v_mfma_f32_16x16x32_bf16 v[60:63], v[156:159], v[188:191], v[60:63]
	v_mfma_f32_16x16x32_bf16 v[56:59], v[160:163], v[184:187], v[56:59]
	v_mfma_f32_16x16x32_bf16 v[56:59], v[164:167], v[188:191], v[56:59]
	v_lshl_add_u64 v[144:145], s[40:41], 0, v[132:133]
	s_mov_b32 m0, s42
	s_nop 0
	global_load_lds_dwordx4 v[144:145], off
	v_mfma_f32_16x16x32_bf16 v[52:55], v[152:155], v[194:197], v[52:55]
	v_mfma_f32_16x16x32_bf16 v[52:55], v[156:159], v[198:201], v[52:55]
	v_mfma_f32_16x16x32_bf16 v[44:47], v[160:163], v[194:197], v[44:47]
	v_mfma_f32_16x16x32_bf16 v[44:47], v[164:167], v[198:201], v[44:47]
	v_mfma_f32_16x16x32_bf16 v[36:39], v[152:155], v[202:205], v[36:39]
	v_mfma_f32_16x16x32_bf16 v[36:39], v[156:159], v[206:209], v[36:39]
	v_lshl_add_u64 v[144:145], s[40:41], 0, v[128:129]
	s_add_i32 m0, s42, 0x2000
	s_nop 0
	global_load_lds_dwordx4 v[144:145], off
	v_mfma_f32_16x16x32_bf16 v[28:31], v[160:163], v[202:205], v[28:31]
	v_mfma_f32_16x16x32_bf16 v[28:31], v[164:167], v[206:209], v[28:31]
	v_mfma_f32_16x16x32_bf16 v[20:23], v[152:155], v[210:213], v[20:23]
	v_mfma_f32_16x16x32_bf16 v[20:23], v[156:159], v[214:217], v[20:23]
	v_mfma_f32_16x16x32_bf16 v[12:15], v[160:163], v[210:213], v[12:15]
	v_mfma_f32_16x16x32_bf16 v[12:15], v[164:167], v[214:217], v[12:15]
	s_setprio 0
	s_setprio 1
	v_mfma_f32_16x16x32_bf16 v[48:51], v[168:171], v[184:187], v[48:51]
	v_mfma_f32_16x16x32_bf16 v[48:51], v[172:175], v[188:191], v[48:51]
	v_lshl_add_u64 v[144:145], v[220:221], 0, s[18:19]
	s_mov_b32 m0, s50
	s_nop 0
	global_load_lds_dwordx4 v[144:145], off
	v_mfma_f32_16x16x32_bf16 v[40:43], v[176:179], v[184:187], v[40:43]
	v_mfma_f32_16x16x32_bf16 v[40:43], v[180:183], v[188:191], v[40:43]
	v_mfma_f32_16x16x32_bf16 v[32:35], v[168:171], v[194:197], v[32:35]
	v_mfma_f32_16x16x32_bf16 v[32:35], v[172:175], v[198:201], v[32:35]
	v_mfma_f32_16x16x32_bf16 v[24:27], v[176:179], v[194:197], v[24:27]
	v_mfma_f32_16x16x32_bf16 v[24:27], v[180:183], v[198:201], v[24:27]
	v_lshl_add_u64 v[144:145], v[222:223], 0, s[18:19]
	s_mov_b32 m0, s51
	s_nop 0
	global_load_lds_dwordx4 v[144:145], off
	v_mfma_f32_16x16x32_bf16 v[16:19], v[168:171], v[202:205], v[16:19]
	v_mfma_f32_16x16x32_bf16 v[16:19], v[172:175], v[206:209], v[16:19]
	v_mfma_f32_16x16x32_bf16 v[8:11], v[176:179], v[202:205], v[8:11]
	v_mfma_f32_16x16x32_bf16 v[8:11], v[180:183], v[206:209], v[8:11]
	v_mfma_f32_16x16x32_bf16 v[4:7], v[168:171], v[210:213], v[4:7]
	v_mfma_f32_16x16x32_bf16 v[4:7], v[172:175], v[214:217], v[4:7]
	v_mfma_f32_16x16x32_bf16 v[0:3], v[176:179], v[210:213], v[0:3]
	v_mfma_f32_16x16x32_bf16 v[0:3], v[180:183], v[214:217], v[0:3]
	s_setprio 0
	s_barrier
	s_add_i32 s61, s61, 2
	s_add_u32 s36, s36, 0x100
	s_addc_u32 s37, s37, 0
	s_add_u32 s59, s59, 0x100
	s_addc_u32 s60, s60, 0
	s_cmp_gt_u32 s61, 5
	s_cbranch_scc0 .LBB0_385
	s_and_b64 vcc, exec, s[20:21]
	s_cbranch_vccz .LBB0_388
	s_barrier

; #define PG8_STAGE(bufoff, gbase, voff) do { _Pragma("unroll") for (int _i = 0; _i < 2; ++_i) \
;         __builtin_amdgcn_global_load_lds((const unsigned*)((const char*)(gbase) + (voff)[_i]), (LAS unsigned*)(lds + (bufoff) + ldsw + _i * 8192), 16, 0, 0); } while (0)
; #define PG8_LDA(dst, b, h) do { _Pragma("unroll") for (int m = 0; m < 4; ++m) _Pragma("unroll") for (int k = 0; k < 2; ++k) dst[m][k] = *(const LAS bf16x8*)(lds + PG8_SA(b, h) + aoff + m * 2048 + k * 1024); } while (0)
; #define PG8_LDB(dst, b, h) do { _Pragma("unroll") for (int n = 0; n < 2; ++n) _Pragma("unroll") for (int k = 0; k < 2; ++k) dst[n][k] = *(const LAS bf16x8*)(lds + PG8_SB(b, h) + boff + n * 2048 + k * 1024); } while (0)
; #define PG8_MMA(ai, bj, At, Bt) do { __builtin_amdgcn_s_setprio(1); _Pragma("unroll") for (int m = 0; m < 4; ++m) _Pragma("unroll") for (int n = 0; n < 2; ++n) _Pragma("unroll") for (int k = 0; k < 2; ++k) \
;         acc[ai][bj][m][n] = __builtin_amdgcn_mfma_f32_16x16x32_bf16(Bt[n][k], At[m][k], acc[ai][bj][m][n], 0, 0, 0); __builtin_amdgcn_s_setprio(0); } while (0)
; #define PG8_WAIT_V(n) asm volatile("s_waitcnt vmcnt(" #n ")" ::: "memory")
; #define PG8_WAIT_L(n) asm volatile("s_waitcnt lgkmcnt(" #n ")" ::: "memory")
; #define PG8_BAR __builtin_amdgcn_s_barrier()
; #define PG8_SCHED __builtin_amdgcn_sched_barrier(0)
; template <class Epi, bool ALIGN_EPI>
; __device__ __forceinline__ void gemm_phase(LAS unsigned char* lds, const Gemm g, const StaticOrder& S, const Epi& E) {
;     ...
;             PG8_LDB(B0, 0, 0); PG8_LDB(B1, 0, 1); PG8_SCHED; PG8_LDA(At, 0, 0); PG8_STAGE(PG8_SA(1, 1), a1 + hA, voffA);
;             PG8_WAIT_V(8); PG8_WAIT_L(0); PG8_BAR; PG8_MMA(0, 0, At, B0); PG8_MMA(0, 1, At, B1); PG8_BAR; PG8_SCHED;
;             PG8_LDA(At, 0, 1); PG8_STAGE(PG8_SB(0, 0), b2, voffB); PG8_STAGE(PG8_SB(0, 1), b2 + hB, voffB); PG8_STAGE(PG8_SA(0, 0), a2, voffA);
;             PG8_WAIT_V(8); PG8_WAIT_L(0); PG8_BAR; PG8_MMA(1, 0, At, B0); PG8_MMA(1, 1, At, B1); PG8_BAR; PG8_SCHED;
.LBB0_403:
	ds_read_b128 v[152:155], v149
	ds_read_b128 v[156:159], v149 offset:1024
	ds_read_b128 v[160:163], v149 offset:2048
	ds_read_b128 v[164:167], v149 offset:3072
	ds_read_b128 v[168:171], v150
	ds_read_b128 v[172:175], v150 offset:1024
	ds_read_b128 v[176:179], v150 offset:2048
	ds_read_b128 v[180:183], v150 offset:3072
	s_add_u32 s30, s6, 0xfff80080
	s_addc_u32 s31, s7, -1
	s_cmp_eq_u32 s53, 8
	s_cselect_b32 s35, s23, s31
	s_cselect_b32 s34, s50, s30
	s_cselect_b32 s31, s25, s52
	s_cselect_b32 s30, s24, s51
	v_lshl_add_u64 v[144:145], s[6:7], 0, v[136:137]
	s_add_i32 m0, s0, 0xc000
	ds_read_b128 v[184:187], v151
	ds_read_b128 v[188:191], v151 offset:1024
	ds_read_b128 v[194:197], v151 offset:2048
	ds_read_b128 v[198:201], v151 offset:3072
	ds_read_b128 v[202:205], v151 offset:4096
	ds_read_b128 v[206:209], v151 offset:5120
	ds_read_b128 v[210:213], v151 offset:6144
	ds_read_b128 v[214:217], v151 offset:7168
	global_load_lds_dwordx4 v[144:145], off
	v_lshl_add_u64 v[144:145], s[6:7], 0, v[138:139]
	s_add_i32 m0, s0, 0xe000
	s_nop 0
	global_load_lds_dwordx4 v[144:145], off
	s_waitcnt vmcnt(8)
	s_waitcnt lgkmcnt(0)
	s_barrier
	s_setprio 1
	s_waitcnt lgkmcnt(0)
	v_mfma_f32_16x16x32_bf16 v[124:127], v[152:155], v[184:187], v[124:127]
	v_mfma_f32_16x16x32_bf16 v[124:127], v[156:159], v[188:191], v[124:127]
	v_mfma_f32_16x16x32_bf16 v[120:123], v[160:163], v[184:187], v[120:123]
	v_mfma_f32_16x16x32_bf16 v[120:123], v[164:167], v[188:191], v[120:123]
	v_mfma_f32_16x16x32_bf16 v[116:119], v[152:155], v[194:197], v[116:119]
	v_mfma_f32_16x16x32_bf16 v[116:119], v[156:159], v[198:201], v[116:119]
	v_mfma_f32_16x16x32_bf16 v[108:111], v[160:163], v[194:197], v[108:111]
	v_mfma_f32_16x16x32_bf16 v[108:111], v[164:167], v[198:201], v[108:111]
	v_mfma_f32_16x16x32_bf16 v[100:103], v[152:155], v[202:205], v[100:103]
	v_mfma_f32_16x16x32_bf16 v[100:103], v[156:159], v[206:209], v[100:103]
	v_mfma_f32_16x16x32_bf16 v[92:95], v[160:163], v[202:205], v[92:95]
	v_mfma_f32_16x16x32_bf16 v[92:95], v[164:167], v[206:209], v[92:95]
	v_mfma_f32_16x16x32_bf16 v[84:87], v[152:155], v[210:213], v[84:87]
	v_mfma_f32_16x16x32_bf16 v[84:87], v[156:159], v[214:217], v[84:87]
	v_mfma_f32_16x16x32_bf16 v[76:79], v[160:163], v[210:213], v[76:79]
	v_mfma_f32_16x16x32_bf16 v[76:79], v[164:167], v[214:217], v[76:79]
	s_setprio 0
	s_setprio 1
	v_mfma_f32_16x16x32_bf16 v[112:115], v[168:171], v[184:187], v[112:115]
	v_mfma_f32_16x16x32_bf16 v[112:115], v[172:175], v[188:191], v[112:115]
	v_mfma_f32_16x16x32_bf16 v[104:107], v[176:179], v[184:187], v[104:107]
	v_mfma_f32_16x16x32_bf16 v[104:107], v[180:183], v[188:191], v[104:107]
	v_mfma_f32_16x16x32_bf16 v[96:99], v[168:171], v[194:197], v[96:99]
	v_mfma_f32_16x16x32_bf16 v[96:99], v[172:175], v[198:201], v[96:99]
	v_mfma_f32_16x16x32_bf16 v[88:91], v[176:179], v[194:197], v[88:91]
	v_mfma_f32_16x16x32_bf16 v[88:91], v[180:183], v[198:201], v[88:91]
	v_mfma_f32_16x16x32_bf16 v[80:83], v[168:171], v[202:205], v[80:83]
	v_mfma_f32_16x16x32_bf16 v[80:83], v[172:175], v[206:209], v[80:83]
	v_mfma_f32_16x16x32_bf16 v[72:75], v[176:179], v[202:205], v[72:75]
	v_mfma_f32_16x16x32_bf16 v[72:75], v[180:183], v[206:209], v[72:75]
	v_mfma_f32_16x16x32_bf16 v[68:71], v[168:171], v[210:213], v[68:71]
	v_mfma_f32_16x16x32_bf16 v[68:71], v[172:175], v[214:217], v[68:71]
	v_mfma_f32_16x16x32_bf16 v[64:67], v[176:179], v[210:213], v[64:67]
	v_mfma_f32_16x16x32_bf16 v[64:67], v[180:183], v[214:217], v[64:67]
	s_setprio 0
	s_barrier
	s_add_i32 s54, s45, s2
	v_lshl_add_u64 v[144:145], s[30:31], 0, v[132:133]
	s_mov_b32 m0, s54
	ds_read_b128 v[184:187], v151 offset:16384
	ds_read_b128 v[188:191], v151 offset:17408
	ds_read_b128 v[194:197], v151 offset:18432
	ds_read_b128 v[198:201], v151 offset:19456
	ds_read_b128 v[202:205], v151 offset:20480
	ds_read_b128 v[206:209], v151 offset:21504
	ds_read_b128 v[210:213], v151 offset:22528
	ds_read_b128 v[214:217], v151 offset:23552
	global_load_lds_dwordx4 v[144:145], off
	s_add_i32 m0, s54, 0x2000
	s_add_u32 s54, s30, 0x30000
	v_lshl_add_u64 v[218:219], s[30:31], 0, v[128:129]
	s_addc_u32 s55, s31, 0
	s_add_i32 s56, s46, s2
	global_load_lds_dwordx4 v[218:219], off
	s_waitcnt vmcnt(4)
	s_waitcnt lgkmcnt(0)
	s_barrier
	s_setprio 1
	s_waitcnt lgkmcnt(0)
	v_mfma_f32_16x16x32_bf16 v[60:63], v[152:155], v[184:187], v[60:63]
	v_mfma_f32_16x16x32_bf16 v[60:63], v[156:159], v[188:191], v[60:63]
	v_mfma_f32_16x16x32_bf16 v[56:59], v[160:163], v[184:187], v[56:59]
	v_mfma_f32_16x16x32_bf16 v[56:59], v[164:167], v[188:191], v[56:59]
	v_lshl_add_u64 v[220:221], s[54:55], 0, v[132:133]
	s_mov_b32 m0, s56
	v_lshl_add_u64 v[222:223], s[34:35], 0, v[130:131]
	global_load_lds_dwordx4 v[220:221], off
	v_mfma_f32_16x16x32_bf16 v[52:55], v[152:155], v[194:197], v[52:55]
	v_mfma_f32_16x16x32_bf16 v[52:55], v[156:159], v[198:201], v[52:55]
	v_mfma_f32_16x16x32_bf16 v[44:47], v[160:163], v[194:197], v[44:47]
	v_mfma_f32_16x16x32_bf16 v[44:47], v[164:167], v[198:201], v[44:47]
	v_mfma_f32_16x16x32_bf16 v[36:39], v[152:155], v[202:205], v[36:39]
	v_mfma_f32_16x16x32_bf16 v[36:39], v[156:159], v[206:209], v[36:39]
	v_lshl_add_u64 v[220:221], s[54:55], 0, v[128:129]
	s_add_i32 m0, s56, 0x2000
	s_nop 0
	global_load_lds_dwordx4 v[220:221], off
	v_mfma_f32_16x16x32_bf16 v[28:31], v[160:163], v[202:205], v[28:31]
	v_mfma_f32_16x16x32_bf16 v[28:31], v[164:167], v[206:209], v[28:31]
	v_mfma_f32_16x16x32_bf16 v[20:23], v[152:155], v[210:213], v[20:23]
	v_mfma_f32_16x16x32_bf16 v[20:23], v[156:159], v[214:217], v[20:23]
	v_mfma_f32_16x16x32_bf16 v[12:15], v[160:163], v[210:213], v[12:15]
	v_mfma_f32_16x16x32_bf16 v[12:15], v[164:167], v[214:217], v[12:15]
	s_setprio 0
	s_setprio 1
	v_mfma_f32_16x16x32_bf16 v[48:51], v[168:171], v[184:187], v[48:51]
	v_mfma_f32_16x16x32_bf16 v[48:51], v[172:175], v[188:191], v[48:51]
	v_lshl_add_u64 v[220:221], s[34:35], 0, v[134:135]
	s_mov_b32 m0, s0
	s_nop 0
	global_load_lds_dwordx4 v[220:221], off
	v_mfma_f32_16x16x32_bf16 v[40:43], v[176:179], v[184:187], v[40:43]
	v_mfma_f32_16x16x32_bf16 v[40:43], v[180:183], v[188:191], v[40:43]
	v_mfma_f32_16x16x32_bf16 v[32:35], v[168:171], v[194:197], v[32:35]
	v_mfma_f32_16x16x32_bf16 v[32:35], v[172:175], v[198:201], v[32:35]
	v_mfma_f32_16x16x32_bf16 v[24:27], v[176:179], v[194:197], v[24:27]
	v_mfma_f32_16x16x32_bf16 v[24:27], v[180:183], v[198:201], v[24:27]
	s_mov_b32 m0, s1
	s_nop 0
	global_load_lds_dwordx4 v[222:223], off
	v_mfma_f32_16x16x32_bf16 v[16:19], v[168:171], v[202:205], v[16:19]
	v_mfma_f32_16x16x32_bf16 v[16:19], v[172:175], v[206:209], v[16:19]
	v_mfma_f32_16x16x32_bf16 v[8:11], v[176:179], v[202:205], v[8:11]
	v_mfma_f32_16x16x32_bf16 v[8:11], v[180:183], v[206:209], v[8:11]
	v_mfma_f32_16x16x32_bf16 v[4:7], v[168:171], v[210:213], v[4:7]
	v_mfma_f32_16x16x32_bf16 v[4:7], v[172:175], v[214:217], v[4:7]
	v_mfma_f32_16x16x32_bf16 v[0:3], v[176:179], v[210:213], v[0:3]
	v_mfma_f32_16x16x32_bf16 v[0:3], v[180:183], v[214:217], v[0:3]
	s_setprio 0
	s_barrier
; #define PG8_STAGE(bufoff, gbase, voff) do { _Pragma("unroll") for (int _i = 0; _i < 2; ++_i) \
;         __builtin_amdgcn_global_load_lds((const unsigned*)((const char*)(gbase) + (voff)[_i]), (LAS unsigned*)(lds + (bufoff) + ldsw + _i * 8192), 16, 0, 0); } while (0)
; #define PG8_LDA(dst, b, h) do { _Pragma("unroll") for (int m = 0; m < 4; ++m) _Pragma("unroll") for (int k = 0; k < 2; ++k) dst[m][k] = *(const LAS bf16x8*)(lds + PG8_SA(b, h) + aoff + m * 2048 + k * 1024); } while (0)
; #define PG8_LDB(dst, b, h) do { _Pragma("unroll") for (int n = 0; n < 2; ++n) _Pragma("unroll") for (int k = 0; k < 2; ++k) dst[n][k] = *(const LAS bf16x8*)(lds + PG8_SB(b, h) + boff + n * 2048 + k * 1024); } while (0)
; #define PG8_MMA(ai, bj, At, Bt) do { __builtin_amdgcn_s_setprio(1); _Pragma("unroll") for (int m = 0; m < 4; ++m) _Pragma("unroll") for (int n = 0; n < 2; ++n) _Pragma("unroll") for (int k = 0; k < 2; ++k) \
;         acc[ai][bj][m][n] = __builtin_amdgcn_mfma_f32_16x16x32_bf16(Bt[n][k], At[m][k], acc[ai][bj][m][n], 0, 0, 0); __builtin_amdgcn_s_setprio(0); } while (0)
; #define PG8_WAIT_V(n) asm volatile("s_waitcnt vmcnt(" #n ")" ::: "memory")
; #define PG8_WAIT_L(n) asm volatile("s_waitcnt lgkmcnt(" #n ")" ::: "memory")
; #define PG8_BAR __builtin_amdgcn_s_barrier()
; #define PG8_SCHED __builtin_amdgcn_sched_barrier(0)
; template <class Epi, bool ALIGN_EPI>
; __device__ __forceinline__ void gemm_phase(LAS unsigned char* lds, const Gemm g, const StaticOrder& S, const Epi& E) {
;     ...
;             PG8_LDB(B0, 1, 0); PG8_LDB(B1, 1, 1); PG8_SCHED; PG8_LDA(At, 1, 0); PG8_STAGE(PG8_SA(0, 1), a2 + hA, voffA);
;             PG8_WAIT_V(8); PG8_WAIT_L(0); PG8_BAR; PG8_MMA(0, 0, At, B0); PG8_MMA(0, 1, At, B1); PG8_BAR; PG8_SCHED;
	s_add_i32 s54, 0, 0x18000
	s_add_i32 s55, 0, 0x1c000
	v_add_u32_e32 v164, s54, v147
	v_add_u32_e32 v180, s55, v147
	ds_read_b128 v[152:155], v164
	ds_read_b128 v[156:159], v164 offset:1024
	ds_read_b128 v[160:163], v164 offset:2048
	ds_read_b128 v[164:167], v164 offset:3072
	ds_read_b128 v[168:171], v180
	ds_read_b128 v[172:175], v180 offset:1024
	ds_read_b128 v[176:179], v180 offset:2048
	ds_read_b128 v[180:183], v180 offset:3072
	s_add_u32 s34, s34, 0x80000
	s_addc_u32 s35, s35, 0
	s_mov_b32 m0, s29
	v_lshl_add_u64 v[224:225], s[34:35], 0, v[134:135]
	ds_read_b128 v[184:187], v151 offset:32768
	ds_read_b128 v[188:191], v151 offset:33792
	ds_read_b128 v[194:197], v151 offset:34816
	ds_read_b128 v[198:201], v151 offset:35840
	ds_read_b128 v[202:205], v151 offset:36864
	ds_read_b128 v[206:209], v151 offset:37888
	ds_read_b128 v[210:213], v151 offset:38912
	ds_read_b128 v[214:217], v151 offset:39936
	global_load_lds_dwordx4 v[224:225], off
	v_lshl_add_u64 v[224:225], s[34:35], 0, v[130:131]
	s_mov_b32 m0, s40
	s_nop 0
	global_load_lds_dwordx4 v[224:225], off
	s_waitcnt vmcnt(8)
	s_waitcnt lgkmcnt(0)
	s_barrier
	s_setprio 1
	s_waitcnt lgkmcnt(0)
	v_mfma_f32_16x16x32_bf16 v[124:127], v[152:155], v[184:187], v[124:127]
	v_mfma_f32_16x16x32_bf16 v[124:127], v[156:159], v[188:191], v[124:127]
	v_mfma_f32_16x16x32_bf16 v[120:123], v[160:163], v[184:187], v[120:123]
	v_mfma_f32_16x16x32_bf16 v[120:123], v[164:167], v[188:191], v[120:123]
	v_mfma_f32_16x16x32_bf16 v[116:119], v[152:155], v[194:197], v[116:119]
	v_mfma_f32_16x16x32_bf16 v[116:119], v[156:159], v[198:201], v[116:119]
	v_mfma_f32_16x16x32_bf16 v[108:111], v[160:163], v[194:197], v[108:111]
	v_mfma_f32_16x16x32_bf16 v[108:111], v[164:167], v[198:201], v[108:111]
	v_mfma_f32_16x16x32_bf16 v[100:103], v[152:155], v[202:205], v[100:103]
	v_mfma_f32_16x16x32_bf16 v[100:103], v[156:159], v[206:209], v[100:103]
	v_mfma_f32_16x16x32_bf16 v[92:95], v[160:163], v[202:205], v[92:95]
	v_mfma_f32_16x16x32_bf16 v[92:95], v[164:167], v[206:209], v[92:95]
	v_mfma_f32_16x16x32_bf16 v[84:87], v[152:155], v[210:213], v[84:87]
	v_mfma_f32_16x16x32_bf16 v[84:87], v[156:159], v[214:217], v[84:87]
	v_mfma_f32_16x16x32_bf16 v[76:79], v[160:163], v[210:213], v[76:79]
	v_mfma_f32_16x16x32_bf16 v[76:79], v[164:167], v[214:217], v[76:79]
	s_setprio 0
	s_setprio 1
	v_mfma_f32_16x16x32_bf16 v[112:115], v[168:171], v[184:187], v[112:115]
	v_mfma_f32_16x16x32_bf16 v[112:115], v[172:175], v[188:191], v[112:115]
	v_mfma_f32_16x16x32_bf16 v[104:107], v[176:179], v[184:187], v[104:107]
	v_mfma_f32_16x16x32_bf16 v[104:107], v[180:183], v[188:191], v[104:107]
	v_mfma_f32_16x16x32_bf16 v[96:99], v[168:171], v[194:197], v[96:99]
	v_mfma_f32_16x16x32_bf16 v[96:99], v[172:175], v[198:201], v[96:99]
	v_mfma_f32_16x16x32_bf16 v[88:91], v[176:179], v[194:197], v[88:91]
	v_mfma_f32_16x16x32_bf16 v[88:91], v[180:183], v[198:201], v[88:91]
	v_mfma_f32_16x16x32_bf16 v[80:83], v[168:171], v[202:205], v[80:83]
	v_mfma_f32_16x16x32_bf16 v[80:83], v[172:175], v[206:209], v[80:83]
	v_mfma_f32_16x16x32_bf16 v[72:75], v[176:179], v[202:205], v[72:75]
	v_mfma_f32_16x16x32_bf16 v[72:75], v[180:183], v[206:209], v[72:75]
	v_mfma_f32_16x16x32_bf16 v[68:71], v[168:171], v[210:213], v[68:71]
	v_mfma_f32_16x16x32_bf16 v[68:71], v[172:175], v[214:217], v[68:71]
	v_mfma_f32_16x16x32_bf16 v[64:67], v[176:179], v[210:213], v[64:67]
	v_mfma_f32_16x16x32_bf16 v[64:67], v[180:183], v[214:217], v[64:67]
	s_setprio 0
	s_barrier
; #define PG8_STAGE(bufoff, gbase, voff) do { _Pragma("unroll") for (int _i = 0; _i < 2; ++_i) \
;         __builtin_amdgcn_global_load_lds((const unsigned*)((const char*)(gbase) + (voff)[_i]), (LAS unsigned*)(lds + (bufoff) + ldsw + _i * 8192), 16, 0, 0); } while (0)
; #define PG8_LDA(dst, b, h) do { _Pragma("unroll") for (int m = 0; m < 4; ++m) _Pragma("unroll") for (int k = 0; k < 2; ++k) dst[m][k] = *(const LAS bf16x8*)(lds + PG8_SA(b, h) + aoff + m * 2048 + k * 1024); } while (0)
; #define PG8_MMA(ai, bj, At, Bt) do { __builtin_amdgcn_s_setprio(1); _Pragma("unroll") for (int m = 0; m < 4; ++m) _Pragma("unroll") for (int n = 0; n < 2; ++n) _Pragma("unroll") for (int k = 0; k < 2; ++k) \
;         acc[ai][bj][m][n] = __builtin_amdgcn_mfma_f32_16x16x32_bf16(Bt[n][k], At[m][k], acc[ai][bj][m][n], 0, 0, 0); __builtin_amdgcn_s_setprio(0); } while (0)
; #define PG8_WAIT_V(n) asm volatile("s_waitcnt vmcnt(" #n ")" ::: "memory")
; #define PG8_WAIT_L(n) asm volatile("s_waitcnt lgkmcnt(" #n ")" ::: "memory")
; #define PG8_BAR __builtin_amdgcn_s_barrier()
; #define PG8_SCHED __builtin_amdgcn_sched_barrier(0)
; template <class Epi, bool ALIGN_EPI>
; __device__ __forceinline__ void gemm_phase(LAS unsigned char* lds, const Gemm g, const StaticOrder& S, const Epi& E) {
;     ...
;         for (int t = 0; t < nt; t += 2) {
;     ...
;             PG8_LDA(At, 1, 1); PG8_STAGE(PG8_SB(1, 0), b3, voffB); PG8_STAGE(PG8_SB(1, 1), b3 + hB, voffB); PG8_STAGE(PG8_SA(1, 0), a3, voffA);
;             PG8_WAIT_V(8); PG8_WAIT_L(0); PG8_BAR; PG8_MMA(1, 0, At, B0); PG8_MMA(1, 1, At, B1); PG8_BAR; PG8_SCHED;
	s_add_i32 s34, s54, s2
	v_lshl_add_u64 v[144:145], v[144:145], 0, s[16:17]
	s_mov_b32 m0, s34
	ds_read_b128 v[184:187], v151 offset:49152
	ds_read_b128 v[188:191], v151 offset:50176
	ds_read_b128 v[194:197], v151 offset:51200
	ds_read_b128 v[198:201], v151 offset:52224
	ds_read_b128 v[202:205], v151 offset:53248
	ds_read_b128 v[206:209], v151 offset:54272
	ds_read_b128 v[210:213], v151 offset:55296
	ds_read_b128 v[214:217], v151 offset:56320
	global_load_lds_dwordx4 v[144:145], off
	s_add_i32 m0, s34, 0x2000
	s_add_u32 s30, s30, 0x30080
	v_lshl_add_u64 v[144:145], v[218:219], 0, s[16:17]
	s_addc_u32 s31, s31, 0
	s_add_i32 s34, s55, s2
	global_load_lds_dwordx4 v[144:145], off
	s_waitcnt vmcnt(4)
	s_waitcnt lgkmcnt(0)
	s_barrier
	s_setprio 1
	s_waitcnt lgkmcnt(0)
	v_mfma_f32_16x16x32_bf16 v[60:63], v[152:155], v[184:187], v[60:63]
	v_mfma_f32_16x16x32_bf16 v[60:63], v[156:159], v[188:191], v[60:63]
	v_mfma_f32_16x16x32_bf16 v[56:59], v[160:163], v[184:187], v[56:59]
	v_mfma_f32_16x16x32_bf16 v[56:59], v[164:167], v[188:191], v[56:59]
	v_lshl_add_u64 v[144:145], s[30:31], 0, v[132:133]
	s_mov_b32 m0, s34
	s_nop 0
	global_load_lds_dwordx4 v[144:145], off
	v_mfma_f32_16x16x32_bf16 v[52:55], v[152:155], v[194:197], v[52:55]
	v_mfma_f32_16x16x32_bf16 v[52:55], v[156:159], v[198:201], v[52:55]
	v_mfma_f32_16x16x32_bf16 v[44:47], v[160:163], v[194:197], v[44:47]
	v_mfma_f32_16x16x32_bf16 v[44:47], v[164:167], v[198:201], v[44:47]
	v_mfma_f32_16x16x32_bf16 v[36:39], v[152:155], v[202:205], v[36:39]
	v_mfma_f32_16x16x32_bf16 v[36:39], v[156:159], v[206:209], v[36:39]
	v_lshl_add_u64 v[144:145], s[30:31], 0, v[128:129]
	s_add_i32 m0, s34, 0x2000
	s_nop 0
	global_load_lds_dwordx4 v[144:145], off
	v_mfma_f32_16x16x32_bf16 v[28:31], v[160:163], v[202:205], v[28:31]
	v_mfma_f32_16x16x32_bf16 v[28:31], v[164:167], v[206:209], v[28:31]
	v_mfma_f32_16x16x32_bf16 v[20:23], v[152:155], v[210:213], v[20:23]
	v_mfma_f32_16x16x32_bf16 v[20:23], v[156:159], v[214:217], v[20:23]
	v_mfma_f32_16x16x32_bf16 v[12:15], v[160:163], v[210:213], v[12:15]
	v_mfma_f32_16x16x32_bf16 v[12:15], v[164:167], v[214:217], v[12:15]
	s_setprio 0
	s_setprio 1
	v_mfma_f32_16x16x32_bf16 v[48:51], v[168:171], v[184:187], v[48:51]
	v_mfma_f32_16x16x32_bf16 v[48:51], v[172:175], v[188:191], v[48:51]
	v_lshl_add_u64 v[144:145], v[220:221], 0, s[16:17]
	s_mov_b32 m0, s42
	s_nop 0
	global_load_lds_dwordx4 v[144:145], off
	v_mfma_f32_16x16x32_bf16 v[40:43], v[176:179], v[184:187], v[40:43]
	v_mfma_f32_16x16x32_bf16 v[40:43], v[180:183], v[188:191], v[40:43]
	v_mfma_f32_16x16x32_bf16 v[32:35], v[168:171], v[194:197], v[32:35]
	v_mfma_f32_16x16x32_bf16 v[32:35], v[172:175], v[198:201], v[32:35]
	v_mfma_f32_16x16x32_bf16 v[24:27], v[176:179], v[194:197], v[24:27]
	v_mfma_f32_16x16x32_bf16 v[24:27], v[180:183], v[198:201], v[24:27]
	v_lshl_add_u64 v[144:145], v[222:223], 0, s[16:17]
	s_mov_b32 m0, s43
	s_nop 0
	global_load_lds_dwordx4 v[144:145], off
	v_mfma_f32_16x16x32_bf16 v[16:19], v[168:171], v[202:205], v[16:19]
	v_mfma_f32_16x16x32_bf16 v[16:19], v[172:175], v[206:209], v[16:19]
	v_mfma_f32_16x16x32_bf16 v[8:11], v[176:179], v[202:205], v[8:11]
	v_mfma_f32_16x16x32_bf16 v[8:11], v[180:183], v[206:209], v[8:11]
	v_mfma_f32_16x16x32_bf16 v[4:7], v[168:171], v[210:213], v[4:7]
	v_mfma_f32_16x16x32_bf16 v[4:7], v[172:175], v[214:217], v[4:7]
	v_mfma_f32_16x16x32_bf16 v[0:3], v[176:179], v[210:213], v[0:3]
	v_mfma_f32_16x16x32_bf16 v[0:3], v[180:183], v[214:217], v[0:3]
	s_setprio 0
	s_barrier
	s_add_i32 s53, s53, 2
	s_add_u32 s6, s6, 0x100
	s_addc_u32 s7, s7, 0
	s_add_u32 s51, s51, 0x100
	s_addc_u32 s52, s52, 0
	s_cmp_gt_u32 s53, 9
	s_cbranch_scc0 .LBB0_403
	s_and_b64 vcc, exec, s[18:19]
	s_cbranch_vccz .LBB0_406
	s_barrier

; #define PG8_STAGE(bufoff, gbase, voff) do { _Pragma("unroll") for (int _i = 0; _i < 2; ++_i) \
;         __builtin_amdgcn_global_load_lds((const unsigned*)((const char*)(gbase) + (voff)[_i]), (LAS unsigned*)(lds + (bufoff) + ldsw + _i * 8192), 16, 0, 0); } while (0)
; #define PG8_LDA(dst, b, h) do { _Pragma("unroll") for (int m = 0; m < 4; ++m) _Pragma("unroll") for (int k = 0; k < 2; ++k) dst[m][k] = *(const LAS bf16x8*)(lds + PG8_SA(b, h) + aoff + m * 2048 + k * 1024); } while (0)
; #define PG8_LDB(dst, b, h) do { _Pragma("unroll") for (int n = 0; n < 2; ++n) _Pragma("unroll") for (int k = 0; k < 2; ++k) dst[n][k] = *(const LAS bf16x8*)(lds + PG8_SB(b, h) + boff + n * 2048 + k * 1024); } while (0)
; #define PG8_MMA(ai, bj, At, Bt) do { __builtin_amdgcn_s_setprio(1); _Pragma("unroll") for (int m = 0; m < 4; ++m) _Pragma("unroll") for (int n = 0; n < 2; ++n) _Pragma("unroll") for (int k = 0; k < 2; ++k) \
;         acc[ai][bj][m][n] = __builtin_amdgcn_mfma_f32_16x16x32_bf16(Bt[n][k], At[m][k], acc[ai][bj][m][n], 0, 0, 0); __builtin_amdgcn_s_setprio(0); } while (0)
; #define PG8_WAIT_V(n) asm volatile("s_waitcnt vmcnt(" #n ")" ::: "memory")
; #define PG8_WAIT_L(n) asm volatile("s_waitcnt lgkmcnt(" #n ")" ::: "memory")
; #define PG8_BAR __builtin_amdgcn_s_barrier()
; #define PG8_SCHED __builtin_amdgcn_sched_barrier(0)
; template <class Epi, bool ALIGN_EPI>
; __device__ __forceinline__ void gemm_phase(LAS unsigned char* lds, const Gemm g, const StaticOrder& S, const Epi& E) {
;     ...
;             PG8_LDB(B0, 0, 0); PG8_LDB(B1, 0, 1); PG8_SCHED; PG8_LDA(At, 0, 0); PG8_STAGE(PG8_SA(1, 1), a1 + hA, voffA);
;             PG8_WAIT_V(8); PG8_WAIT_L(0); PG8_BAR; PG8_MMA(0, 0, At, B0); PG8_MMA(0, 1, At, B1); PG8_BAR; PG8_SCHED;
;             PG8_LDA(At, 0, 1); PG8_STAGE(PG8_SB(0, 0), b2, voffB); PG8_STAGE(PG8_SB(0, 1), b2 + hB, voffB); PG8_STAGE(PG8_SA(0, 0), a2, voffA);
;             PG8_WAIT_V(8); PG8_WAIT_L(0); PG8_BAR; PG8_MMA(1, 0, At, B0); PG8_MMA(1, 1, At, B1); PG8_BAR; PG8_SCHED;
.LBB0_419:
	ds_read_b128 v[148:151], v145
	ds_read_b128 v[152:155], v145 offset:1024
	ds_read_b128 v[156:159], v145 offset:2048
	ds_read_b128 v[160:163], v145 offset:3072
	ds_read_b128 v[164:167], v146
	ds_read_b128 v[168:171], v146 offset:1024
	ds_read_b128 v[172:175], v146 offset:2048
	ds_read_b128 v[176:179], v146 offset:3072
	s_add_u32 s30, s28, 0xfff80080
	s_addc_u32 s31, s29, -1
	s_cmp_eq_u32 s53, 28
	s_cselect_b32 s35, s19, s31
	s_cselect_b32 s34, s49, s30
	s_cselect_b32 s31, s17, s52
	s_cselect_b32 s30, s50, s51
	v_lshl_add_u64 v[140:141], s[28:29], 0, v[136:137]
	s_add_i32 m0, s27, 0xc000
	ds_read_b128 v[180:183], v147
	ds_read_b128 v[184:187], v147 offset:1024
	ds_read_b128 v[188:191], v147 offset:2048
	ds_read_b128 v[194:197], v147 offset:3072
	ds_read_b128 v[198:201], v147 offset:4096
	ds_read_b128 v[202:205], v147 offset:5120
	ds_read_b128 v[206:209], v147 offset:6144
	ds_read_b128 v[210:213], v147 offset:7168
	global_load_lds_dwordx4 v[140:141], off
	v_lshl_add_u64 v[140:141], s[28:29], 0, v[138:139]
	s_add_i32 m0, s27, 0xe000
	s_nop 0
	global_load_lds_dwordx4 v[140:141], off
	s_waitcnt vmcnt(8)
	s_waitcnt lgkmcnt(0)
	s_barrier
	s_setprio 1
	s_waitcnt lgkmcnt(0)
	v_mfma_f32_16x16x32_bf16 v[124:127], v[148:151], v[180:183], v[124:127]
	v_mfma_f32_16x16x32_bf16 v[124:127], v[152:155], v[184:187], v[124:127]
	v_mfma_f32_16x16x32_bf16 v[120:123], v[156:159], v[180:183], v[120:123]
	v_mfma_f32_16x16x32_bf16 v[120:123], v[160:163], v[184:187], v[120:123]
	v_mfma_f32_16x16x32_bf16 v[116:119], v[148:151], v[188:191], v[116:119]
	v_mfma_f32_16x16x32_bf16 v[116:119], v[152:155], v[194:197], v[116:119]
	v_mfma_f32_16x16x32_bf16 v[108:111], v[156:159], v[188:191], v[108:111]
	v_mfma_f32_16x16x32_bf16 v[108:111], v[160:163], v[194:197], v[108:111]
	v_mfma_f32_16x16x32_bf16 v[100:103], v[148:151], v[198:201], v[100:103]
	v_mfma_f32_16x16x32_bf16 v[100:103], v[152:155], v[202:205], v[100:103]
	v_mfma_f32_16x16x32_bf16 v[92:95], v[156:159], v[198:201], v[92:95]
	v_mfma_f32_16x16x32_bf16 v[92:95], v[160:163], v[202:205], v[92:95]
	v_mfma_f32_16x16x32_bf16 v[84:87], v[148:151], v[206:209], v[84:87]
	v_mfma_f32_16x16x32_bf16 v[84:87], v[152:155], v[210:213], v[84:87]
	v_mfma_f32_16x16x32_bf16 v[76:79], v[156:159], v[206:209], v[76:79]
	v_mfma_f32_16x16x32_bf16 v[76:79], v[160:163], v[210:213], v[76:79]
	s_setprio 0
	s_setprio 1
	v_mfma_f32_16x16x32_bf16 v[112:115], v[164:167], v[180:183], v[112:115]
	v_mfma_f32_16x16x32_bf16 v[112:115], v[168:171], v[184:187], v[112:115]
	v_mfma_f32_16x16x32_bf16 v[104:107], v[172:175], v[180:183], v[104:107]
	v_mfma_f32_16x16x32_bf16 v[104:107], v[176:179], v[184:187], v[104:107]
	v_mfma_f32_16x16x32_bf16 v[96:99], v[164:167], v[188:191], v[96:99]
	v_mfma_f32_16x16x32_bf16 v[96:99], v[168:171], v[194:197], v[96:99]
	v_mfma_f32_16x16x32_bf16 v[88:91], v[172:175], v[188:191], v[88:91]
	v_mfma_f32_16x16x32_bf16 v[88:91], v[176:179], v[194:197], v[88:91]
	v_mfma_f32_16x16x32_bf16 v[80:83], v[164:167], v[198:201], v[80:83]
	v_mfma_f32_16x16x32_bf16 v[80:83], v[168:171], v[202:205], v[80:83]
	v_mfma_f32_16x16x32_bf16 v[72:75], v[172:175], v[198:201], v[72:75]
	v_mfma_f32_16x16x32_bf16 v[72:75], v[176:179], v[202:205], v[72:75]
	v_mfma_f32_16x16x32_bf16 v[68:71], v[164:167], v[206:209], v[68:71]
	v_mfma_f32_16x16x32_bf16 v[68:71], v[168:171], v[210:213], v[68:71]
	v_mfma_f32_16x16x32_bf16 v[64:67], v[172:175], v[206:209], v[64:67]
	v_mfma_f32_16x16x32_bf16 v[64:67], v[176:179], v[210:213], v[64:67]
	s_setprio 0
	s_barrier
	s_add_i32 s54, s45, s1
	v_lshl_add_u64 v[140:141], s[30:31], 0, v[132:133]
	s_mov_b32 m0, s54
	ds_read_b128 v[180:183], v147 offset:16384
	ds_read_b128 v[184:187], v147 offset:17408
	ds_read_b128 v[188:191], v147 offset:18432
	ds_read_b128 v[194:197], v147 offset:19456
	ds_read_b128 v[198:201], v147 offset:20480
	ds_read_b128 v[202:205], v147 offset:21504
	ds_read_b128 v[206:209], v147 offset:22528
	ds_read_b128 v[210:213], v147 offset:23552
	global_load_lds_dwordx4 v[140:141], off
	s_add_i32 m0, s54, 0x2000
	s_add_u32 s54, s30, 0x80000
	v_lshl_add_u64 v[214:215], s[30:31], 0, v[128:129]
	s_addc_u32 s55, s31, 0
	s_add_i32 s56, s46, s1
	global_load_lds_dwordx4 v[214:215], off
	s_waitcnt vmcnt(4)
	s_waitcnt lgkmcnt(0)
	s_barrier
	s_setprio 1
	s_waitcnt lgkmcnt(0)
	v_mfma_f32_16x16x32_bf16 v[60:63], v[148:151], v[180:183], v[60:63]
	v_mfma_f32_16x16x32_bf16 v[60:63], v[152:155], v[184:187], v[60:63]
	v_mfma_f32_16x16x32_bf16 v[56:59], v[156:159], v[180:183], v[56:59]
	v_mfma_f32_16x16x32_bf16 v[56:59], v[160:163], v[184:187], v[56:59]
	v_lshl_add_u64 v[216:217], s[54:55], 0, v[132:133]
	s_mov_b32 m0, s56
	v_lshl_add_u64 v[218:219], s[34:35], 0, v[130:131]
	global_load_lds_dwordx4 v[216:217], off
	v_mfma_f32_16x16x32_bf16 v[52:55], v[148:151], v[188:191], v[52:55]
	v_mfma_f32_16x16x32_bf16 v[52:55], v[152:155], v[194:197], v[52:55]
	v_mfma_f32_16x16x32_bf16 v[44:47], v[156:159], v[188:191], v[44:47]
	v_mfma_f32_16x16x32_bf16 v[44:47], v[160:163], v[194:197], v[44:47]
	v_mfma_f32_16x16x32_bf16 v[36:39], v[148:151], v[198:201], v[36:39]
	v_mfma_f32_16x16x32_bf16 v[36:39], v[152:155], v[202:205], v[36:39]
	v_lshl_add_u64 v[216:217], s[54:55], 0, v[128:129]
	s_add_i32 m0, s56, 0x2000
	s_nop 0
	global_load_lds_dwordx4 v[216:217], off
	v_mfma_f32_16x16x32_bf16 v[28:31], v[156:159], v[198:201], v[28:31]
	v_mfma_f32_16x16x32_bf16 v[28:31], v[160:163], v[202:205], v[28:31]
	v_mfma_f32_16x16x32_bf16 v[20:23], v[148:151], v[206:209], v[20:23]
	v_mfma_f32_16x16x32_bf16 v[20:23], v[152:155], v[210:213], v[20:23]
	v_mfma_f32_16x16x32_bf16 v[12:15], v[156:159], v[206:209], v[12:15]
	v_mfma_f32_16x16x32_bf16 v[12:15], v[160:163], v[210:213], v[12:15]
	s_setprio 0
	s_setprio 1
	v_mfma_f32_16x16x32_bf16 v[48:51], v[164:167], v[180:183], v[48:51]
	v_mfma_f32_16x16x32_bf16 v[48:51], v[168:171], v[184:187], v[48:51]
	v_lshl_add_u64 v[216:217], s[34:35], 0, v[134:135]
	s_mov_b32 m0, s27
	s_nop 0
	global_load_lds_dwordx4 v[216:217], off
	v_mfma_f32_16x16x32_bf16 v[40:43], v[172:175], v[180:183], v[40:43]
	v_mfma_f32_16x16x32_bf16 v[40:43], v[176:179], v[184:187], v[40:43]
	v_mfma_f32_16x16x32_bf16 v[32:35], v[164:167], v[188:191], v[32:35]
	v_mfma_f32_16x16x32_bf16 v[32:35], v[168:171], v[194:197], v[32:35]
	v_mfma_f32_16x16x32_bf16 v[24:27], v[172:175], v[188:191], v[24:27]
	v_mfma_f32_16x16x32_bf16 v[24:27], v[176:179], v[194:197], v[24:27]
	s_mov_b32 m0, s39
	s_nop 0
	global_load_lds_dwordx4 v[218:219], off
	v_mfma_f32_16x16x32_bf16 v[16:19], v[164:167], v[198:201], v[16:19]
	v_mfma_f32_16x16x32_bf16 v[16:19], v[168:171], v[202:205], v[16:19]
	v_mfma_f32_16x16x32_bf16 v[8:11], v[172:175], v[198:201], v[8:11]
	v_mfma_f32_16x16x32_bf16 v[8:11], v[176:179], v[202:205], v[8:11]
	v_mfma_f32_16x16x32_bf16 v[4:7], v[164:167], v[206:209], v[4:7]
	v_mfma_f32_16x16x32_bf16 v[4:7], v[168:171], v[210:213], v[4:7]
	v_mfma_f32_16x16x32_bf16 v[0:3], v[172:175], v[206:209], v[0:3]
	v_mfma_f32_16x16x32_bf16 v[0:3], v[176:179], v[210:213], v[0:3]
	s_setprio 0
	s_barrier
; #define PG8_STAGE(bufoff, gbase, voff) do { _Pragma("unroll") for (int _i = 0; _i < 2; ++_i) \
;         __builtin_amdgcn_global_load_lds((const unsigned*)((const char*)(gbase) + (voff)[_i]), (LAS unsigned*)(lds + (bufoff) + ldsw + _i * 8192), 16, 0, 0); } while (0)
; #define PG8_LDA(dst, b, h) do { _Pragma("unroll") for (int m = 0; m < 4; ++m) _Pragma("unroll") for (int k = 0; k < 2; ++k) dst[m][k] = *(const LAS bf16x8*)(lds + PG8_SA(b, h) + aoff + m * 2048 + k * 1024); } while (0)
; #define PG8_LDB(dst, b, h) do { _Pragma("unroll") for (int n = 0; n < 2; ++n) _Pragma("unroll") for (int k = 0; k < 2; ++k) dst[n][k] = *(const LAS bf16x8*)(lds + PG8_SB(b, h) + boff + n * 2048 + k * 1024); } while (0)
; #define PG8_MMA(ai, bj, At, Bt) do { __builtin_amdgcn_s_setprio(1); _Pragma("unroll") for (int m = 0; m < 4; ++m) _Pragma("unroll") for (int n = 0; n < 2; ++n) _Pragma("unroll") for (int k = 0; k < 2; ++k) \
;         acc[ai][bj][m][n] = __builtin_amdgcn_mfma_f32_16x16x32_bf16(Bt[n][k], At[m][k], acc[ai][bj][m][n], 0, 0, 0); __builtin_amdgcn_s_setprio(0); } while (0)
; #define PG8_WAIT_V(n) asm volatile("s_waitcnt vmcnt(" #n ")" ::: "memory")
; #define PG8_WAIT_L(n) asm volatile("s_waitcnt lgkmcnt(" #n ")" ::: "memory")
; #define PG8_BAR __builtin_amdgcn_s_barrier()
; #define PG8_SCHED __builtin_amdgcn_sched_barrier(0)
; template <class Epi, bool ALIGN_EPI>
; __device__ __forceinline__ void gemm_phase(LAS unsigned char* lds, const Gemm g, const StaticOrder& S, const Epi& E) {
;     ...
;             PG8_LDB(B0, 1, 0); PG8_LDB(B1, 1, 1); PG8_SCHED; PG8_LDA(At, 1, 0); PG8_STAGE(PG8_SA(0, 1), a2 + hA, voffA);
;             PG8_WAIT_V(8); PG8_WAIT_L(0); PG8_BAR; PG8_MMA(0, 0, At, B0); PG8_MMA(0, 1, At, B1); PG8_BAR; PG8_SCHED;
	s_add_i32 s54, 0, 0x18000
	s_add_i32 s55, 0, 0x1c000
	v_add_u32_e32 v160, s54, v143
	v_add_u32_e32 v176, s55, v143
	ds_read_b128 v[148:151], v160
	ds_read_b128 v[152:155], v160 offset:1024
	ds_read_b128 v[156:159], v160 offset:2048
	ds_read_b128 v[160:163], v160 offset:3072
	ds_read_b128 v[164:167], v176
	ds_read_b128 v[168:171], v176 offset:1024
	ds_read_b128 v[172:175], v176 offset:2048
	ds_read_b128 v[176:179], v176 offset:3072
	s_add_u32 s34, s34, 0x80000
	s_addc_u32 s35, s35, 0
	s_mov_b32 m0, s40
	v_lshl_add_u64 v[220:221], s[34:35], 0, v[134:135]
	ds_read_b128 v[180:183], v147 offset:32768
	ds_read_b128 v[184:187], v147 offset:33792
	ds_read_b128 v[188:191], v147 offset:34816
	ds_read_b128 v[194:197], v147 offset:35840
	ds_read_b128 v[198:201], v147 offset:36864
	ds_read_b128 v[202:205], v147 offset:37888
	ds_read_b128 v[206:209], v147 offset:38912
	ds_read_b128 v[210:213], v147 offset:39936
	global_load_lds_dwordx4 v[220:221], off
	v_lshl_add_u64 v[220:221], s[34:35], 0, v[130:131]
	s_mov_b32 m0, s41
	s_nop 0
	global_load_lds_dwordx4 v[220:221], off
	s_waitcnt vmcnt(8)
	s_waitcnt lgkmcnt(0)
	s_barrier
	s_setprio 1
	s_waitcnt lgkmcnt(0)
	v_mfma_f32_16x16x32_bf16 v[124:127], v[148:151], v[180:183], v[124:127]
	v_mfma_f32_16x16x32_bf16 v[124:127], v[152:155], v[184:187], v[124:127]
	v_mfma_f32_16x16x32_bf16 v[120:123], v[156:159], v[180:183], v[120:123]
	v_mfma_f32_16x16x32_bf16 v[120:123], v[160:163], v[184:187], v[120:123]
	v_mfma_f32_16x16x32_bf16 v[116:119], v[148:151], v[188:191], v[116:119]
	v_mfma_f32_16x16x32_bf16 v[116:119], v[152:155], v[194:197], v[116:119]
	v_mfma_f32_16x16x32_bf16 v[108:111], v[156:159], v[188:191], v[108:111]
	v_mfma_f32_16x16x32_bf16 v[108:111], v[160:163], v[194:197], v[108:111]
	v_mfma_f32_16x16x32_bf16 v[100:103], v[148:151], v[198:201], v[100:103]
	v_mfma_f32_16x16x32_bf16 v[100:103], v[152:155], v[202:205], v[100:103]
	v_mfma_f32_16x16x32_bf16 v[92:95], v[156:159], v[198:201], v[92:95]
	v_mfma_f32_16x16x32_bf16 v[92:95], v[160:163], v[202:205], v[92:95]
	v_mfma_f32_16x16x32_bf16 v[84:87], v[148:151], v[206:209], v[84:87]
	v_mfma_f32_16x16x32_bf16 v[84:87], v[152:155], v[210:213], v[84:87]
	v_mfma_f32_16x16x32_bf16 v[76:79], v[156:159], v[206:209], v[76:79]
	v_mfma_f32_16x16x32_bf16 v[76:79], v[160:163], v[210:213], v[76:79]
	s_setprio 0
	s_setprio 1
	v_mfma_f32_16x16x32_bf16 v[112:115], v[164:167], v[180:183], v[112:115]
	v_mfma_f32_16x16x32_bf16 v[112:115], v[168:171], v[184:187], v[112:115]
	v_mfma_f32_16x16x32_bf16 v[104:107], v[172:175], v[180:183], v[104:107]
	v_mfma_f32_16x16x32_bf16 v[104:107], v[176:179], v[184:187], v[104:107]
	v_mfma_f32_16x16x32_bf16 v[96:99], v[164:167], v[188:191], v[96:99]
	v_mfma_f32_16x16x32_bf16 v[96:99], v[168:171], v[194:197], v[96:99]
	v_mfma_f32_16x16x32_bf16 v[88:91], v[172:175], v[188:191], v[88:91]
	v_mfma_f32_16x16x32_bf16 v[88:91], v[176:179], v[194:197], v[88:91]
	v_mfma_f32_16x16x32_bf16 v[80:83], v[164:167], v[198:201], v[80:83]
	v_mfma_f32_16x16x32_bf16 v[80:83], v[168:171], v[202:205], v[80:83]
	v_mfma_f32_16x16x32_bf16 v[72:75], v[172:175], v[198:201], v[72:75]
	v_mfma_f32_16x16x32_bf16 v[72:75], v[176:179], v[202:205], v[72:75]
	v_mfma_f32_16x16x32_bf16 v[68:71], v[164:167], v[206:209], v[68:71]
	v_mfma_f32_16x16x32_bf16 v[68:71], v[168:171], v[210:213], v[68:71]
	v_mfma_f32_16x16x32_bf16 v[64:67], v[172:175], v[206:209], v[64:67]
	v_mfma_f32_16x16x32_bf16 v[64:67], v[176:179], v[210:213], v[64:67]
	s_setprio 0
	s_barrier
; #define PG8_STAGE(bufoff, gbase, voff) do { _Pragma("unroll") for (int _i = 0; _i < 2; ++_i) \
;         __builtin_amdgcn_global_load_lds((const unsigned*)((const char*)(gbase) + (voff)[_i]), (LAS unsigned*)(lds + (bufoff) + ldsw + _i * 8192), 16, 0, 0); } while (0)
; #define PG8_LDA(dst, b, h) do { _Pragma("unroll") for (int m = 0; m < 4; ++m) _Pragma("unroll") for (int k = 0; k < 2; ++k) dst[m][k] = *(const LAS bf16x8*)(lds + PG8_SA(b, h) + aoff + m * 2048 + k * 1024); } while (0)
; #define PG8_MMA(ai, bj, At, Bt) do { __builtin_amdgcn_s_setprio(1); _Pragma("unroll") for (int m = 0; m < 4; ++m) _Pragma("unroll") for (int n = 0; n < 2; ++n) _Pragma("unroll") for (int k = 0; k < 2; ++k) \
;         acc[ai][bj][m][n] = __builtin_amdgcn_mfma_f32_16x16x32_bf16(Bt[n][k], At[m][k], acc[ai][bj][m][n], 0, 0, 0); __builtin_amdgcn_s_setprio(0); } while (0)
; #define PG8_WAIT_V(n) asm volatile("s_waitcnt vmcnt(" #n ")" ::: "memory")
; #define PG8_WAIT_L(n) asm volatile("s_waitcnt lgkmcnt(" #n ")" ::: "memory")
; #define PG8_BAR __builtin_amdgcn_s_barrier()
; #define PG8_SCHED __builtin_amdgcn_sched_barrier(0)
; template <class Epi, bool ALIGN_EPI>
; __device__ __forceinline__ void gemm_phase(LAS unsigned char* lds, const Gemm g, const StaticOrder& S, const Epi& E) {
;     ...
;         for (int t = 0; t < nt; t += 2) {
;     ...
;             PG8_LDA(At, 1, 1); PG8_STAGE(PG8_SB(1, 0), b3, voffB); PG8_STAGE(PG8_SB(1, 1), b3 + hB, voffB); PG8_STAGE(PG8_SA(1, 0), a3, voffA);
;             PG8_WAIT_V(8); PG8_WAIT_L(0); PG8_BAR; PG8_MMA(1, 0, At, B0); PG8_MMA(1, 1, At, B1); PG8_BAR; PG8_SCHED;
	s_add_i32 s34, s54, s1
	v_lshl_add_u64 v[140:141], v[140:141], 0, s[10:11]
	s_mov_b32 m0, s34
	ds_read_b128 v[180:183], v147 offset:49152
	ds_read_b128 v[184:187], v147 offset:50176
	ds_read_b128 v[188:191], v147 offset:51200
	ds_read_b128 v[194:197], v147 offset:52224
	ds_read_b128 v[198:201], v147 offset:53248
	ds_read_b128 v[202:205], v147 offset:54272
	ds_read_b128 v[206:209], v147 offset:55296
	ds_read_b128 v[210:213], v147 offset:56320
	global_load_lds_dwordx4 v[140:141], off
	s_add_i32 m0, s34, 0x2000
	s_add_u32 s30, s30, 0x80080
	v_lshl_add_u64 v[140:141], v[214:215], 0, s[10:11]
	s_addc_u32 s31, s31, 0
	s_add_i32 s34, s55, s1
	global_load_lds_dwordx4 v[140:141], off
	s_waitcnt vmcnt(4)
	s_waitcnt lgkmcnt(0)
	s_barrier
	s_setprio 1
	s_waitcnt lgkmcnt(0)
	v_mfma_f32_16x16x32_bf16 v[60:63], v[148:151], v[180:183], v[60:63]
	v_mfma_f32_16x16x32_bf16 v[60:63], v[152:155], v[184:187], v[60:63]
	v_mfma_f32_16x16x32_bf16 v[56:59], v[156:159], v[180:183], v[56:59]
	v_mfma_f32_16x16x32_bf16 v[56:59], v[160:163], v[184:187], v[56:59]
	v_lshl_add_u64 v[140:141], s[30:31], 0, v[132:133]
	s_mov_b32 m0, s34
	s_nop 0
	global_load_lds_dwordx4 v[140:141], off
	v_mfma_f32_16x16x32_bf16 v[52:55], v[148:151], v[188:191], v[52:55]
	v_mfma_f32_16x16x32_bf16 v[52:55], v[152:155], v[194:197], v[52:55]
	v_mfma_f32_16x16x32_bf16 v[44:47], v[156:159], v[188:191], v[44:47]
	v_mfma_f32_16x16x32_bf16 v[44:47], v[160:163], v[194:197], v[44:47]
	v_mfma_f32_16x16x32_bf16 v[36:39], v[148:151], v[198:201], v[36:39]
	v_mfma_f32_16x16x32_bf16 v[36:39], v[152:155], v[202:205], v[36:39]
	v_lshl_add_u64 v[140:141], s[30:31], 0, v[128:129]
	s_add_i32 m0, s34, 0x2000
	s_nop 0
	global_load_lds_dwordx4 v[140:141], off
	v_mfma_f32_16x16x32_bf16 v[28:31], v[156:159], v[198:201], v[28:31]
	v_mfma_f32_16x16x32_bf16 v[28:31], v[160:163], v[202:205], v[28:31]
	v_mfma_f32_16x16x32_bf16 v[20:23], v[148:151], v[206:209], v[20:23]
	v_mfma_f32_16x16x32_bf16 v[20:23], v[152:155], v[210:213], v[20:23]
	v_mfma_f32_16x16x32_bf16 v[12:15], v[156:159], v[206:209], v[12:15]
	v_mfma_f32_16x16x32_bf16 v[12:15], v[160:163], v[210:213], v[12:15]
	s_setprio 0
	s_setprio 1
	v_mfma_f32_16x16x32_bf16 v[48:51], v[164:167], v[180:183], v[48:51]
	v_mfma_f32_16x16x32_bf16 v[48:51], v[168:171], v[184:187], v[48:51]
	v_lshl_add_u64 v[140:141], v[216:217], 0, s[10:11]
	s_mov_b32 m0, s42
	s_nop 0
	global_load_lds_dwordx4 v[140:141], off
	v_mfma_f32_16x16x32_bf16 v[40:43], v[172:175], v[180:183], v[40:43]
	v_mfma_f32_16x16x32_bf16 v[40:43], v[176:179], v[184:187], v[40:43]
	v_mfma_f32_16x16x32_bf16 v[32:35], v[164:167], v[188:191], v[32:35]
	v_mfma_f32_16x16x32_bf16 v[32:35], v[168:171], v[194:197], v[32:35]
	v_mfma_f32_16x16x32_bf16 v[24:27], v[172:175], v[188:191], v[24:27]
	v_mfma_f32_16x16x32_bf16 v[24:27], v[176:179], v[194:197], v[24:27]
	v_lshl_add_u64 v[140:141], v[218:219], 0, s[10:11]
	s_mov_b32 m0, s43
	s_nop 0
	global_load_lds_dwordx4 v[140:141], off
	v_mfma_f32_16x16x32_bf16 v[16:19], v[164:167], v[198:201], v[16:19]
	v_mfma_f32_16x16x32_bf16 v[16:19], v[168:171], v[202:205], v[16:19]
	v_mfma_f32_16x16x32_bf16 v[8:11], v[172:175], v[198:201], v[8:11]
	v_mfma_f32_16x16x32_bf16 v[8:11], v[176:179], v[202:205], v[8:11]
	v_mfma_f32_16x16x32_bf16 v[4:7], v[164:167], v[206:209], v[4:7]
	v_mfma_f32_16x16x32_bf16 v[4:7], v[168:171], v[210:213], v[4:7]
	v_mfma_f32_16x16x32_bf16 v[0:3], v[172:175], v[206:209], v[0:3]
	v_mfma_f32_16x16x32_bf16 v[0:3], v[176:179], v[210:213], v[0:3]
	s_setprio 0
	s_barrier
	s_add_i32 s53, s53, 2
	s_add_u32 s28, s28, 0x100
	s_addc_u32 s29, s29, 0
	s_add_u32 s51, s51, 0x100
	s_addc_u32 s52, s52, 0
	s_cmp_gt_u32 s53, 29
	s_cbranch_scc0 .LBB0_419
	s_and_b64 vcc, exec, s[14:15]
	s_cbranch_vccz .LBB0_422
	s_barrier

; #define PG8_STAGE(bufoff, gbase, voff) do { _Pragma("unroll") for (int _i = 0; _i < 2; ++_i) \
;         __builtin_amdgcn_global_load_lds((const unsigned*)((const char*)(gbase) + (voff)[_i]), (LAS unsigned*)(lds + (bufoff) + ldsw + _i * 8192), 16, 0, 0); } while (0)
; #define PG8_LDA(dst, b, h) do { _Pragma("unroll") for (int m = 0; m < 4; ++m) _Pragma("unroll") for (int k = 0; k < 2; ++k) dst[m][k] = *(const LAS bf16x8*)(lds + PG8_SA(b, h) + aoff + m * 2048 + k * 1024); } while (0)
; #define PG8_LDB(dst, b, h) do { _Pragma("unroll") for (int n = 0; n < 2; ++n) _Pragma("unroll") for (int k = 0; k < 2; ++k) dst[n][k] = *(const LAS bf16x8*)(lds + PG8_SB(b, h) + boff + n * 2048 + k * 1024); } while (0)
; #define PG8_MMA(ai, bj, At, Bt) do { __builtin_amdgcn_s_setprio(1); _Pragma("unroll") for (int m = 0; m < 4; ++m) _Pragma("unroll") for (int n = 0; n < 2; ++n) _Pragma("unroll") for (int k = 0; k < 2; ++k) \
;         acc[ai][bj][m][n] = __builtin_amdgcn_mfma_f32_16x16x32_bf16(Bt[n][k], At[m][k], acc[ai][bj][m][n], 0, 0, 0); __builtin_amdgcn_s_setprio(0); } while (0)
; #define PG8_WAIT_V(n) asm volatile("s_waitcnt vmcnt(" #n ")" ::: "memory")
; #define PG8_WAIT_L(n) asm volatile("s_waitcnt lgkmcnt(" #n ")" ::: "memory")
; #define PG8_BAR __builtin_amdgcn_s_barrier()
; #define PG8_SCHED __builtin_amdgcn_sched_barrier(0)
; template <class Epi, bool ALIGN_EPI>
; __device__ __forceinline__ void gemm_phase(LAS unsigned char* lds, const Gemm g, const StaticOrder& S, const Epi& E) {
;     ...
;             PG8_LDB(B0, 0, 0); PG8_LDB(B1, 0, 1); PG8_SCHED; PG8_LDA(At, 0, 0); PG8_STAGE(PG8_SA(1, 1), a1 + hA, voffA);
;             PG8_WAIT_V(8); PG8_WAIT_L(0); PG8_BAR; PG8_MMA(0, 0, At, B0); PG8_MMA(0, 1, At, B1); PG8_BAR; PG8_SCHED;
;             PG8_LDA(At, 0, 1); PG8_STAGE(PG8_SB(0, 0), b2, voffB); PG8_STAGE(PG8_SB(0, 1), b2 + hB, voffB); PG8_STAGE(PG8_SA(0, 0), a2, voffA);
;             PG8_WAIT_V(8); PG8_WAIT_L(0); PG8_BAR; PG8_MMA(1, 0, At, B0); PG8_MMA(1, 1, At, B1); PG8_BAR; PG8_SCHED;
.LBB0_775:
	ds_read_b128 v[128:131], v196
	ds_read_b128 v[132:135], v196 offset:1024
	ds_read_b128 v[136:139], v196 offset:2048
	ds_read_b128 v[140:143], v196 offset:3072
	ds_read_b128 v[144:147], v197
	ds_read_b128 v[148:151], v197 offset:1024
	ds_read_b128 v[152:155], v197 offset:2048
	ds_read_b128 v[156:159], v197 offset:3072
	s_add_u32 s37, s40, 0xfff80080
	s_addc_u32 s38, s41, -1
	s_cmp_eq_u32 s29, 28
	s_cselect_b32 s45, s0, s38
	s_cselect_b32 s44, s1, s37
	s_cselect_b32 s43, s2, s27
	s_cselect_b32 s42, s3, s9
	v_lshl_add_u64 v[216:217], s[40:41], 0, v[168:169]
	s_add_i32 m0, s50, 0xc000
	ds_read_b128 v[176:179], v198
	ds_read_b128 v[180:183], v198 offset:1024
	ds_read_b128 v[184:187], v198 offset:2048
	ds_read_b128 v[188:191], v198 offset:3072
	ds_read_b128 v[200:203], v198 offset:4096
	ds_read_b128 v[204:207], v198 offset:5120
	ds_read_b128 v[208:211], v198 offset:6144
	ds_read_b128 v[212:215], v198 offset:7168
	global_load_lds_dwordx4 v[216:217], off
	v_lshl_add_u64 v[216:217], s[40:41], 0, v[170:171]
	s_add_i32 m0, s50, 0xe000
	s_nop 0
	global_load_lds_dwordx4 v[216:217], off
	s_waitcnt vmcnt(8)
	s_waitcnt lgkmcnt(0)
	s_barrier
	s_setprio 1
	s_waitcnt lgkmcnt(0)
	v_mfma_f32_16x16x32_bf16 v[124:127], v[128:131], v[176:179], v[124:127]
	v_mfma_f32_16x16x32_bf16 v[124:127], v[132:135], v[180:183], v[124:127]
	v_mfma_f32_16x16x32_bf16 v[120:123], v[136:139], v[176:179], v[120:123]
	v_mfma_f32_16x16x32_bf16 v[120:123], v[140:143], v[180:183], v[120:123]
	v_mfma_f32_16x16x32_bf16 v[108:111], v[128:131], v[184:187], v[108:111]
	v_mfma_f32_16x16x32_bf16 v[108:111], v[132:135], v[188:191], v[108:111]
	v_mfma_f32_16x16x32_bf16 v[104:107], v[136:139], v[184:187], v[104:107]
	v_mfma_f32_16x16x32_bf16 v[104:107], v[140:143], v[188:191], v[104:107]
	v_mfma_f32_16x16x32_bf16 v[92:95], v[128:131], v[200:203], v[92:95]
	v_mfma_f32_16x16x32_bf16 v[92:95], v[132:135], v[204:207], v[92:95]
	v_mfma_f32_16x16x32_bf16 v[88:91], v[136:139], v[200:203], v[88:91]
	v_mfma_f32_16x16x32_bf16 v[88:91], v[140:143], v[204:207], v[88:91]
	v_mfma_f32_16x16x32_bf16 v[76:79], v[128:131], v[208:211], v[76:79]
	v_mfma_f32_16x16x32_bf16 v[76:79], v[132:135], v[212:215], v[76:79]
	v_mfma_f32_16x16x32_bf16 v[72:75], v[136:139], v[208:211], v[72:75]
	v_mfma_f32_16x16x32_bf16 v[72:75], v[140:143], v[212:215], v[72:75]
	s_setprio 0
	s_setprio 1
	v_mfma_f32_16x16x32_bf16 v[116:119], v[144:147], v[176:179], v[116:119]
	v_mfma_f32_16x16x32_bf16 v[116:119], v[148:151], v[180:183], v[116:119]
	v_mfma_f32_16x16x32_bf16 v[112:115], v[152:155], v[176:179], v[112:115]
	v_mfma_f32_16x16x32_bf16 v[112:115], v[156:159], v[180:183], v[112:115]
	v_mfma_f32_16x16x32_bf16 v[100:103], v[144:147], v[184:187], v[100:103]
	v_mfma_f32_16x16x32_bf16 v[100:103], v[148:151], v[188:191], v[100:103]
	v_mfma_f32_16x16x32_bf16 v[96:99], v[152:155], v[184:187], v[96:99]
	v_mfma_f32_16x16x32_bf16 v[96:99], v[156:159], v[188:191], v[96:99]
	v_mfma_f32_16x16x32_bf16 v[84:87], v[144:147], v[200:203], v[84:87]
	v_mfma_f32_16x16x32_bf16 v[84:87], v[148:151], v[204:207], v[84:87]
	v_mfma_f32_16x16x32_bf16 v[80:83], v[152:155], v[200:203], v[80:83]
	v_mfma_f32_16x16x32_bf16 v[80:83], v[156:159], v[204:207], v[80:83]
	v_mfma_f32_16x16x32_bf16 v[68:71], v[144:147], v[208:211], v[68:71]
	v_mfma_f32_16x16x32_bf16 v[68:71], v[148:151], v[212:215], v[68:71]
	v_mfma_f32_16x16x32_bf16 v[64:67], v[152:155], v[208:211], v[64:67]
	v_mfma_f32_16x16x32_bf16 v[64:67], v[156:159], v[212:215], v[64:67]
	s_setprio 0
	s_barrier
	s_add_i32 s37, s60, s49
	v_lshl_add_u64 v[216:217], s[42:43], 0, v[162:163]
	s_mov_b32 m0, s37
	ds_read_b128 v[176:179], v198 offset:16384
	ds_read_b128 v[180:183], v198 offset:17408
	ds_read_b128 v[184:187], v198 offset:18432
	ds_read_b128 v[188:191], v198 offset:19456
	ds_read_b128 v[200:203], v198 offset:20480
	ds_read_b128 v[204:207], v198 offset:21504
	ds_read_b128 v[208:211], v198 offset:22528
	ds_read_b128 v[212:215], v198 offset:23552
	global_load_lds_dwordx4 v[216:217], off
	s_add_i32 m0, s37, 0x2000
	s_add_u32 s38, s42, 0x80000
	v_lshl_add_u64 v[218:219], s[42:43], 0, v[166:167]
	s_addc_u32 s39, s43, 0
	s_add_i32 s37, s61, s49
	global_load_lds_dwordx4 v[218:219], off
	s_waitcnt vmcnt(4)
	s_waitcnt lgkmcnt(0)
	s_barrier
	s_setprio 1
	s_waitcnt lgkmcnt(0)
	v_mfma_f32_16x16x32_bf16 v[60:63], v[128:131], v[176:179], v[60:63]
	v_mfma_f32_16x16x32_bf16 v[60:63], v[132:135], v[180:183], v[60:63]
	v_mfma_f32_16x16x32_bf16 v[56:59], v[136:139], v[176:179], v[56:59]
	v_mfma_f32_16x16x32_bf16 v[56:59], v[140:143], v[180:183], v[56:59]
	v_lshl_add_u64 v[220:221], s[38:39], 0, v[162:163]
	s_mov_b32 m0, s37
	v_lshl_add_u64 v[222:223], s[44:45], 0, v[164:165]
	global_load_lds_dwordx4 v[220:221], off
	v_mfma_f32_16x16x32_bf16 v[44:47], v[128:131], v[184:187], v[44:47]
	v_mfma_f32_16x16x32_bf16 v[44:47], v[132:135], v[188:191], v[44:47]
	v_mfma_f32_16x16x32_bf16 v[40:43], v[136:139], v[184:187], v[40:43]
	v_mfma_f32_16x16x32_bf16 v[40:43], v[140:143], v[188:191], v[40:43]
	v_mfma_f32_16x16x32_bf16 v[28:31], v[128:131], v[200:203], v[28:31]
	v_mfma_f32_16x16x32_bf16 v[28:31], v[132:135], v[204:207], v[28:31]
	v_lshl_add_u64 v[220:221], s[38:39], 0, v[166:167]
	s_add_i32 m0, s37, 0x2000
	s_nop 0
	global_load_lds_dwordx4 v[220:221], off
	v_mfma_f32_16x16x32_bf16 v[24:27], v[136:139], v[200:203], v[24:27]
	v_mfma_f32_16x16x32_bf16 v[24:27], v[140:143], v[204:207], v[24:27]
	v_mfma_f32_16x16x32_bf16 v[16:19], v[128:131], v[208:211], v[16:19]
	v_mfma_f32_16x16x32_bf16 v[16:19], v[132:135], v[212:215], v[16:19]
	v_mfma_f32_16x16x32_bf16 v[8:11], v[136:139], v[208:211], v[8:11]
	v_mfma_f32_16x16x32_bf16 v[8:11], v[140:143], v[212:215], v[8:11]
	s_setprio 0
	s_setprio 1
	v_mfma_f32_16x16x32_bf16 v[52:55], v[144:147], v[176:179], v[52:55]
	v_mfma_f32_16x16x32_bf16 v[52:55], v[148:151], v[180:183], v[52:55]
	v_lshl_add_u64 v[220:221], s[44:45], 0, v[160:161]
	s_mov_b32 m0, s50
	s_nop 0
	global_load_lds_dwordx4 v[220:221], off
	v_mfma_f32_16x16x32_bf16 v[48:51], v[152:155], v[176:179], v[48:51]
	v_mfma_f32_16x16x32_bf16 v[48:51], v[156:159], v[180:183], v[48:51]
	v_mfma_f32_16x16x32_bf16 v[36:39], v[144:147], v[184:187], v[36:39]
	v_mfma_f32_16x16x32_bf16 v[36:39], v[148:151], v[188:191], v[36:39]
	v_mfma_f32_16x16x32_bf16 v[32:35], v[152:155], v[184:187], v[32:35]
	v_mfma_f32_16x16x32_bf16 v[32:35], v[156:159], v[188:191], v[32:35]
	s_mov_b32 m0, s51
	s_nop 0
	global_load_lds_dwordx4 v[222:223], off
	v_mfma_f32_16x16x32_bf16 v[20:23], v[144:147], v[200:203], v[20:23]
	v_mfma_f32_16x16x32_bf16 v[20:23], v[148:151], v[204:207], v[20:23]
	v_mfma_f32_16x16x32_bf16 v[12:15], v[152:155], v[200:203], v[12:15]
	v_mfma_f32_16x16x32_bf16 v[12:15], v[156:159], v[204:207], v[12:15]
	v_mfma_f32_16x16x32_bf16 v[4:7], v[144:147], v[208:211], v[4:7]
	v_mfma_f32_16x16x32_bf16 v[4:7], v[148:151], v[212:215], v[4:7]
	v_mfma_f32_16x16x32_bf16 v[0:3], v[152:155], v[208:211], v[0:3]
	v_mfma_f32_16x16x32_bf16 v[0:3], v[156:159], v[212:215], v[0:3]
	s_setprio 0
	s_barrier
; #define PG8_STAGE(bufoff, gbase, voff) do { _Pragma("unroll") for (int _i = 0; _i < 2; ++_i) \
;         __builtin_amdgcn_global_load_lds((const unsigned*)((const char*)(gbase) + (voff)[_i]), (LAS unsigned*)(lds + (bufoff) + ldsw + _i * 8192), 16, 0, 0); } while (0)
; #define PG8_LDA(dst, b, h) do { _Pragma("unroll") for (int m = 0; m < 4; ++m) _Pragma("unroll") for (int k = 0; k < 2; ++k) dst[m][k] = *(const LAS bf16x8*)(lds + PG8_SA(b, h) + aoff + m * 2048 + k * 1024); } while (0)
; #define PG8_LDB(dst, b, h) do { _Pragma("unroll") for (int n = 0; n < 2; ++n) _Pragma("unroll") for (int k = 0; k < 2; ++k) dst[n][k] = *(const LAS bf16x8*)(lds + PG8_SB(b, h) + boff + n * 2048 + k * 1024); } while (0)
; #define PG8_MMA(ai, bj, At, Bt) do { __builtin_amdgcn_s_setprio(1); _Pragma("unroll") for (int m = 0; m < 4; ++m) _Pragma("unroll") for (int n = 0; n < 2; ++n) _Pragma("unroll") for (int k = 0; k < 2; ++k) \
;         acc[ai][bj][m][n] = __builtin_amdgcn_mfma_f32_16x16x32_bf16(Bt[n][k], At[m][k], acc[ai][bj][m][n], 0, 0, 0); __builtin_amdgcn_s_setprio(0); } while (0)
; #define PG8_WAIT_V(n) asm volatile("s_waitcnt vmcnt(" #n ")" ::: "memory")
; #define PG8_WAIT_L(n) asm volatile("s_waitcnt lgkmcnt(" #n ")" ::: "memory")
; #define PG8_BAR __builtin_amdgcn_s_barrier()
; #define PG8_SCHED __builtin_amdgcn_sched_barrier(0)
; template <class Epi, bool ALIGN_EPI>
; __device__ __forceinline__ void gemm_phase(LAS unsigned char* lds, const Gemm g, const StaticOrder& S, const Epi& E) {
;     ...
;             PG8_LDB(B0, 1, 0); PG8_LDB(B1, 1, 1); PG8_SCHED; PG8_LDA(At, 1, 0); PG8_STAGE(PG8_SA(0, 1), a2 + hA, voffA);
;             PG8_WAIT_V(8); PG8_WAIT_L(0); PG8_BAR; PG8_MMA(0, 0, At, B0); PG8_MMA(0, 1, At, B1); PG8_BAR; PG8_SCHED;
	s_add_i32 s37, 0, 0x18000
	s_add_i32 s63, 0, 0x1c000
	v_add_u32_e32 v140, s37, v194
	v_add_u32_e32 v156, s63, v194
	ds_read_b128 v[128:131], v140
	ds_read_b128 v[132:135], v140 offset:1024
	ds_read_b128 v[136:139], v140 offset:2048
	ds_read_b128 v[140:143], v140 offset:3072
	ds_read_b128 v[144:147], v156
	ds_read_b128 v[148:151], v156 offset:1024
	ds_read_b128 v[152:155], v156 offset:2048
	ds_read_b128 v[156:159], v156 offset:3072
	s_add_u32 s38, s44, 0x80000
	s_addc_u32 s39, s45, 0
	s_mov_b32 m0, s52
	v_lshl_add_u64 v[224:225], s[38:39], 0, v[160:161]
	ds_read_b128 v[176:179], v198 offset:32768
	ds_read_b128 v[180:183], v198 offset:33792
	ds_read_b128 v[184:187], v198 offset:34816
	ds_read_b128 v[188:191], v198 offset:35840
	ds_read_b128 v[200:203], v198 offset:36864
	ds_read_b128 v[204:207], v198 offset:37888
	ds_read_b128 v[208:211], v198 offset:38912
	ds_read_b128 v[212:215], v198 offset:39936
	global_load_lds_dwordx4 v[224:225], off
	v_lshl_add_u64 v[224:225], s[38:39], 0, v[164:165]
	s_mov_b32 m0, s53
	s_nop 0
	global_load_lds_dwordx4 v[224:225], off
	s_waitcnt vmcnt(8)
	s_waitcnt lgkmcnt(0)
	s_barrier
	s_setprio 1
	s_waitcnt lgkmcnt(0)
	v_mfma_f32_16x16x32_bf16 v[124:127], v[128:131], v[176:179], v[124:127]
	v_mfma_f32_16x16x32_bf16 v[124:127], v[132:135], v[180:183], v[124:127]
	v_mfma_f32_16x16x32_bf16 v[120:123], v[136:139], v[176:179], v[120:123]
	v_mfma_f32_16x16x32_bf16 v[120:123], v[140:143], v[180:183], v[120:123]
	v_mfma_f32_16x16x32_bf16 v[108:111], v[128:131], v[184:187], v[108:111]
	v_mfma_f32_16x16x32_bf16 v[108:111], v[132:135], v[188:191], v[108:111]
	v_mfma_f32_16x16x32_bf16 v[104:107], v[136:139], v[184:187], v[104:107]
	v_mfma_f32_16x16x32_bf16 v[104:107], v[140:143], v[188:191], v[104:107]
	v_mfma_f32_16x16x32_bf16 v[92:95], v[128:131], v[200:203], v[92:95]
	v_mfma_f32_16x16x32_bf16 v[92:95], v[132:135], v[204:207], v[92:95]
	v_mfma_f32_16x16x32_bf16 v[88:91], v[136:139], v[200:203], v[88:91]
	v_mfma_f32_16x16x32_bf16 v[88:91], v[140:143], v[204:207], v[88:91]
	v_mfma_f32_16x16x32_bf16 v[76:79], v[128:131], v[208:211], v[76:79]
	v_mfma_f32_16x16x32_bf16 v[76:79], v[132:135], v[212:215], v[76:79]
	v_mfma_f32_16x16x32_bf16 v[72:75], v[136:139], v[208:211], v[72:75]
	v_mfma_f32_16x16x32_bf16 v[72:75], v[140:143], v[212:215], v[72:75]
	s_setprio 0
	s_setprio 1
	v_mfma_f32_16x16x32_bf16 v[116:119], v[144:147], v[176:179], v[116:119]
	v_mfma_f32_16x16x32_bf16 v[116:119], v[148:151], v[180:183], v[116:119]
	v_mfma_f32_16x16x32_bf16 v[112:115], v[152:155], v[176:179], v[112:115]
	v_mfma_f32_16x16x32_bf16 v[112:115], v[156:159], v[180:183], v[112:115]
	v_mfma_f32_16x16x32_bf16 v[100:103], v[144:147], v[184:187], v[100:103]
	v_mfma_f32_16x16x32_bf16 v[100:103], v[148:151], v[188:191], v[100:103]
	v_mfma_f32_16x16x32_bf16 v[96:99], v[152:155], v[184:187], v[96:99]
	v_mfma_f32_16x16x32_bf16 v[96:99], v[156:159], v[188:191], v[96:99]
	v_mfma_f32_16x16x32_bf16 v[84:87], v[144:147], v[200:203], v[84:87]
	v_mfma_f32_16x16x32_bf16 v[84:87], v[148:151], v[204:207], v[84:87]
	v_mfma_f32_16x16x32_bf16 v[80:83], v[152:155], v[200:203], v[80:83]
	v_mfma_f32_16x16x32_bf16 v[80:83], v[156:159], v[204:207], v[80:83]
	v_mfma_f32_16x16x32_bf16 v[68:71], v[144:147], v[208:211], v[68:71]
	v_mfma_f32_16x16x32_bf16 v[68:71], v[148:151], v[212:215], v[68:71]
	v_mfma_f32_16x16x32_bf16 v[64:67], v[152:155], v[208:211], v[64:67]
	v_mfma_f32_16x16x32_bf16 v[64:67], v[156:159], v[212:215], v[64:67]
	s_setprio 0
	s_barrier
; #define PG8_STAGE(bufoff, gbase, voff) do { _Pragma("unroll") for (int _i = 0; _i < 2; ++_i) \
;         __builtin_amdgcn_global_load_lds((const unsigned*)((const char*)(gbase) + (voff)[_i]), (LAS unsigned*)(lds + (bufoff) + ldsw + _i * 8192), 16, 0, 0); } while (0)
; #define PG8_LDA(dst, b, h) do { _Pragma("unroll") for (int m = 0; m < 4; ++m) _Pragma("unroll") for (int k = 0; k < 2; ++k) dst[m][k] = *(const LAS bf16x8*)(lds + PG8_SA(b, h) + aoff + m * 2048 + k * 1024); } while (0)
; #define PG8_MMA(ai, bj, At, Bt) do { __builtin_amdgcn_s_setprio(1); _Pragma("unroll") for (int m = 0; m < 4; ++m) _Pragma("unroll") for (int n = 0; n < 2; ++n) _Pragma("unroll") for (int k = 0; k < 2; ++k) \
;         acc[ai][bj][m][n] = __builtin_amdgcn_mfma_f32_16x16x32_bf16(Bt[n][k], At[m][k], acc[ai][bj][m][n], 0, 0, 0); __builtin_amdgcn_s_setprio(0); } while (0)
; #define PG8_WAIT_V(n) asm volatile("s_waitcnt vmcnt(" #n ")" ::: "memory")
; #define PG8_WAIT_L(n) asm volatile("s_waitcnt lgkmcnt(" #n ")" ::: "memory")
; #define PG8_BAR __builtin_amdgcn_s_barrier()
; #define PG8_SCHED __builtin_amdgcn_sched_barrier(0)
; template <class Epi, bool ALIGN_EPI>
; __device__ __forceinline__ void gemm_phase(LAS unsigned char* lds, const Gemm g, const StaticOrder& S, const Epi& E) {
;     ...
;         for (int t = 0; t < nt; t += 2) {
;     ...
;             PG8_LDA(At, 1, 1); PG8_STAGE(PG8_SB(1, 0), b3, voffB); PG8_STAGE(PG8_SB(1, 1), b3 + hB, voffB); PG8_STAGE(PG8_SA(1, 0), a3, voffA);
;             PG8_WAIT_V(8); PG8_WAIT_L(0); PG8_BAR; PG8_MMA(1, 0, At, B0); PG8_MMA(1, 1, At, B1); PG8_BAR; PG8_SCHED;
	s_add_i32 s37, s37, s49
	v_lshl_add_u64 v[216:217], v[216:217], 0, s[20:21]
	s_mov_b32 m0, s37
	ds_read_b128 v[176:179], v198 offset:49152
	ds_read_b128 v[180:183], v198 offset:50176
	ds_read_b128 v[184:187], v198 offset:51200
	ds_read_b128 v[188:191], v198 offset:52224
	ds_read_b128 v[200:203], v198 offset:53248
	ds_read_b128 v[204:207], v198 offset:54272
	ds_read_b128 v[208:211], v198 offset:55296
	ds_read_b128 v[212:215], v198 offset:56320
	global_load_lds_dwordx4 v[216:217], off
	s_add_i32 m0, s37, 0x2000
	s_add_u32 s38, s42, 0x80080
	v_lshl_add_u64 v[216:217], v[218:219], 0, s[20:21]
	s_addc_u32 s39, s43, 0
	s_add_i32 s37, s63, s49
	global_load_lds_dwordx4 v[216:217], off
	s_waitcnt vmcnt(4)
	s_waitcnt lgkmcnt(0)
	s_barrier
	s_setprio 1
	s_waitcnt lgkmcnt(0)
	v_mfma_f32_16x16x32_bf16 v[60:63], v[128:131], v[176:179], v[60:63]
	v_mfma_f32_16x16x32_bf16 v[60:63], v[132:135], v[180:183], v[60:63]
	v_mfma_f32_16x16x32_bf16 v[56:59], v[136:139], v[176:179], v[56:59]
	v_mfma_f32_16x16x32_bf16 v[56:59], v[140:143], v[180:183], v[56:59]
	v_lshl_add_u64 v[216:217], s[38:39], 0, v[162:163]
	s_mov_b32 m0, s37
	s_nop 0
	global_load_lds_dwordx4 v[216:217], off
	v_mfma_f32_16x16x32_bf16 v[44:47], v[128:131], v[184:187], v[44:47]
	v_mfma_f32_16x16x32_bf16 v[44:47], v[132:135], v[188:191], v[44:47]
	v_mfma_f32_16x16x32_bf16 v[40:43], v[136:139], v[184:187], v[40:43]
	v_mfma_f32_16x16x32_bf16 v[40:43], v[140:143], v[188:191], v[40:43]
	v_mfma_f32_16x16x32_bf16 v[28:31], v[128:131], v[200:203], v[28:31]
	v_mfma_f32_16x16x32_bf16 v[28:31], v[132:135], v[204:207], v[28:31]
	v_lshl_add_u64 v[216:217], s[38:39], 0, v[166:167]
	s_add_i32 m0, s37, 0x2000
	s_nop 0
	global_load_lds_dwordx4 v[216:217], off
	v_mfma_f32_16x16x32_bf16 v[24:27], v[136:139], v[200:203], v[24:27]
	v_mfma_f32_16x16x32_bf16 v[24:27], v[140:143], v[204:207], v[24:27]
	v_mfma_f32_16x16x32_bf16 v[16:19], v[128:131], v[208:211], v[16:19]
	v_mfma_f32_16x16x32_bf16 v[16:19], v[132:135], v[212:215], v[16:19]
	v_mfma_f32_16x16x32_bf16 v[8:11], v[136:139], v[208:211], v[8:11]
	v_mfma_f32_16x16x32_bf16 v[8:11], v[140:143], v[212:215], v[8:11]
	s_setprio 0
	s_setprio 1
	v_mfma_f32_16x16x32_bf16 v[52:55], v[144:147], v[176:179], v[52:55]
	v_mfma_f32_16x16x32_bf16 v[52:55], v[148:151], v[180:183], v[52:55]
	v_lshl_add_u64 v[216:217], v[220:221], 0, s[20:21]
	s_mov_b32 m0, s57
	s_nop 0
	global_load_lds_dwordx4 v[216:217], off
	v_mfma_f32_16x16x32_bf16 v[48:51], v[152:155], v[176:179], v[48:51]
	v_mfma_f32_16x16x32_bf16 v[48:51], v[156:159], v[180:183], v[48:51]
	v_mfma_f32_16x16x32_bf16 v[36:39], v[144:147], v[184:187], v[36:39]
	v_mfma_f32_16x16x32_bf16 v[36:39], v[148:151], v[188:191], v[36:39]
	v_mfma_f32_16x16x32_bf16 v[32:35], v[152:155], v[184:187], v[32:35]
	v_mfma_f32_16x16x32_bf16 v[32:35], v[156:159], v[188:191], v[32:35]
	v_lshl_add_u64 v[216:217], v[222:223], 0, s[20:21]
	s_mov_b32 m0, s58
	s_nop 0
	global_load_lds_dwordx4 v[216:217], off
	v_mfma_f32_16x16x32_bf16 v[20:23], v[144:147], v[200:203], v[20:23]
	v_mfma_f32_16x16x32_bf16 v[20:23], v[148:151], v[204:207], v[20:23]
	v_mfma_f32_16x16x32_bf16 v[12:15], v[152:155], v[200:203], v[12:15]
	v_mfma_f32_16x16x32_bf16 v[12:15], v[156:159], v[204:207], v[12:15]
	v_mfma_f32_16x16x32_bf16 v[4:7], v[144:147], v[208:211], v[4:7]
	v_mfma_f32_16x16x32_bf16 v[4:7], v[148:151], v[212:215], v[4:7]
	v_mfma_f32_16x16x32_bf16 v[0:3], v[152:155], v[208:211], v[0:3]
	v_mfma_f32_16x16x32_bf16 v[0:3], v[156:159], v[212:215], v[0:3]
	s_setprio 0
	s_barrier
	s_add_i32 s29, s29, 2
	s_add_u32 s40, s40, 0x100
	s_addc_u32 s41, s41, 0
	s_add_u32 s9, s9, 0x100
	s_addc_u32 s27, s27, 0
	s_cmp_gt_u32 s29, 29
	s_cbranch_scc0 .LBB0_775
	s_and_b64 vcc, exec, s[22:23]
	s_cbranch_vccz .LBB0_778
	s_barrier

; #define PG8_STAGE(bufoff, gbase, voff) do { _Pragma("unroll") for (int _i = 0; _i < 2; ++_i) \
;         __builtin_amdgcn_global_load_lds((const unsigned*)((const char*)(gbase) + (voff)[_i]), (LAS unsigned*)(lds + (bufoff) + ldsw + _i * 8192), 16, 0, 0); } while (0)
; #define PG8_LDA(dst, b, h) do { _Pragma("unroll") for (int m = 0; m < 4; ++m) _Pragma("unroll") for (int k = 0; k < 2; ++k) dst[m][k] = *(const LAS bf16x8*)(lds + PG8_SA(b, h) + aoff + m * 2048 + k * 1024); } while (0)
; #define PG8_LDB(dst, b, h) do { _Pragma("unroll") for (int n = 0; n < 2; ++n) _Pragma("unroll") for (int k = 0; k < 2; ++k) dst[n][k] = *(const LAS bf16x8*)(lds + PG8_SB(b, h) + boff + n * 2048 + k * 1024); } while (0)
; #define PG8_MMA(ai, bj, At, Bt) do { __builtin_amdgcn_s_setprio(1); _Pragma("unroll") for (int m = 0; m < 4; ++m) _Pragma("unroll") for (int n = 0; n < 2; ++n) _Pragma("unroll") for (int k = 0; k < 2; ++k) \
;         acc[ai][bj][m][n] = __builtin_amdgcn_mfma_f32_16x16x32_bf16(Bt[n][k], At[m][k], acc[ai][bj][m][n], 0, 0, 0); __builtin_amdgcn_s_setprio(0); } while (0)
; #define PG8_WAIT_V(n) asm volatile("s_waitcnt vmcnt(" #n ")" ::: "memory")
; #define PG8_WAIT_L(n) asm volatile("s_waitcnt lgkmcnt(" #n ")" ::: "memory")
; #define PG8_BAR __builtin_amdgcn_s_barrier()
; #define PG8_SCHED __builtin_amdgcn_sched_barrier(0)
; template <class Epi, bool ALIGN_EPI>
; __device__ __forceinline__ void gemm_phase(LAS unsigned char* lds, const Gemm g, const StaticOrder& S, const Epi& E) {
;     ...
;             const char* a1 = cA + (size_t)(t + 1) * kstep;
;             const char* a2 = last ? nA : cA + (size_t)(t + 2) * kstep; const char* b2 = last ? nB : cB + (size_t)(t + 2) * kstep;
;             const char* a3 = a2 + kstep; const char* b3 = b2 + kstep;
;             PG8_LDB(B0, 0, 0); PG8_LDB(B1, 0, 1); PG8_SCHED; PG8_LDA(At, 0, 0); PG8_STAGE(PG8_SA(1, 1), a1 + hA, voffA);
;             PG8_WAIT_V(8); PG8_WAIT_L(0); PG8_BAR; PG8_MMA(0, 0, At, B0); PG8_MMA(0, 1, At, B1); PG8_BAR; PG8_SCHED;
;             PG8_LDA(At, 0, 1); PG8_STAGE(PG8_SB(0, 0), b2, voffB); PG8_STAGE(PG8_SB(0, 1), b2 + hB, voffB); PG8_STAGE(PG8_SA(0, 0), a2, voffA);
;             PG8_WAIT_V(8); PG8_WAIT_L(0); PG8_BAR; PG8_MMA(1, 0, At, B0); PG8_MMA(1, 1, At, B1); PG8_BAR; PG8_SCHED;
.LBB0_926:
	ds_read_b128 v[168:171], v153
	ds_read_b128 v[172:175], v153 offset:1024
	ds_read_b128 v[176:179], v153 offset:2048
	ds_read_b128 v[180:183], v153 offset:3072
	ds_read_b128 v[184:187], v155
	ds_read_b128 v[188:191], v155 offset:1024
	ds_read_b128 v[194:197], v155 offset:2048
	ds_read_b128 v[198:201], v155 offset:3072
	s_add_u32 s8, s6, 0xfff80080
	s_addc_u32 s9, s7, -1
	s_cmp_eq_u32 s71, 28
	s_cselect_b32 s55, s47, s9
	s_cselect_b32 s54, s67, s8
	s_cselect_b32 s9, s45, s70
	s_cselect_b32 s8, s68, s69
	v_lshl_add_u64 v[234:235], s[6:7], 0, v[136:137]
	s_add_i32 m0, s39, 0xc000
	ds_read_b128 v[202:205], v156
	ds_read_b128 v[206:209], v156 offset:1024
	ds_read_b128 v[210:213], v156 offset:2048
	ds_read_b128 v[214:217], v156 offset:3072
	ds_read_b128 v[218:221], v156 offset:4096
	ds_read_b128 v[222:225], v156 offset:5120
	ds_read_b128 v[226:229], v156 offset:6144
	ds_read_b128 v[230:233], v156 offset:7168
	global_load_lds_dwordx4 v[234:235], off
	v_lshl_add_u64 v[234:235], s[6:7], 0, v[138:139]
	s_add_i32 m0, s39, 0xe000
	s_nop 0
	global_load_lds_dwordx4 v[234:235], off
	s_waitcnt vmcnt(8)
	s_waitcnt lgkmcnt(0)
	s_barrier
	s_setprio 1
	s_waitcnt lgkmcnt(0)
	v_mfma_f32_16x16x32_bf16 v[124:127], v[168:171], v[202:205], v[124:127]
	v_mfma_f32_16x16x32_bf16 v[124:127], v[172:175], v[206:209], v[124:127]
	v_mfma_f32_16x16x32_bf16 v[120:123], v[176:179], v[202:205], v[120:123]
	v_mfma_f32_16x16x32_bf16 v[120:123], v[180:183], v[206:209], v[120:123]
	v_mfma_f32_16x16x32_bf16 v[108:111], v[168:171], v[210:213], v[108:111]
	v_mfma_f32_16x16x32_bf16 v[108:111], v[172:175], v[214:217], v[108:111]
	v_mfma_f32_16x16x32_bf16 v[104:107], v[176:179], v[210:213], v[104:107]
	v_mfma_f32_16x16x32_bf16 v[104:107], v[180:183], v[214:217], v[104:107]
	v_mfma_f32_16x16x32_bf16 v[92:95], v[168:171], v[218:221], v[92:95]
	v_mfma_f32_16x16x32_bf16 v[92:95], v[172:175], v[222:225], v[92:95]
	v_mfma_f32_16x16x32_bf16 v[88:91], v[176:179], v[218:221], v[88:91]
	v_mfma_f32_16x16x32_bf16 v[88:91], v[180:183], v[222:225], v[88:91]
	v_mfma_f32_16x16x32_bf16 v[76:79], v[168:171], v[226:229], v[76:79]
	v_mfma_f32_16x16x32_bf16 v[76:79], v[172:175], v[230:233], v[76:79]
	v_mfma_f32_16x16x32_bf16 v[72:75], v[176:179], v[226:229], v[72:75]
	v_mfma_f32_16x16x32_bf16 v[72:75], v[180:183], v[230:233], v[72:75]
	s_setprio 0
	s_setprio 1
	v_mfma_f32_16x16x32_bf16 v[116:119], v[184:187], v[202:205], v[116:119]
	v_mfma_f32_16x16x32_bf16 v[116:119], v[188:191], v[206:209], v[116:119]
	v_mfma_f32_16x16x32_bf16 v[112:115], v[194:197], v[202:205], v[112:115]
	v_mfma_f32_16x16x32_bf16 v[112:115], v[198:201], v[206:209], v[112:115]
	v_mfma_f32_16x16x32_bf16 v[100:103], v[184:187], v[210:213], v[100:103]
	v_mfma_f32_16x16x32_bf16 v[100:103], v[188:191], v[214:217], v[100:103]
	v_mfma_f32_16x16x32_bf16 v[96:99], v[194:197], v[210:213], v[96:99]
	v_mfma_f32_16x16x32_bf16 v[96:99], v[198:201], v[214:217], v[96:99]
	v_mfma_f32_16x16x32_bf16 v[84:87], v[184:187], v[218:221], v[84:87]
	v_mfma_f32_16x16x32_bf16 v[84:87], v[188:191], v[222:225], v[84:87]
	v_mfma_f32_16x16x32_bf16 v[80:83], v[194:197], v[218:221], v[80:83]
	v_mfma_f32_16x16x32_bf16 v[80:83], v[198:201], v[222:225], v[80:83]
	v_mfma_f32_16x16x32_bf16 v[68:71], v[184:187], v[226:229], v[68:71]
	v_mfma_f32_16x16x32_bf16 v[68:71], v[188:191], v[230:233], v[68:71]
	v_mfma_f32_16x16x32_bf16 v[64:67], v[194:197], v[226:229], v[64:67]
	v_mfma_f32_16x16x32_bf16 v[64:67], v[198:201], v[230:233], v[64:67]
	s_setprio 0
	s_barrier
	s_add_i32 s72, s63, s33
	v_lshl_add_u64 v[234:235], s[8:9], 0, v[132:133]
	s_mov_b32 m0, s72
	ds_read_b128 v[202:205], v156 offset:16384
	ds_read_b128 v[206:209], v156 offset:17408
	ds_read_b128 v[210:213], v156 offset:18432
	ds_read_b128 v[214:217], v156 offset:19456
	ds_read_b128 v[218:221], v156 offset:20480
	ds_read_b128 v[222:225], v156 offset:21504
	ds_read_b128 v[226:229], v156 offset:22528
	ds_read_b128 v[230:233], v156 offset:23552
	global_load_lds_dwordx4 v[234:235], off
	s_add_i32 m0, s72, 0x2000
	s_add_u32 s72, s8, 0x80000
	v_lshl_add_u64 v[236:237], s[8:9], 0, v[128:129]
	s_addc_u32 s73, s9, 0
	s_add_i32 s74, s64, s33
	global_load_lds_dwordx4 v[236:237], off
	s_waitcnt vmcnt(4)
	s_waitcnt lgkmcnt(0)
	s_barrier
	s_setprio 1
	s_waitcnt lgkmcnt(0)
	v_mfma_f32_16x16x32_bf16 v[60:63], v[168:171], v[202:205], v[60:63]
	v_mfma_f32_16x16x32_bf16 v[60:63], v[172:175], v[206:209], v[60:63]
	v_mfma_f32_16x16x32_bf16 v[56:59], v[176:179], v[202:205], v[56:59]
	v_mfma_f32_16x16x32_bf16 v[56:59], v[180:183], v[206:209], v[56:59]
	v_lshl_add_u64 v[238:239], s[72:73], 0, v[132:133]
	s_mov_b32 m0, s74
	v_lshl_add_u64 v[240:241], s[54:55], 0, v[130:131]
	global_load_lds_dwordx4 v[238:239], off
	v_mfma_f32_16x16x32_bf16 v[44:47], v[168:171], v[210:213], v[44:47]
	v_mfma_f32_16x16x32_bf16 v[44:47], v[172:175], v[214:217], v[44:47]
	v_mfma_f32_16x16x32_bf16 v[40:43], v[176:179], v[210:213], v[40:43]
	v_mfma_f32_16x16x32_bf16 v[40:43], v[180:183], v[214:217], v[40:43]
	v_mfma_f32_16x16x32_bf16 v[28:31], v[168:171], v[218:221], v[28:31]
	v_mfma_f32_16x16x32_bf16 v[28:31], v[172:175], v[222:225], v[28:31]
	v_lshl_add_u64 v[238:239], s[72:73], 0, v[128:129]
	s_add_i32 m0, s74, 0x2000
	s_nop 0
	global_load_lds_dwordx4 v[238:239], off
	v_mfma_f32_16x16x32_bf16 v[24:27], v[176:179], v[218:221], v[24:27]
	v_mfma_f32_16x16x32_bf16 v[24:27], v[180:183], v[222:225], v[24:27]
	v_mfma_f32_16x16x32_bf16 v[12:15], v[168:171], v[226:229], v[12:15]
	v_mfma_f32_16x16x32_bf16 v[12:15], v[172:175], v[230:233], v[12:15]
	v_mfma_f32_16x16x32_bf16 v[8:11], v[176:179], v[226:229], v[8:11]
	v_mfma_f32_16x16x32_bf16 v[8:11], v[180:183], v[230:233], v[8:11]
	s_setprio 0
	s_setprio 1
	v_mfma_f32_16x16x32_bf16 v[52:55], v[184:187], v[202:205], v[52:55]
	v_mfma_f32_16x16x32_bf16 v[52:55], v[188:191], v[206:209], v[52:55]
	v_lshl_add_u64 v[238:239], s[54:55], 0, v[134:135]
	s_mov_b32 m0, s39
	s_nop 0
	global_load_lds_dwordx4 v[238:239], off
	v_mfma_f32_16x16x32_bf16 v[48:51], v[194:197], v[202:205], v[48:51]
	v_mfma_f32_16x16x32_bf16 v[48:51], v[198:201], v[206:209], v[48:51]
	v_mfma_f32_16x16x32_bf16 v[36:39], v[184:187], v[210:213], v[36:39]
	v_mfma_f32_16x16x32_bf16 v[36:39], v[188:191], v[214:217], v[36:39]
	v_mfma_f32_16x16x32_bf16 v[32:35], v[194:197], v[210:213], v[32:35]
	v_mfma_f32_16x16x32_bf16 v[32:35], v[198:201], v[214:217], v[32:35]
	s_mov_b32 m0, s53
	s_nop 0
	global_load_lds_dwordx4 v[240:241], off
	v_mfma_f32_16x16x32_bf16 v[20:23], v[184:187], v[218:221], v[20:23]
	v_mfma_f32_16x16x32_bf16 v[20:23], v[188:191], v[222:225], v[20:23]
	v_mfma_f32_16x16x32_bf16 v[16:19], v[194:197], v[218:221], v[16:19]
	v_mfma_f32_16x16x32_bf16 v[16:19], v[198:201], v[222:225], v[16:19]
	v_mfma_f32_16x16x32_bf16 v[4:7], v[184:187], v[226:229], v[4:7]
	v_mfma_f32_16x16x32_bf16 v[4:7], v[188:191], v[230:233], v[4:7]
	v_mfma_f32_16x16x32_bf16 v[0:3], v[194:197], v[226:229], v[0:3]
	v_mfma_f32_16x16x32_bf16 v[0:3], v[198:201], v[230:233], v[0:3]
	s_setprio 0
	s_barrier
; #define PG8_STAGE(bufoff, gbase, voff) do { _Pragma("unroll") for (int _i = 0; _i < 2; ++_i) \
;         __builtin_amdgcn_global_load_lds((const unsigned*)((const char*)(gbase) + (voff)[_i]), (LAS unsigned*)(lds + (bufoff) + ldsw + _i * 8192), 16, 0, 0); } while (0)
; #define PG8_LDA(dst, b, h) do { _Pragma("unroll") for (int m = 0; m < 4; ++m) _Pragma("unroll") for (int k = 0; k < 2; ++k) dst[m][k] = *(const LAS bf16x8*)(lds + PG8_SA(b, h) + aoff + m * 2048 + k * 1024); } while (0)
; #define PG8_LDB(dst, b, h) do { _Pragma("unroll") for (int n = 0; n < 2; ++n) _Pragma("unroll") for (int k = 0; k < 2; ++k) dst[n][k] = *(const LAS bf16x8*)(lds + PG8_SB(b, h) + boff + n * 2048 + k * 1024); } while (0)
; #define PG8_MMA(ai, bj, At, Bt) do { __builtin_amdgcn_s_setprio(1); _Pragma("unroll") for (int m = 0; m < 4; ++m) _Pragma("unroll") for (int n = 0; n < 2; ++n) _Pragma("unroll") for (int k = 0; k < 2; ++k) \
;         acc[ai][bj][m][n] = __builtin_amdgcn_mfma_f32_16x16x32_bf16(Bt[n][k], At[m][k], acc[ai][bj][m][n], 0, 0, 0); __builtin_amdgcn_s_setprio(0); } while (0)
; #define PG8_WAIT_V(n) asm volatile("s_waitcnt vmcnt(" #n ")" ::: "memory")
; #define PG8_WAIT_L(n) asm volatile("s_waitcnt lgkmcnt(" #n ")" ::: "memory")
; #define PG8_BAR __builtin_amdgcn_s_barrier()
; #define PG8_SCHED __builtin_amdgcn_sched_barrier(0)
; template <class Epi, bool ALIGN_EPI>
; __device__ __forceinline__ void gemm_phase(LAS unsigned char* lds, const Gemm g, const StaticOrder& S, const Epi& E) {
;     ...
;             PG8_LDB(B0, 1, 0); PG8_LDB(B1, 1, 1); PG8_SCHED; PG8_LDA(At, 1, 0); PG8_STAGE(PG8_SA(0, 1), a2 + hA, voffA);
;             PG8_WAIT_V(8); PG8_WAIT_L(0); PG8_BAR; PG8_MMA(0, 0, At, B0); PG8_MMA(0, 1, At, B1); PG8_BAR; PG8_SCHED;
	s_add_i32 s72, 0, 0x18000
	v_add_u32_e32 v167, s72, v149
	s_add_i32 s73, 0, 0x1c000
	ds_read_b128 v[168:171], v167
	ds_read_b128 v[172:175], v167 offset:1024
	ds_read_b128 v[176:179], v167 offset:2048
	ds_read_b128 v[180:183], v167 offset:3072
	v_add_u32_e32 v167, s73, v149
	ds_read_b128 v[184:187], v167
	ds_read_b128 v[188:191], v167 offset:1024
	ds_read_b128 v[194:197], v167 offset:2048
	ds_read_b128 v[198:201], v167 offset:3072
	s_add_u32 s54, s54, 0x80000
	s_addc_u32 s55, s55, 0
	s_mov_b32 m0, s56
	v_lshl_add_u64 v[242:243], s[54:55], 0, v[134:135]
	ds_read_b128 v[202:205], v156 offset:32768
	ds_read_b128 v[206:209], v156 offset:33792
	ds_read_b128 v[210:213], v156 offset:34816
	ds_read_b128 v[214:217], v156 offset:35840
	ds_read_b128 v[218:221], v156 offset:36864
	ds_read_b128 v[222:225], v156 offset:37888
	ds_read_b128 v[226:229], v156 offset:38912
	ds_read_b128 v[230:233], v156 offset:39936
	global_load_lds_dwordx4 v[242:243], off
	v_lshl_add_u64 v[242:243], s[54:55], 0, v[130:131]
	s_mov_b32 m0, s57
	s_nop 0
	global_load_lds_dwordx4 v[242:243], off
	s_waitcnt vmcnt(8)
	s_waitcnt lgkmcnt(0)
	s_barrier
	s_setprio 1
	s_waitcnt lgkmcnt(0)
	v_mfma_f32_16x16x32_bf16 v[124:127], v[168:171], v[202:205], v[124:127]
	v_mfma_f32_16x16x32_bf16 v[124:127], v[172:175], v[206:209], v[124:127]
	v_mfma_f32_16x16x32_bf16 v[120:123], v[176:179], v[202:205], v[120:123]
	v_mfma_f32_16x16x32_bf16 v[120:123], v[180:183], v[206:209], v[120:123]
	v_mfma_f32_16x16x32_bf16 v[108:111], v[168:171], v[210:213], v[108:111]
	v_mfma_f32_16x16x32_bf16 v[108:111], v[172:175], v[214:217], v[108:111]
	v_mfma_f32_16x16x32_bf16 v[104:107], v[176:179], v[210:213], v[104:107]
	v_mfma_f32_16x16x32_bf16 v[104:107], v[180:183], v[214:217], v[104:107]
	v_mfma_f32_16x16x32_bf16 v[92:95], v[168:171], v[218:221], v[92:95]
	v_mfma_f32_16x16x32_bf16 v[92:95], v[172:175], v[222:225], v[92:95]
	v_mfma_f32_16x16x32_bf16 v[88:91], v[176:179], v[218:221], v[88:91]
	v_mfma_f32_16x16x32_bf16 v[88:91], v[180:183], v[222:225], v[88:91]
	v_mfma_f32_16x16x32_bf16 v[76:79], v[168:171], v[226:229], v[76:79]
	v_mfma_f32_16x16x32_bf16 v[76:79], v[172:175], v[230:233], v[76:79]
	v_mfma_f32_16x16x32_bf16 v[72:75], v[176:179], v[226:229], v[72:75]
	v_mfma_f32_16x16x32_bf16 v[72:75], v[180:183], v[230:233], v[72:75]
	s_setprio 0
	s_setprio 1
	v_mfma_f32_16x16x32_bf16 v[116:119], v[184:187], v[202:205], v[116:119]
	v_mfma_f32_16x16x32_bf16 v[116:119], v[188:191], v[206:209], v[116:119]
	v_mfma_f32_16x16x32_bf16 v[112:115], v[194:197], v[202:205], v[112:115]
	v_mfma_f32_16x16x32_bf16 v[112:115], v[198:201], v[206:209], v[112:115]
	v_mfma_f32_16x16x32_bf16 v[100:103], v[184:187], v[210:213], v[100:103]
	v_mfma_f32_16x16x32_bf16 v[100:103], v[188:191], v[214:217], v[100:103]
	v_mfma_f32_16x16x32_bf16 v[96:99], v[194:197], v[210:213], v[96:99]
	v_mfma_f32_16x16x32_bf16 v[96:99], v[198:201], v[214:217], v[96:99]
	v_mfma_f32_16x16x32_bf16 v[84:87], v[184:187], v[218:221], v[84:87]
	v_mfma_f32_16x16x32_bf16 v[84:87], v[188:191], v[222:225], v[84:87]
	v_mfma_f32_16x16x32_bf16 v[80:83], v[194:197], v[218:221], v[80:83]
	v_mfma_f32_16x16x32_bf16 v[80:83], v[198:201], v[222:225], v[80:83]
	v_mfma_f32_16x16x32_bf16 v[68:71], v[184:187], v[226:229], v[68:71]
	v_mfma_f32_16x16x32_bf16 v[68:71], v[188:191], v[230:233], v[68:71]
	v_mfma_f32_16x16x32_bf16 v[64:67], v[194:197], v[226:229], v[64:67]
	v_mfma_f32_16x16x32_bf16 v[64:67], v[198:201], v[230:233], v[64:67]
	s_setprio 0
	s_barrier
; #define PG8_STAGE(bufoff, gbase, voff) do { _Pragma("unroll") for (int _i = 0; _i < 2; ++_i) \
;         __builtin_amdgcn_global_load_lds((const unsigned*)((const char*)(gbase) + (voff)[_i]), (LAS unsigned*)(lds + (bufoff) + ldsw + _i * 8192), 16, 0, 0); } while (0)
; #define PG8_LDA(dst, b, h) do { _Pragma("unroll") for (int m = 0; m < 4; ++m) _Pragma("unroll") for (int k = 0; k < 2; ++k) dst[m][k] = *(const LAS bf16x8*)(lds + PG8_SA(b, h) + aoff + m * 2048 + k * 1024); } while (0)
; #define PG8_MMA(ai, bj, At, Bt) do { __builtin_amdgcn_s_setprio(1); _Pragma("unroll") for (int m = 0; m < 4; ++m) _Pragma("unroll") for (int n = 0; n < 2; ++n) _Pragma("unroll") for (int k = 0; k < 2; ++k) \
;         acc[ai][bj][m][n] = __builtin_amdgcn_mfma_f32_16x16x32_bf16(Bt[n][k], At[m][k], acc[ai][bj][m][n], 0, 0, 0); __builtin_amdgcn_s_setprio(0); } while (0)
; #define PG8_WAIT_V(n) asm volatile("s_waitcnt vmcnt(" #n ")" ::: "memory")
; #define PG8_WAIT_L(n) asm volatile("s_waitcnt lgkmcnt(" #n ")" ::: "memory")
; #define PG8_BAR __builtin_amdgcn_s_barrier()
; #define PG8_SCHED __builtin_amdgcn_sched_barrier(0)
; template <class Epi, bool ALIGN_EPI>
; __device__ __forceinline__ void gemm_phase(LAS unsigned char* lds, const Gemm g, const StaticOrder& S, const Epi& E) {
;     ...
;             PG8_LDA(At, 1, 1); PG8_STAGE(PG8_SB(1, 0), b3, voffB); PG8_STAGE(PG8_SB(1, 1), b3 + hB, voffB); PG8_STAGE(PG8_SA(1, 0), a3, voffA);
;             PG8_WAIT_V(8); PG8_WAIT_L(0); PG8_BAR; PG8_MMA(1, 0, At, B0); PG8_MMA(1, 1, At, B1); PG8_BAR; PG8_SCHED;
;         }
	s_add_i32 s54, s72, s33
	v_lshl_add_u64 v[234:235], v[234:235], 0, s[18:19]
	s_mov_b32 m0, s54
	ds_read_b128 v[202:205], v156 offset:49152
	ds_read_b128 v[206:209], v156 offset:50176
	ds_read_b128 v[210:213], v156 offset:51200
	ds_read_b128 v[214:217], v156 offset:52224
	ds_read_b128 v[218:221], v156 offset:53248
	ds_read_b128 v[222:225], v156 offset:54272
	ds_read_b128 v[226:229], v156 offset:55296
	ds_read_b128 v[230:233], v156 offset:56320
	global_load_lds_dwordx4 v[234:235], off
	s_add_i32 m0, s54, 0x2000
	s_add_u32 s8, s8, 0x80080
	v_lshl_add_u64 v[234:235], v[236:237], 0, s[18:19]
	s_addc_u32 s9, s9, 0
	s_add_i32 s54, s73, s33
	global_load_lds_dwordx4 v[234:235], off
	s_waitcnt vmcnt(4)
	s_waitcnt lgkmcnt(0)
	s_barrier
	s_setprio 1
	s_waitcnt lgkmcnt(0)
	v_mfma_f32_16x16x32_bf16 v[60:63], v[168:171], v[202:205], v[60:63]
	v_mfma_f32_16x16x32_bf16 v[60:63], v[172:175], v[206:209], v[60:63]
	v_mfma_f32_16x16x32_bf16 v[56:59], v[176:179], v[202:205], v[56:59]
	v_mfma_f32_16x16x32_bf16 v[56:59], v[180:183], v[206:209], v[56:59]
	v_lshl_add_u64 v[234:235], s[8:9], 0, v[132:133]
	s_mov_b32 m0, s54
	s_nop 0
	global_load_lds_dwordx4 v[234:235], off
	v_mfma_f32_16x16x32_bf16 v[44:47], v[168:171], v[210:213], v[44:47]
	v_mfma_f32_16x16x32_bf16 v[44:47], v[172:175], v[214:217], v[44:47]
	v_mfma_f32_16x16x32_bf16 v[40:43], v[176:179], v[210:213], v[40:43]
	v_mfma_f32_16x16x32_bf16 v[40:43], v[180:183], v[214:217], v[40:43]
	v_mfma_f32_16x16x32_bf16 v[28:31], v[168:171], v[218:221], v[28:31]
	v_mfma_f32_16x16x32_bf16 v[28:31], v[172:175], v[222:225], v[28:31]
	v_lshl_add_u64 v[234:235], s[8:9], 0, v[128:129]
	s_add_i32 m0, s54, 0x2000
	s_nop 0
	global_load_lds_dwordx4 v[234:235], off
	v_mfma_f32_16x16x32_bf16 v[24:27], v[176:179], v[218:221], v[24:27]
	v_mfma_f32_16x16x32_bf16 v[24:27], v[180:183], v[222:225], v[24:27]
	v_mfma_f32_16x16x32_bf16 v[12:15], v[168:171], v[226:229], v[12:15]
	v_mfma_f32_16x16x32_bf16 v[12:15], v[172:175], v[230:233], v[12:15]
	v_mfma_f32_16x16x32_bf16 v[8:11], v[176:179], v[226:229], v[8:11]
	v_mfma_f32_16x16x32_bf16 v[8:11], v[180:183], v[230:233], v[8:11]
	s_setprio 0
	s_setprio 1
	v_mfma_f32_16x16x32_bf16 v[52:55], v[184:187], v[202:205], v[52:55]
	v_mfma_f32_16x16x32_bf16 v[52:55], v[188:191], v[206:209], v[52:55]
	v_lshl_add_u64 v[234:235], v[238:239], 0, s[18:19]
	s_mov_b32 m0, s60
	s_nop 0
	global_load_lds_dwordx4 v[234:235], off
	v_mfma_f32_16x16x32_bf16 v[48:51], v[194:197], v[202:205], v[48:51]
	v_mfma_f32_16x16x32_bf16 v[48:51], v[198:201], v[206:209], v[48:51]
	v_mfma_f32_16x16x32_bf16 v[36:39], v[184:187], v[210:213], v[36:39]
	v_mfma_f32_16x16x32_bf16 v[36:39], v[188:191], v[214:217], v[36:39]
	v_mfma_f32_16x16x32_bf16 v[32:35], v[194:197], v[210:213], v[32:35]
	v_mfma_f32_16x16x32_bf16 v[32:35], v[198:201], v[214:217], v[32:35]
	v_lshl_add_u64 v[234:235], v[240:241], 0, s[18:19]
	s_mov_b32 m0, s61
	s_nop 0
	global_load_lds_dwordx4 v[234:235], off
	v_mfma_f32_16x16x32_bf16 v[20:23], v[184:187], v[218:221], v[20:23]
	v_mfma_f32_16x16x32_bf16 v[20:23], v[188:191], v[222:225], v[20:23]
	v_mfma_f32_16x16x32_bf16 v[16:19], v[194:197], v[218:221], v[16:19]
	v_mfma_f32_16x16x32_bf16 v[16:19], v[198:201], v[222:225], v[16:19]
	v_mfma_f32_16x16x32_bf16 v[4:7], v[184:187], v[226:229], v[4:7]
	v_mfma_f32_16x16x32_bf16 v[4:7], v[188:191], v[230:233], v[4:7]
	v_mfma_f32_16x16x32_bf16 v[0:3], v[194:197], v[226:229], v[0:3]
	v_mfma_f32_16x16x32_bf16 v[0:3], v[198:201], v[230:233], v[0:3]
	s_setprio 0
	s_barrier
	s_add_i32 s71, s71, 2
	s_add_u32 s6, s6, 0x100
	s_addc_u32 s7, s7, 0
	s_add_u32 s69, s69, 0x100
	s_addc_u32 s70, s70, 0
	s_cmp_gt_u32 s71, 29
	s_cbranch_scc0 .LBB0_926
	s_and_b64 vcc, exec, s[20:21]
	s_cbranch_vccz .LBB0_929
	s_barrier

; #define PG8_STAGE(bufoff, gbase, voff) do { _Pragma("unroll") for (int _i = 0; _i < 2; ++_i) \
;         __builtin_amdgcn_global_load_lds((const unsigned*)((const char*)(gbase) + (voff)[_i]), (LAS unsigned*)(lds + (bufoff) + ldsw + _i * 8192), 16, 0, 0); } while (0)
; #define PG8_LDA(dst, b, h) do { _Pragma("unroll") for (int m = 0; m < 4; ++m) _Pragma("unroll") for (int k = 0; k < 2; ++k) dst[m][k] = *(const LAS bf16x8*)(lds + PG8_SA(b, h) + aoff + m * 2048 + k * 1024); } while (0)
; #define PG8_LDB(dst, b, h) do { _Pragma("unroll") for (int n = 0; n < 2; ++n) _Pragma("unroll") for (int k = 0; k < 2; ++k) dst[n][k] = *(const LAS bf16x8*)(lds + PG8_SB(b, h) + boff + n * 2048 + k * 1024); } while (0)
; #define PG8_MMA(ai, bj, At, Bt) do { __builtin_amdgcn_s_setprio(1); _Pragma("unroll") for (int m = 0; m < 4; ++m) _Pragma("unroll") for (int n = 0; n < 2; ++n) _Pragma("unroll") for (int k = 0; k < 2; ++k) \
;         acc[ai][bj][m][n] = __builtin_amdgcn_mfma_f32_16x16x32_bf16(Bt[n][k], At[m][k], acc[ai][bj][m][n], 0, 0, 0); __builtin_amdgcn_s_setprio(0); } while (0)
; #define PG8_WAIT_V(n) asm volatile("s_waitcnt vmcnt(" #n ")" ::: "memory")
; #define PG8_WAIT_L(n) asm volatile("s_waitcnt lgkmcnt(" #n ")" ::: "memory")
; #define PG8_BAR __builtin_amdgcn_s_barrier()
; #define PG8_SCHED __builtin_amdgcn_sched_barrier(0)
; template <class Epi, bool ALIGN_EPI>
; __device__ __forceinline__ void gemm_phase(LAS unsigned char* lds, const Gemm g, const StaticOrder& S, const Epi& E) {
;     ...
;             const char* a1 = cA + (size_t)(t + 1) * kstep;
;             const char* a2 = last ? nA : cA + (size_t)(t + 2) * kstep; const char* b2 = last ? nB : cB + (size_t)(t + 2) * kstep;
;             const char* a3 = a2 + kstep; const char* b3 = b2 + kstep;
;             PG8_LDB(B0, 0, 0); PG8_LDB(B1, 0, 1); PG8_SCHED; PG8_LDA(At, 0, 0); PG8_STAGE(PG8_SA(1, 1), a1 + hA, voffA);
;             PG8_WAIT_V(8); PG8_WAIT_L(0); PG8_BAR; PG8_MMA(0, 0, At, B0); PG8_MMA(0, 1, At, B1); PG8_BAR; PG8_SCHED;
;             PG8_LDA(At, 0, 1); PG8_STAGE(PG8_SB(0, 0), b2, voffB); PG8_STAGE(PG8_SB(0, 1), b2 + hB, voffB); PG8_STAGE(PG8_SA(0, 0), a2, voffA);
;             PG8_WAIT_V(8); PG8_WAIT_L(0); PG8_BAR; PG8_MMA(1, 0, At, B0); PG8_MMA(1, 1, At, B1); PG8_BAR; PG8_SCHED;
.LBB0_1005:
	ds_read_b128 v[128:131], v175
	ds_read_b128 v[132:135], v175 offset:1024
	ds_read_b128 v[136:139], v175 offset:2048
	ds_read_b128 v[140:143], v175 offset:3072
	ds_read_b128 v[160:163], v176
	ds_read_b128 v[164:167], v176 offset:1024
	ds_read_b128 v[168:171], v176 offset:2048
	ds_read_b128 v[180:183], v176 offset:3072
	s_add_u32 s40, s36, 0xffe00080
	s_addc_u32 s41, s37, -1
	s_cmpk_eq_i32 s57, 0x7c
	s_cselect_b32 s43, s25, s41
	s_cselect_b32 s42, s31, s40
	s_cselect_b32 s41, s23, s56
	s_cselect_b32 s40, s54, s55
	v_lshl_add_u64 v[218:219], s[36:37], 0, v[152:153]
	s_add_i32 m0, s35, 0xc000
	ds_read_b128 v[184:187], v177
	ds_read_b128 v[188:191], v177 offset:1024
	ds_read_b128 v[194:197], v177 offset:2048
	ds_read_b128 v[198:201], v177 offset:3072
	ds_read_b128 v[202:205], v177 offset:4096
	ds_read_b128 v[206:209], v177 offset:5120
	ds_read_b128 v[210:213], v177 offset:6144
	ds_read_b128 v[214:217], v177 offset:7168
	global_load_lds_dwordx4 v[218:219], off
	v_lshl_add_u64 v[218:219], s[36:37], 0, v[154:155]
	s_add_i32 m0, s35, 0xe000
	s_nop 0
	global_load_lds_dwordx4 v[218:219], off
	s_waitcnt vmcnt(8)
	s_waitcnt lgkmcnt(0)
	s_barrier
	s_setprio 1
	s_waitcnt lgkmcnt(0)
	v_mfma_f32_16x16x32_bf16 v[124:127], v[128:131], v[184:187], v[124:127]
	v_mfma_f32_16x16x32_bf16 v[124:127], v[132:135], v[188:191], v[124:127]
	v_mfma_f32_16x16x32_bf16 v[120:123], v[136:139], v[184:187], v[120:123]
	v_mfma_f32_16x16x32_bf16 v[120:123], v[140:143], v[188:191], v[120:123]
	v_mfma_f32_16x16x32_bf16 v[112:115], v[128:131], v[194:197], v[112:115]
	v_mfma_f32_16x16x32_bf16 v[112:115], v[132:135], v[198:201], v[112:115]
	v_mfma_f32_16x16x32_bf16 v[104:107], v[136:139], v[194:197], v[104:107]
	v_mfma_f32_16x16x32_bf16 v[104:107], v[140:143], v[198:201], v[104:107]
	v_mfma_f32_16x16x32_bf16 v[92:95], v[128:131], v[202:205], v[92:95]
	v_mfma_f32_16x16x32_bf16 v[92:95], v[132:135], v[206:209], v[92:95]
	v_mfma_f32_16x16x32_bf16 v[88:91], v[136:139], v[202:205], v[88:91]
	v_mfma_f32_16x16x32_bf16 v[88:91], v[140:143], v[206:209], v[88:91]
	v_mfma_f32_16x16x32_bf16 v[76:79], v[128:131], v[210:213], v[76:79]
	v_mfma_f32_16x16x32_bf16 v[76:79], v[132:135], v[214:217], v[76:79]
	v_mfma_f32_16x16x32_bf16 v[72:75], v[136:139], v[210:213], v[72:75]
	v_mfma_f32_16x16x32_bf16 v[72:75], v[140:143], v[214:217], v[72:75]
	s_setprio 0
	s_setprio 1
	v_mfma_f32_16x16x32_bf16 v[116:119], v[160:163], v[184:187], v[116:119]
	v_mfma_f32_16x16x32_bf16 v[116:119], v[164:167], v[188:191], v[116:119]
	v_mfma_f32_16x16x32_bf16 v[108:111], v[168:171], v[184:187], v[108:111]
	v_mfma_f32_16x16x32_bf16 v[108:111], v[180:183], v[188:191], v[108:111]
	v_mfma_f32_16x16x32_bf16 v[100:103], v[160:163], v[194:197], v[100:103]
	v_mfma_f32_16x16x32_bf16 v[100:103], v[164:167], v[198:201], v[100:103]
	v_mfma_f32_16x16x32_bf16 v[96:99], v[168:171], v[194:197], v[96:99]
	v_mfma_f32_16x16x32_bf16 v[96:99], v[180:183], v[198:201], v[96:99]
	v_mfma_f32_16x16x32_bf16 v[84:87], v[160:163], v[202:205], v[84:87]
	v_mfma_f32_16x16x32_bf16 v[84:87], v[164:167], v[206:209], v[84:87]
	v_mfma_f32_16x16x32_bf16 v[80:83], v[168:171], v[202:205], v[80:83]
	v_mfma_f32_16x16x32_bf16 v[80:83], v[180:183], v[206:209], v[80:83]
	v_mfma_f32_16x16x32_bf16 v[68:71], v[160:163], v[210:213], v[68:71]
	v_mfma_f32_16x16x32_bf16 v[68:71], v[164:167], v[214:217], v[68:71]
	v_mfma_f32_16x16x32_bf16 v[64:67], v[168:171], v[210:213], v[64:67]
	v_mfma_f32_16x16x32_bf16 v[64:67], v[180:183], v[214:217], v[64:67]
	s_setprio 0
	s_barrier
	s_add_i32 s58, s51, s33
	v_lshl_add_u64 v[218:219], s[40:41], 0, v[146:147]
	s_mov_b32 m0, s58
	ds_read_b128 v[184:187], v177 offset:16384
	ds_read_b128 v[188:191], v177 offset:17408
	ds_read_b128 v[194:197], v177 offset:18432
	ds_read_b128 v[198:201], v177 offset:19456
	ds_read_b128 v[202:205], v177 offset:20480
	ds_read_b128 v[206:209], v177 offset:21504
	ds_read_b128 v[210:213], v177 offset:22528
	ds_read_b128 v[214:217], v177 offset:23552
	global_load_lds_dwordx4 v[218:219], off
	s_add_i32 m0, s58, 0x2000
	s_add_u32 s58, s40, 0x200000
	v_lshl_add_u64 v[220:221], s[40:41], 0, v[150:151]
	s_addc_u32 s59, s41, 0
	s_add_i32 s60, s52, s33
	global_load_lds_dwordx4 v[220:221], off
	s_waitcnt vmcnt(4)
	s_waitcnt lgkmcnt(0)
	s_barrier
	s_setprio 1
	s_waitcnt lgkmcnt(0)
	v_mfma_f32_16x16x32_bf16 v[60:63], v[128:131], v[184:187], v[60:63]
	v_mfma_f32_16x16x32_bf16 v[60:63], v[132:135], v[188:191], v[60:63]
	v_mfma_f32_16x16x32_bf16 v[56:59], v[136:139], v[184:187], v[56:59]
	v_mfma_f32_16x16x32_bf16 v[56:59], v[140:143], v[188:191], v[56:59]
	v_lshl_add_u64 v[222:223], s[58:59], 0, v[146:147]
	s_mov_b32 m0, s60
	v_lshl_add_u64 v[224:225], s[42:43], 0, v[148:149]
	global_load_lds_dwordx4 v[222:223], off
	v_mfma_f32_16x16x32_bf16 v[44:47], v[128:131], v[194:197], v[44:47]
	v_mfma_f32_16x16x32_bf16 v[44:47], v[132:135], v[198:201], v[44:47]
	v_mfma_f32_16x16x32_bf16 v[40:43], v[136:139], v[194:197], v[40:43]
	v_mfma_f32_16x16x32_bf16 v[40:43], v[140:143], v[198:201], v[40:43]
	v_mfma_f32_16x16x32_bf16 v[28:31], v[128:131], v[202:205], v[28:31]
	v_mfma_f32_16x16x32_bf16 v[28:31], v[132:135], v[206:209], v[28:31]
	v_lshl_add_u64 v[222:223], s[58:59], 0, v[150:151]
	s_add_i32 m0, s60, 0x2000
	s_nop 0
	global_load_lds_dwordx4 v[222:223], off
	v_mfma_f32_16x16x32_bf16 v[24:27], v[136:139], v[202:205], v[24:27]
	v_mfma_f32_16x16x32_bf16 v[24:27], v[140:143], v[206:209], v[24:27]
	v_mfma_f32_16x16x32_bf16 v[12:15], v[128:131], v[210:213], v[12:15]
	v_mfma_f32_16x16x32_bf16 v[12:15], v[132:135], v[214:217], v[12:15]
	v_mfma_f32_16x16x32_bf16 v[8:11], v[136:139], v[210:213], v[8:11]
	v_mfma_f32_16x16x32_bf16 v[8:11], v[140:143], v[214:217], v[8:11]
	s_setprio 0
	s_setprio 1
	v_mfma_f32_16x16x32_bf16 v[52:55], v[160:163], v[184:187], v[52:55]
	v_mfma_f32_16x16x32_bf16 v[52:55], v[164:167], v[188:191], v[52:55]
	v_lshl_add_u64 v[222:223], s[42:43], 0, v[144:145]
	s_mov_b32 m0, s35
	s_nop 0
	global_load_lds_dwordx4 v[222:223], off
	v_mfma_f32_16x16x32_bf16 v[48:51], v[168:171], v[184:187], v[48:51]
	v_mfma_f32_16x16x32_bf16 v[48:51], v[180:183], v[188:191], v[48:51]
	v_mfma_f32_16x16x32_bf16 v[36:39], v[160:163], v[194:197], v[36:39]
	v_mfma_f32_16x16x32_bf16 v[36:39], v[164:167], v[198:201], v[36:39]
	v_mfma_f32_16x16x32_bf16 v[32:35], v[168:171], v[194:197], v[32:35]
	v_mfma_f32_16x16x32_bf16 v[32:35], v[180:183], v[198:201], v[32:35]
	s_mov_b32 m0, s38
	s_nop 0
	global_load_lds_dwordx4 v[224:225], off
	v_mfma_f32_16x16x32_bf16 v[20:23], v[160:163], v[202:205], v[20:23]
	v_mfma_f32_16x16x32_bf16 v[20:23], v[164:167], v[206:209], v[20:23]
	v_mfma_f32_16x16x32_bf16 v[16:19], v[168:171], v[202:205], v[16:19]
	v_mfma_f32_16x16x32_bf16 v[16:19], v[180:183], v[206:209], v[16:19]
	v_mfma_f32_16x16x32_bf16 v[4:7], v[160:163], v[210:213], v[4:7]
	v_mfma_f32_16x16x32_bf16 v[4:7], v[164:167], v[214:217], v[4:7]
	v_mfma_f32_16x16x32_bf16 v[0:3], v[168:171], v[210:213], v[0:3]
	v_mfma_f32_16x16x32_bf16 v[0:3], v[180:183], v[214:217], v[0:3]
	s_setprio 0
	s_barrier
; #define PG8_STAGE(bufoff, gbase, voff) do { _Pragma("unroll") for (int _i = 0; _i < 2; ++_i) \
;         __builtin_amdgcn_global_load_lds((const unsigned*)((const char*)(gbase) + (voff)[_i]), (LAS unsigned*)(lds + (bufoff) + ldsw + _i * 8192), 16, 0, 0); } while (0)
; #define PG8_LDA(dst, b, h) do { _Pragma("unroll") for (int m = 0; m < 4; ++m) _Pragma("unroll") for (int k = 0; k < 2; ++k) dst[m][k] = *(const LAS bf16x8*)(lds + PG8_SA(b, h) + aoff + m * 2048 + k * 1024); } while (0)
; #define PG8_LDB(dst, b, h) do { _Pragma("unroll") for (int n = 0; n < 2; ++n) _Pragma("unroll") for (int k = 0; k < 2; ++k) dst[n][k] = *(const LAS bf16x8*)(lds + PG8_SB(b, h) + boff + n * 2048 + k * 1024); } while (0)
; #define PG8_MMA(ai, bj, At, Bt) do { __builtin_amdgcn_s_setprio(1); _Pragma("unroll") for (int m = 0; m < 4; ++m) _Pragma("unroll") for (int n = 0; n < 2; ++n) _Pragma("unroll") for (int k = 0; k < 2; ++k) \
;         acc[ai][bj][m][n] = __builtin_amdgcn_mfma_f32_16x16x32_bf16(Bt[n][k], At[m][k], acc[ai][bj][m][n], 0, 0, 0); __builtin_amdgcn_s_setprio(0); } while (0)
; #define PG8_WAIT_V(n) asm volatile("s_waitcnt vmcnt(" #n ")" ::: "memory")
; #define PG8_WAIT_L(n) asm volatile("s_waitcnt lgkmcnt(" #n ")" ::: "memory")
; #define PG8_BAR __builtin_amdgcn_s_barrier()
; #define PG8_SCHED __builtin_amdgcn_sched_barrier(0)
; template <class Epi, bool ALIGN_EPI>
; __device__ __forceinline__ void gemm_phase(LAS unsigned char* lds, const Gemm g, const StaticOrder& S, const Epi& E) {
;     ...
;             PG8_LDB(B0, 1, 0); PG8_LDB(B1, 1, 1); PG8_SCHED; PG8_LDA(At, 1, 0); PG8_STAGE(PG8_SA(0, 1), a2 + hA, voffA);
;             PG8_WAIT_V(8); PG8_WAIT_L(0); PG8_BAR; PG8_MMA(0, 0, At, B0); PG8_MMA(0, 1, At, B1); PG8_BAR; PG8_SCHED;
	s_add_i32 s58, 0, 0x18000
	s_add_i32 s59, 0, 0x1c000
	v_add_u32_e32 v140, s58, v173
	v_add_u32_e32 v179, s59, v173
	ds_read_b128 v[128:131], v140
	ds_read_b128 v[132:135], v140 offset:1024
	ds_read_b128 v[136:139], v140 offset:2048
	ds_read_b128 v[140:143], v140 offset:3072
	ds_read_b128 v[160:163], v179
	ds_read_b128 v[164:167], v179 offset:1024
	ds_read_b128 v[168:171], v179 offset:2048
	ds_read_b128 v[180:183], v179 offset:3072
	s_add_u32 s42, s42, 0x200000
	s_addc_u32 s43, s43, 0
	s_mov_b32 m0, s39
	v_lshl_add_u64 v[226:227], s[42:43], 0, v[144:145]
	ds_read_b128 v[184:187], v177 offset:32768
	ds_read_b128 v[188:191], v177 offset:33792
	ds_read_b128 v[194:197], v177 offset:34816
	ds_read_b128 v[198:201], v177 offset:35840
	ds_read_b128 v[202:205], v177 offset:36864
	ds_read_b128 v[206:209], v177 offset:37888
	ds_read_b128 v[210:213], v177 offset:38912
	ds_read_b128 v[214:217], v177 offset:39936
	global_load_lds_dwordx4 v[226:227], off
	v_lshl_add_u64 v[226:227], s[42:43], 0, v[148:149]
	s_mov_b32 m0, s44
	s_nop 0
	global_load_lds_dwordx4 v[226:227], off
	s_waitcnt vmcnt(8)
	s_waitcnt lgkmcnt(0)
	s_barrier
	s_setprio 1
	s_waitcnt lgkmcnt(0)
	v_mfma_f32_16x16x32_bf16 v[124:127], v[128:131], v[184:187], v[124:127]
	v_mfma_f32_16x16x32_bf16 v[124:127], v[132:135], v[188:191], v[124:127]
	v_mfma_f32_16x16x32_bf16 v[120:123], v[136:139], v[184:187], v[120:123]
	v_mfma_f32_16x16x32_bf16 v[120:123], v[140:143], v[188:191], v[120:123]
	v_mfma_f32_16x16x32_bf16 v[112:115], v[128:131], v[194:197], v[112:115]
	v_mfma_f32_16x16x32_bf16 v[112:115], v[132:135], v[198:201], v[112:115]
	v_mfma_f32_16x16x32_bf16 v[104:107], v[136:139], v[194:197], v[104:107]
	v_mfma_f32_16x16x32_bf16 v[104:107], v[140:143], v[198:201], v[104:107]
	v_mfma_f32_16x16x32_bf16 v[92:95], v[128:131], v[202:205], v[92:95]
	v_mfma_f32_16x16x32_bf16 v[92:95], v[132:135], v[206:209], v[92:95]
	v_mfma_f32_16x16x32_bf16 v[88:91], v[136:139], v[202:205], v[88:91]
	v_mfma_f32_16x16x32_bf16 v[88:91], v[140:143], v[206:209], v[88:91]
	v_mfma_f32_16x16x32_bf16 v[76:79], v[128:131], v[210:213], v[76:79]
	v_mfma_f32_16x16x32_bf16 v[76:79], v[132:135], v[214:217], v[76:79]
	v_mfma_f32_16x16x32_bf16 v[72:75], v[136:139], v[210:213], v[72:75]
	v_mfma_f32_16x16x32_bf16 v[72:75], v[140:143], v[214:217], v[72:75]
	s_setprio 0
	s_setprio 1
	v_mfma_f32_16x16x32_bf16 v[116:119], v[160:163], v[184:187], v[116:119]
	v_mfma_f32_16x16x32_bf16 v[116:119], v[164:167], v[188:191], v[116:119]
	v_mfma_f32_16x16x32_bf16 v[108:111], v[168:171], v[184:187], v[108:111]
	v_mfma_f32_16x16x32_bf16 v[108:111], v[180:183], v[188:191], v[108:111]
	v_mfma_f32_16x16x32_bf16 v[100:103], v[160:163], v[194:197], v[100:103]
	v_mfma_f32_16x16x32_bf16 v[100:103], v[164:167], v[198:201], v[100:103]
	v_mfma_f32_16x16x32_bf16 v[96:99], v[168:171], v[194:197], v[96:99]
	v_mfma_f32_16x16x32_bf16 v[96:99], v[180:183], v[198:201], v[96:99]
	v_mfma_f32_16x16x32_bf16 v[84:87], v[160:163], v[202:205], v[84:87]
	v_mfma_f32_16x16x32_bf16 v[84:87], v[164:167], v[206:209], v[84:87]
	v_mfma_f32_16x16x32_bf16 v[80:83], v[168:171], v[202:205], v[80:83]
	v_mfma_f32_16x16x32_bf16 v[80:83], v[180:183], v[206:209], v[80:83]
	v_mfma_f32_16x16x32_bf16 v[68:71], v[160:163], v[210:213], v[68:71]
	v_mfma_f32_16x16x32_bf16 v[68:71], v[164:167], v[214:217], v[68:71]
	v_mfma_f32_16x16x32_bf16 v[64:67], v[168:171], v[210:213], v[64:67]
	v_mfma_f32_16x16x32_bf16 v[64:67], v[180:183], v[214:217], v[64:67]
	s_setprio 0
	s_barrier
; #define PG8_STAGE(bufoff, gbase, voff) do { _Pragma("unroll") for (int _i = 0; _i < 2; ++_i) \
;         __builtin_amdgcn_global_load_lds((const unsigned*)((const char*)(gbase) + (voff)[_i]), (LAS unsigned*)(lds + (bufoff) + ldsw + _i * 8192), 16, 0, 0); } while (0)
; #define PG8_LDA(dst, b, h) do { _Pragma("unroll") for (int m = 0; m < 4; ++m) _Pragma("unroll") for (int k = 0; k < 2; ++k) dst[m][k] = *(const LAS bf16x8*)(lds + PG8_SA(b, h) + aoff + m * 2048 + k * 1024); } while (0)
; #define PG8_MMA(ai, bj, At, Bt) do { __builtin_amdgcn_s_setprio(1); _Pragma("unroll") for (int m = 0; m < 4; ++m) _Pragma("unroll") for (int n = 0; n < 2; ++n) _Pragma("unroll") for (int k = 0; k < 2; ++k) \
;         acc[ai][bj][m][n] = __builtin_amdgcn_mfma_f32_16x16x32_bf16(Bt[n][k], At[m][k], acc[ai][bj][m][n], 0, 0, 0); __builtin_amdgcn_s_setprio(0); } while (0)
; #define PG8_WAIT_V(n) asm volatile("s_waitcnt vmcnt(" #n ")" ::: "memory")
; #define PG8_WAIT_L(n) asm volatile("s_waitcnt lgkmcnt(" #n ")" ::: "memory")
; #define PG8_BAR __builtin_amdgcn_s_barrier()
; #define PG8_SCHED __builtin_amdgcn_sched_barrier(0)
; template <class Epi, bool ALIGN_EPI>
; __device__ __forceinline__ void gemm_phase(LAS unsigned char* lds, const Gemm g, const StaticOrder& S, const Epi& E) {
;     ...
;             PG8_LDA(At, 1, 1); PG8_STAGE(PG8_SB(1, 0), b3, voffB); PG8_STAGE(PG8_SB(1, 1), b3 + hB, voffB); PG8_STAGE(PG8_SA(1, 0), a3, voffA);
;             PG8_WAIT_V(8); PG8_WAIT_L(0); PG8_BAR; PG8_MMA(1, 0, At, B0); PG8_MMA(1, 1, At, B1); PG8_BAR; PG8_SCHED;
;         }
	s_add_i32 s42, s58, s33
	v_lshl_add_u64 v[218:219], v[218:219], 0, s[16:17]
	s_mov_b32 m0, s42
	ds_read_b128 v[184:187], v177 offset:49152
	ds_read_b128 v[188:191], v177 offset:50176
	ds_read_b128 v[194:197], v177 offset:51200
	ds_read_b128 v[198:201], v177 offset:52224
	ds_read_b128 v[202:205], v177 offset:53248
	ds_read_b128 v[206:209], v177 offset:54272
	ds_read_b128 v[210:213], v177 offset:55296
	ds_read_b128 v[214:217], v177 offset:56320
	global_load_lds_dwordx4 v[218:219], off
	s_add_i32 m0, s42, 0x2000
	s_add_u32 s40, s40, 0x200080
	v_lshl_add_u64 v[218:219], v[220:221], 0, s[16:17]
	s_addc_u32 s41, s41, 0
	s_add_i32 s42, s59, s33
	global_load_lds_dwordx4 v[218:219], off
	s_waitcnt vmcnt(4)
	s_waitcnt lgkmcnt(0)
	s_barrier
	s_setprio 1
	s_waitcnt lgkmcnt(0)
	v_mfma_f32_16x16x32_bf16 v[60:63], v[128:131], v[184:187], v[60:63]
	v_mfma_f32_16x16x32_bf16 v[60:63], v[132:135], v[188:191], v[60:63]
	v_mfma_f32_16x16x32_bf16 v[56:59], v[136:139], v[184:187], v[56:59]
	v_mfma_f32_16x16x32_bf16 v[56:59], v[140:143], v[188:191], v[56:59]
	v_lshl_add_u64 v[218:219], s[40:41], 0, v[146:147]
	s_mov_b32 m0, s42
	s_nop 0
	global_load_lds_dwordx4 v[218:219], off
	v_mfma_f32_16x16x32_bf16 v[44:47], v[128:131], v[194:197], v[44:47]
	v_mfma_f32_16x16x32_bf16 v[44:47], v[132:135], v[198:201], v[44:47]
	v_mfma_f32_16x16x32_bf16 v[40:43], v[136:139], v[194:197], v[40:43]
	v_mfma_f32_16x16x32_bf16 v[40:43], v[140:143], v[198:201], v[40:43]
	v_mfma_f32_16x16x32_bf16 v[28:31], v[128:131], v[202:205], v[28:31]
	v_mfma_f32_16x16x32_bf16 v[28:31], v[132:135], v[206:209], v[28:31]
	v_lshl_add_u64 v[218:219], s[40:41], 0, v[150:151]
	s_add_i32 m0, s42, 0x2000
	s_nop 0
	global_load_lds_dwordx4 v[218:219], off
	v_mfma_f32_16x16x32_bf16 v[24:27], v[136:139], v[202:205], v[24:27]
	v_mfma_f32_16x16x32_bf16 v[24:27], v[140:143], v[206:209], v[24:27]
	v_mfma_f32_16x16x32_bf16 v[12:15], v[128:131], v[210:213], v[12:15]
	v_mfma_f32_16x16x32_bf16 v[12:15], v[132:135], v[214:217], v[12:15]
	v_mfma_f32_16x16x32_bf16 v[8:11], v[136:139], v[210:213], v[8:11]
	v_mfma_f32_16x16x32_bf16 v[8:11], v[140:143], v[214:217], v[8:11]
	s_setprio 0
	s_setprio 1
	v_mfma_f32_16x16x32_bf16 v[52:55], v[160:163], v[184:187], v[52:55]
	v_mfma_f32_16x16x32_bf16 v[52:55], v[164:167], v[188:191], v[52:55]
	v_lshl_add_u64 v[218:219], v[222:223], 0, s[16:17]
	s_mov_b32 m0, s48
	s_nop 0
	global_load_lds_dwordx4 v[218:219], off
	v_mfma_f32_16x16x32_bf16 v[48:51], v[168:171], v[184:187], v[48:51]
	v_mfma_f32_16x16x32_bf16 v[48:51], v[180:183], v[188:191], v[48:51]
	v_mfma_f32_16x16x32_bf16 v[36:39], v[160:163], v[194:197], v[36:39]
	v_mfma_f32_16x16x32_bf16 v[36:39], v[164:167], v[198:201], v[36:39]
	v_mfma_f32_16x16x32_bf16 v[32:35], v[168:171], v[194:197], v[32:35]
	v_mfma_f32_16x16x32_bf16 v[32:35], v[180:183], v[198:201], v[32:35]
	v_lshl_add_u64 v[218:219], v[224:225], 0, s[16:17]
	s_mov_b32 m0, s49
	s_nop 0
	global_load_lds_dwordx4 v[218:219], off
	v_mfma_f32_16x16x32_bf16 v[20:23], v[160:163], v[202:205], v[20:23]
	v_mfma_f32_16x16x32_bf16 v[20:23], v[164:167], v[206:209], v[20:23]
	v_mfma_f32_16x16x32_bf16 v[16:19], v[168:171], v[202:205], v[16:19]
	v_mfma_f32_16x16x32_bf16 v[16:19], v[180:183], v[206:209], v[16:19]
	v_mfma_f32_16x16x32_bf16 v[4:7], v[160:163], v[210:213], v[4:7]
	v_mfma_f32_16x16x32_bf16 v[4:7], v[164:167], v[214:217], v[4:7]
	v_mfma_f32_16x16x32_bf16 v[0:3], v[168:171], v[210:213], v[0:3]
	v_mfma_f32_16x16x32_bf16 v[0:3], v[180:183], v[214:217], v[0:3]
	s_setprio 0
	s_barrier
	s_add_i32 s57, s57, 2
	s_add_u32 s36, s36, 0x100
	s_addc_u32 s37, s37, 0
	s_add_u32 s55, s55, 0x100
	s_addc_u32 s56, s56, 0
	s_cmpk_gt_u32 s57, 0x7d
	s_cbranch_scc0 .LBB0_1005
	s_and_b64 vcc, exec, s[18:19]
	s_cbranch_vccz .LBB0_1008
	s_barrier

; #define PG8_STAGE(bufoff, gbase, voff) do { _Pragma("unroll") for (int _i = 0; _i < 2; ++_i) \
;         __builtin_amdgcn_global_load_lds((const unsigned*)((const char*)(gbase) + (voff)[_i]), (LAS unsigned*)(lds + (bufoff) + ldsw + _i * 8192), 16, 0, 0); } while (0)
; #define PG8_LDA(dst, b, h) do { _Pragma("unroll") for (int m = 0; m < 4; ++m) _Pragma("unroll") for (int k = 0; k < 2; ++k) dst[m][k] = *(const LAS bf16x8*)(lds + PG8_SA(b, h) + aoff + m * 2048 + k * 1024); } while (0)
; #define PG8_LDB(dst, b, h) do { _Pragma("unroll") for (int n = 0; n < 2; ++n) _Pragma("unroll") for (int k = 0; k < 2; ++k) dst[n][k] = *(const LAS bf16x8*)(lds + PG8_SB(b, h) + boff + n * 2048 + k * 1024); } while (0)
; #define PG8_MMA(ai, bj, At, Bt) do { __builtin_amdgcn_s_setprio(1); _Pragma("unroll") for (int m = 0; m < 4; ++m) _Pragma("unroll") for (int n = 0; n < 2; ++n) _Pragma("unroll") for (int k = 0; k < 2; ++k) \
;         acc[ai][bj][m][n] = __builtin_amdgcn_mfma_f32_16x16x32_bf16(Bt[n][k], At[m][k], acc[ai][bj][m][n], 0, 0, 0); __builtin_amdgcn_s_setprio(0); } while (0)
; #define PG8_WAIT_V(n) asm volatile("s_waitcnt vmcnt(" #n ")" ::: "memory")
; #define PG8_WAIT_L(n) asm volatile("s_waitcnt lgkmcnt(" #n ")" ::: "memory")
; #define PG8_BAR __builtin_amdgcn_s_barrier()
; #define PG8_SCHED __builtin_amdgcn_sched_barrier(0)
; template <class Epi, bool ALIGN_EPI>
; __device__ __forceinline__ void gemm_phase(LAS unsigned char* lds, const Gemm g, const StaticOrder& S, const Epi& E) {
;     ...
;             const char* a1 = cA + (size_t)(t + 1) * kstep;
;             const char* a2 = last ? nA : cA + (size_t)(t + 2) * kstep; const char* b2 = last ? nB : cB + (size_t)(t + 2) * kstep;
;             const char* a3 = a2 + kstep; const char* b3 = b2 + kstep;
;             PG8_LDB(B0, 0, 0); PG8_LDB(B1, 0, 1); PG8_SCHED; PG8_LDA(At, 0, 0); PG8_STAGE(PG8_SA(1, 1), a1 + hA, voffA);
;             PG8_WAIT_V(8); PG8_WAIT_L(0); PG8_BAR; PG8_MMA(0, 0, At, B0); PG8_MMA(0, 1, At, B1); PG8_BAR; PG8_SCHED;
;             PG8_LDA(At, 0, 1); PG8_STAGE(PG8_SB(0, 0), b2, voffB); PG8_STAGE(PG8_SB(0, 1), b2 + hB, voffB); PG8_STAGE(PG8_SA(0, 0), a2, voffA);
;             PG8_WAIT_V(8); PG8_WAIT_L(0); PG8_BAR; PG8_MMA(1, 0, At, B0); PG8_MMA(1, 1, At, B1); PG8_BAR; PG8_SCHED;
.LBB0_1094:
	ds_read_b128 v[146:149], v153
	ds_read_b128 v[174:177], v153 offset:1024
	ds_read_b128 v[178:181], v153 offset:2048
	ds_read_b128 v[182:185], v153 offset:3072
	ds_read_b128 v[186:189], v154
	ds_read_b128 v[194:197], v154 offset:1024
	ds_read_b128 v[198:201], v154 offset:2048
	ds_read_b128 v[202:205], v154 offset:3072
	s_add_u32 s36, s4, 0xfff80080
	s_addc_u32 s37, s5, -1
	s_cmp_eq_u32 s38, 28
	s_cselect_b32 s45, s0, s37
	s_cselect_b32 s44, s1, s36
	s_cselect_b32 s37, s2, s29
	s_cselect_b32 s36, s3, s27
	v_lshl_add_u64 v[190:191], s[4:5], 0, v[136:137]
	s_add_i32 m0, s41, 0xc000
	ds_read_b128 v[206:209], v155
	ds_read_b128 v[210:213], v155 offset:1024
	ds_read_b128 v[214:217], v155 offset:2048
	ds_read_b128 v[218:221], v155 offset:3072
	ds_read_b128 v[222:225], v155 offset:4096
	ds_read_b128 v[226:229], v155 offset:5120
	ds_read_b128 v[230:233], v155 offset:6144
	ds_read_b128 v[234:237], v155 offset:7168
	global_load_lds_dwordx4 v[190:191], off
	v_lshl_add_u64 v[190:191], s[4:5], 0, v[138:139]
	s_add_i32 m0, s41, 0xe000
	s_nop 0
	global_load_lds_dwordx4 v[190:191], off
	s_waitcnt vmcnt(8)
	s_waitcnt lgkmcnt(0)
	s_barrier
	s_setprio 1
	s_waitcnt lgkmcnt(0)
	v_mfma_f32_16x16x32_bf16 v[124:127], v[146:149], v[206:209], v[124:127]
	v_mfma_f32_16x16x32_bf16 v[124:127], v[174:177], v[210:213], v[124:127]
	v_mfma_f32_16x16x32_bf16 v[120:123], v[178:181], v[206:209], v[120:123]
	v_mfma_f32_16x16x32_bf16 v[120:123], v[182:185], v[210:213], v[120:123]
	v_mfma_f32_16x16x32_bf16 v[108:111], v[146:149], v[214:217], v[108:111]
	v_mfma_f32_16x16x32_bf16 v[108:111], v[174:177], v[218:221], v[108:111]
	v_mfma_f32_16x16x32_bf16 v[104:107], v[178:181], v[214:217], v[104:107]
	v_mfma_f32_16x16x32_bf16 v[104:107], v[182:185], v[218:221], v[104:107]
	v_mfma_f32_16x16x32_bf16 v[92:95], v[146:149], v[222:225], v[92:95]
	v_mfma_f32_16x16x32_bf16 v[92:95], v[174:177], v[226:229], v[92:95]
	v_mfma_f32_16x16x32_bf16 v[88:91], v[178:181], v[222:225], v[88:91]
	v_mfma_f32_16x16x32_bf16 v[88:91], v[182:185], v[226:229], v[88:91]
	v_mfma_f32_16x16x32_bf16 v[76:79], v[146:149], v[230:233], v[76:79]
	v_mfma_f32_16x16x32_bf16 v[76:79], v[174:177], v[234:237], v[76:79]
	v_mfma_f32_16x16x32_bf16 v[72:75], v[178:181], v[230:233], v[72:75]
	v_mfma_f32_16x16x32_bf16 v[72:75], v[182:185], v[234:237], v[72:75]
	s_setprio 0
	s_setprio 1
	v_mfma_f32_16x16x32_bf16 v[116:119], v[186:189], v[206:209], v[116:119]
	v_mfma_f32_16x16x32_bf16 v[116:119], v[194:197], v[210:213], v[116:119]
	v_mfma_f32_16x16x32_bf16 v[112:115], v[198:201], v[206:209], v[112:115]
	v_mfma_f32_16x16x32_bf16 v[112:115], v[202:205], v[210:213], v[112:115]
	v_mfma_f32_16x16x32_bf16 v[100:103], v[186:189], v[214:217], v[100:103]
	v_mfma_f32_16x16x32_bf16 v[100:103], v[194:197], v[218:221], v[100:103]
	v_mfma_f32_16x16x32_bf16 v[96:99], v[198:201], v[214:217], v[96:99]
	v_mfma_f32_16x16x32_bf16 v[96:99], v[202:205], v[218:221], v[96:99]
	v_mfma_f32_16x16x32_bf16 v[84:87], v[186:189], v[222:225], v[84:87]
	v_mfma_f32_16x16x32_bf16 v[84:87], v[194:197], v[226:229], v[84:87]
	v_mfma_f32_16x16x32_bf16 v[80:83], v[198:201], v[222:225], v[80:83]
	v_mfma_f32_16x16x32_bf16 v[80:83], v[202:205], v[226:229], v[80:83]
	v_mfma_f32_16x16x32_bf16 v[68:71], v[186:189], v[230:233], v[68:71]
	v_mfma_f32_16x16x32_bf16 v[68:71], v[194:197], v[234:237], v[68:71]
	v_mfma_f32_16x16x32_bf16 v[64:67], v[198:201], v[230:233], v[64:67]
	v_mfma_f32_16x16x32_bf16 v[64:67], v[202:205], v[234:237], v[64:67]
	s_setprio 0
	s_barrier
	s_add_i32 s39, s61, s51
	v_lshl_add_u64 v[190:191], s[36:37], 0, v[130:131]
	s_mov_b32 m0, s39
	ds_read_b128 v[206:209], v155 offset:16384
	ds_read_b128 v[210:213], v155 offset:17408
	ds_read_b128 v[214:217], v155 offset:18432
	ds_read_b128 v[218:221], v155 offset:19456
	ds_read_b128 v[222:225], v155 offset:20480
	ds_read_b128 v[226:229], v155 offset:21504
	ds_read_b128 v[230:233], v155 offset:22528
	ds_read_b128 v[234:237], v155 offset:23552
	global_load_lds_dwordx4 v[190:191], off
	s_add_i32 m0, s39, 0x2000
	s_add_u32 s46, s36, 0x80000
	v_lshl_add_u64 v[238:239], s[36:37], 0, v[134:135]
	s_addc_u32 s47, s37, 0
	s_add_i32 s39, s62, s51
	global_load_lds_dwordx4 v[238:239], off
	s_waitcnt vmcnt(4)
	s_waitcnt lgkmcnt(0)
	s_barrier
	s_setprio 1
	s_waitcnt lgkmcnt(0)
	v_mfma_f32_16x16x32_bf16 v[60:63], v[146:149], v[206:209], v[60:63]
	v_mfma_f32_16x16x32_bf16 v[60:63], v[174:177], v[210:213], v[60:63]
	v_mfma_f32_16x16x32_bf16 v[56:59], v[178:181], v[206:209], v[56:59]
	v_mfma_f32_16x16x32_bf16 v[56:59], v[182:185], v[210:213], v[56:59]
	v_lshl_add_u64 v[240:241], s[46:47], 0, v[130:131]
	s_mov_b32 m0, s39
	v_lshl_add_u64 v[242:243], s[44:45], 0, v[132:133]
	global_load_lds_dwordx4 v[240:241], off
	v_mfma_f32_16x16x32_bf16 v[44:47], v[146:149], v[214:217], v[44:47]
	v_mfma_f32_16x16x32_bf16 v[44:47], v[174:177], v[218:221], v[44:47]
	v_mfma_f32_16x16x32_bf16 v[40:43], v[178:181], v[214:217], v[40:43]
	v_mfma_f32_16x16x32_bf16 v[40:43], v[182:185], v[218:221], v[40:43]
	v_mfma_f32_16x16x32_bf16 v[28:31], v[146:149], v[222:225], v[28:31]
	v_mfma_f32_16x16x32_bf16 v[28:31], v[174:177], v[226:229], v[28:31]
	v_lshl_add_u64 v[240:241], s[46:47], 0, v[134:135]
	s_add_i32 m0, s39, 0x2000
	s_nop 0
	global_load_lds_dwordx4 v[240:241], off
	v_mfma_f32_16x16x32_bf16 v[24:27], v[178:181], v[222:225], v[24:27]
	v_mfma_f32_16x16x32_bf16 v[24:27], v[182:185], v[226:229], v[24:27]
	v_mfma_f32_16x16x32_bf16 v[12:15], v[146:149], v[230:233], v[12:15]
	v_mfma_f32_16x16x32_bf16 v[12:15], v[174:177], v[234:237], v[12:15]
	v_mfma_f32_16x16x32_bf16 v[8:11], v[178:181], v[230:233], v[8:11]
	v_mfma_f32_16x16x32_bf16 v[8:11], v[182:185], v[234:237], v[8:11]
	s_setprio 0
	s_setprio 1
	v_mfma_f32_16x16x32_bf16 v[52:55], v[186:189], v[206:209], v[52:55]
	v_mfma_f32_16x16x32_bf16 v[52:55], v[194:197], v[210:213], v[52:55]
	v_lshl_add_u64 v[240:241], s[44:45], 0, v[128:129]
	s_mov_b32 m0, s41
	s_nop 0
	global_load_lds_dwordx4 v[240:241], off
	v_mfma_f32_16x16x32_bf16 v[48:51], v[198:201], v[206:209], v[48:51]
	v_mfma_f32_16x16x32_bf16 v[48:51], v[202:205], v[210:213], v[48:51]
	v_mfma_f32_16x16x32_bf16 v[36:39], v[186:189], v[214:217], v[36:39]
	v_mfma_f32_16x16x32_bf16 v[36:39], v[194:197], v[218:221], v[36:39]
	v_mfma_f32_16x16x32_bf16 v[32:35], v[198:201], v[214:217], v[32:35]
	v_mfma_f32_16x16x32_bf16 v[32:35], v[202:205], v[218:221], v[32:35]
	s_mov_b32 m0, s43
	s_nop 0
	global_load_lds_dwordx4 v[242:243], off
	v_mfma_f32_16x16x32_bf16 v[20:23], v[186:189], v[222:225], v[20:23]
	v_mfma_f32_16x16x32_bf16 v[20:23], v[194:197], v[226:229], v[20:23]
	v_mfma_f32_16x16x32_bf16 v[16:19], v[198:201], v[222:225], v[16:19]
	v_mfma_f32_16x16x32_bf16 v[16:19], v[202:205], v[226:229], v[16:19]
	v_mfma_f32_16x16x32_bf16 v[4:7], v[186:189], v[230:233], v[4:7]
	v_mfma_f32_16x16x32_bf16 v[4:7], v[194:197], v[234:237], v[4:7]
	v_mfma_f32_16x16x32_bf16 v[0:3], v[198:201], v[230:233], v[0:3]
	v_mfma_f32_16x16x32_bf16 v[0:3], v[202:205], v[234:237], v[0:3]
	s_setprio 0
	s_barrier
; #define PG8_STAGE(bufoff, gbase, voff) do { _Pragma("unroll") for (int _i = 0; _i < 2; ++_i) \
;         __builtin_amdgcn_global_load_lds((const unsigned*)((const char*)(gbase) + (voff)[_i]), (LAS unsigned*)(lds + (bufoff) + ldsw + _i * 8192), 16, 0, 0); } while (0)
; #define PG8_LDA(dst, b, h) do { _Pragma("unroll") for (int m = 0; m < 4; ++m) _Pragma("unroll") for (int k = 0; k < 2; ++k) dst[m][k] = *(const LAS bf16x8*)(lds + PG8_SA(b, h) + aoff + m * 2048 + k * 1024); } while (0)
; #define PG8_LDB(dst, b, h) do { _Pragma("unroll") for (int n = 0; n < 2; ++n) _Pragma("unroll") for (int k = 0; k < 2; ++k) dst[n][k] = *(const LAS bf16x8*)(lds + PG8_SB(b, h) + boff + n * 2048 + k * 1024); } while (0)
; #define PG8_MMA(ai, bj, At, Bt) do { __builtin_amdgcn_s_setprio(1); _Pragma("unroll") for (int m = 0; m < 4; ++m) _Pragma("unroll") for (int n = 0; n < 2; ++n) _Pragma("unroll") for (int k = 0; k < 2; ++k) \
;         acc[ai][bj][m][n] = __builtin_amdgcn_mfma_f32_16x16x32_bf16(Bt[n][k], At[m][k], acc[ai][bj][m][n], 0, 0, 0); __builtin_amdgcn_s_setprio(0); } while (0)
; #define PG8_WAIT_V(n) asm volatile("s_waitcnt vmcnt(" #n ")" ::: "memory")
; #define PG8_WAIT_L(n) asm volatile("s_waitcnt lgkmcnt(" #n ")" ::: "memory")
; #define PG8_BAR __builtin_amdgcn_s_barrier()
; #define PG8_SCHED __builtin_amdgcn_sched_barrier(0)
; template <class Epi, bool ALIGN_EPI>
; __device__ __forceinline__ void gemm_phase(LAS unsigned char* lds, const Gemm g, const StaticOrder& S, const Epi& E) {
;     ...
;             PG8_LDB(B0, 1, 0); PG8_LDB(B1, 1, 1); PG8_SCHED; PG8_LDA(At, 1, 0); PG8_STAGE(PG8_SA(0, 1), a2 + hA, voffA);
;             PG8_WAIT_V(8); PG8_WAIT_L(0); PG8_BAR; PG8_MMA(0, 0, At, B0); PG8_MMA(0, 1, At, B1); PG8_BAR; PG8_SCHED;
	s_add_i32 s39, 0, 0x18000
	v_add_u32_e32 v145, s39, v151
	s_add_i32 s46, 0, 0x1c000
	ds_read_b128 v[146:149], v145
	ds_read_b128 v[174:177], v145 offset:1024
	ds_read_b128 v[178:181], v145 offset:2048
	ds_read_b128 v[182:185], v145 offset:3072
	v_add_u32_e32 v145, s46, v151
	ds_read_b128 v[186:189], v145
	ds_read_b128 v[194:197], v145 offset:1024
	ds_read_b128 v[198:201], v145 offset:2048
	ds_read_b128 v[202:205], v145 offset:3072
	s_add_u32 s44, s44, 0x80000
	s_addc_u32 s45, s45, 0
	s_mov_b32 m0, s52
	v_lshl_add_u64 v[244:245], s[44:45], 0, v[128:129]
	ds_read_b128 v[206:209], v155 offset:32768
	ds_read_b128 v[210:213], v155 offset:33792
	ds_read_b128 v[214:217], v155 offset:34816
	ds_read_b128 v[218:221], v155 offset:35840
	ds_read_b128 v[222:225], v155 offset:36864
	ds_read_b128 v[226:229], v155 offset:37888
	ds_read_b128 v[230:233], v155 offset:38912
	ds_read_b128 v[234:237], v155 offset:39936
	global_load_lds_dwordx4 v[244:245], off
	v_lshl_add_u64 v[244:245], s[44:45], 0, v[132:133]
	s_mov_b32 m0, s53
	s_nop 0
	global_load_lds_dwordx4 v[244:245], off
	s_waitcnt vmcnt(8)
	s_waitcnt lgkmcnt(0)
	s_barrier
	s_setprio 1
	s_waitcnt lgkmcnt(0)
	v_mfma_f32_16x16x32_bf16 v[124:127], v[146:149], v[206:209], v[124:127]
	v_mfma_f32_16x16x32_bf16 v[124:127], v[174:177], v[210:213], v[124:127]
	v_mfma_f32_16x16x32_bf16 v[120:123], v[178:181], v[206:209], v[120:123]
	v_mfma_f32_16x16x32_bf16 v[120:123], v[182:185], v[210:213], v[120:123]
	v_mfma_f32_16x16x32_bf16 v[108:111], v[146:149], v[214:217], v[108:111]
	v_mfma_f32_16x16x32_bf16 v[108:111], v[174:177], v[218:221], v[108:111]
	v_mfma_f32_16x16x32_bf16 v[104:107], v[178:181], v[214:217], v[104:107]
	v_mfma_f32_16x16x32_bf16 v[104:107], v[182:185], v[218:221], v[104:107]
	v_mfma_f32_16x16x32_bf16 v[92:95], v[146:149], v[222:225], v[92:95]
	v_mfma_f32_16x16x32_bf16 v[92:95], v[174:177], v[226:229], v[92:95]
	v_mfma_f32_16x16x32_bf16 v[88:91], v[178:181], v[222:225], v[88:91]
	v_mfma_f32_16x16x32_bf16 v[88:91], v[182:185], v[226:229], v[88:91]
	v_mfma_f32_16x16x32_bf16 v[76:79], v[146:149], v[230:233], v[76:79]
	v_mfma_f32_16x16x32_bf16 v[76:79], v[174:177], v[234:237], v[76:79]
	v_mfma_f32_16x16x32_bf16 v[72:75], v[178:181], v[230:233], v[72:75]
	v_mfma_f32_16x16x32_bf16 v[72:75], v[182:185], v[234:237], v[72:75]
	s_setprio 0
	s_setprio 1
	v_mfma_f32_16x16x32_bf16 v[116:119], v[186:189], v[206:209], v[116:119]
	v_mfma_f32_16x16x32_bf16 v[116:119], v[194:197], v[210:213], v[116:119]
	v_mfma_f32_16x16x32_bf16 v[112:115], v[198:201], v[206:209], v[112:115]
	v_mfma_f32_16x16x32_bf16 v[112:115], v[202:205], v[210:213], v[112:115]
	v_mfma_f32_16x16x32_bf16 v[100:103], v[186:189], v[214:217], v[100:103]
	v_mfma_f32_16x16x32_bf16 v[100:103], v[194:197], v[218:221], v[100:103]
	v_mfma_f32_16x16x32_bf16 v[96:99], v[198:201], v[214:217], v[96:99]
	v_mfma_f32_16x16x32_bf16 v[96:99], v[202:205], v[218:221], v[96:99]
	v_mfma_f32_16x16x32_bf16 v[84:87], v[186:189], v[222:225], v[84:87]
	v_mfma_f32_16x16x32_bf16 v[84:87], v[194:197], v[226:229], v[84:87]
	v_mfma_f32_16x16x32_bf16 v[80:83], v[198:201], v[222:225], v[80:83]
	v_mfma_f32_16x16x32_bf16 v[80:83], v[202:205], v[226:229], v[80:83]
	v_mfma_f32_16x16x32_bf16 v[68:71], v[186:189], v[230:233], v[68:71]
	v_mfma_f32_16x16x32_bf16 v[68:71], v[194:197], v[234:237], v[68:71]
	v_mfma_f32_16x16x32_bf16 v[64:67], v[198:201], v[230:233], v[64:67]
	v_mfma_f32_16x16x32_bf16 v[64:67], v[202:205], v[234:237], v[64:67]
	s_setprio 0
	s_barrier
; #define PG8_STAGE(bufoff, gbase, voff) do { _Pragma("unroll") for (int _i = 0; _i < 2; ++_i) \
;         __builtin_amdgcn_global_load_lds((const unsigned*)((const char*)(gbase) + (voff)[_i]), (LAS unsigned*)(lds + (bufoff) + ldsw + _i * 8192), 16, 0, 0); } while (0)
; #define PG8_LDA(dst, b, h) do { _Pragma("unroll") for (int m = 0; m < 4; ++m) _Pragma("unroll") for (int k = 0; k < 2; ++k) dst[m][k] = *(const LAS bf16x8*)(lds + PG8_SA(b, h) + aoff + m * 2048 + k * 1024); } while (0)
; #define PG8_MMA(ai, bj, At, Bt) do { __builtin_amdgcn_s_setprio(1); _Pragma("unroll") for (int m = 0; m < 4; ++m) _Pragma("unroll") for (int n = 0; n < 2; ++n) _Pragma("unroll") for (int k = 0; k < 2; ++k) \
;         acc[ai][bj][m][n] = __builtin_amdgcn_mfma_f32_16x16x32_bf16(Bt[n][k], At[m][k], acc[ai][bj][m][n], 0, 0, 0); __builtin_amdgcn_s_setprio(0); } while (0)
; #define PG8_WAIT_V(n) asm volatile("s_waitcnt vmcnt(" #n ")" ::: "memory")
; #define PG8_WAIT_L(n) asm volatile("s_waitcnt lgkmcnt(" #n ")" ::: "memory")
; #define PG8_BAR __builtin_amdgcn_s_barrier()
; #define PG8_SCHED __builtin_amdgcn_sched_barrier(0)
; template <class Epi, bool ALIGN_EPI>
; __device__ __forceinline__ void gemm_phase(LAS unsigned char* lds, const Gemm g, const StaticOrder& S, const Epi& E) {
;     ...
;             PG8_LDA(At, 1, 1); PG8_STAGE(PG8_SB(1, 0), b3, voffB); PG8_STAGE(PG8_SB(1, 1), b3 + hB, voffB); PG8_STAGE(PG8_SA(1, 0), a3, voffA);
;             PG8_WAIT_V(8); PG8_WAIT_L(0); PG8_BAR; PG8_MMA(1, 0, At, B0); PG8_MMA(1, 1, At, B1); PG8_BAR; PG8_SCHED;
;         }
	s_add_i32 s39, s39, s51
	v_lshl_add_u64 v[190:191], v[190:191], 0, s[20:21]
	s_mov_b32 m0, s39
	ds_read_b128 v[206:209], v155 offset:49152
	ds_read_b128 v[210:213], v155 offset:50176
	ds_read_b128 v[214:217], v155 offset:51200
	ds_read_b128 v[218:221], v155 offset:52224
	ds_read_b128 v[222:225], v155 offset:53248
	ds_read_b128 v[226:229], v155 offset:54272
	ds_read_b128 v[230:233], v155 offset:55296
	ds_read_b128 v[234:237], v155 offset:56320
	global_load_lds_dwordx4 v[190:191], off
	s_add_i32 m0, s39, 0x2000
	s_add_u32 s36, s36, 0x80080
	v_lshl_add_u64 v[190:191], v[238:239], 0, s[20:21]
	s_addc_u32 s37, s37, 0
	s_add_i32 s39, s46, s51
	global_load_lds_dwordx4 v[190:191], off
	s_waitcnt vmcnt(4)
	s_waitcnt lgkmcnt(0)
	s_barrier
	s_setprio 1
	s_waitcnt lgkmcnt(0)
	v_mfma_f32_16x16x32_bf16 v[60:63], v[146:149], v[206:209], v[60:63]
	v_mfma_f32_16x16x32_bf16 v[60:63], v[174:177], v[210:213], v[60:63]
	v_mfma_f32_16x16x32_bf16 v[56:59], v[178:181], v[206:209], v[56:59]
	v_mfma_f32_16x16x32_bf16 v[56:59], v[182:185], v[210:213], v[56:59]
	v_lshl_add_u64 v[190:191], s[36:37], 0, v[130:131]
	s_mov_b32 m0, s39
	s_nop 0
	global_load_lds_dwordx4 v[190:191], off
	v_mfma_f32_16x16x32_bf16 v[44:47], v[146:149], v[214:217], v[44:47]
	v_mfma_f32_16x16x32_bf16 v[44:47], v[174:177], v[218:221], v[44:47]
	v_mfma_f32_16x16x32_bf16 v[40:43], v[178:181], v[214:217], v[40:43]
	v_mfma_f32_16x16x32_bf16 v[40:43], v[182:185], v[218:221], v[40:43]
	v_mfma_f32_16x16x32_bf16 v[28:31], v[146:149], v[222:225], v[28:31]
	v_mfma_f32_16x16x32_bf16 v[28:31], v[174:177], v[226:229], v[28:31]
	v_lshl_add_u64 v[190:191], s[36:37], 0, v[134:135]
	s_add_i32 m0, s39, 0x2000
	s_nop 0
	global_load_lds_dwordx4 v[190:191], off
	v_mfma_f32_16x16x32_bf16 v[24:27], v[178:181], v[222:225], v[24:27]
	v_mfma_f32_16x16x32_bf16 v[24:27], v[182:185], v[226:229], v[24:27]
	v_mfma_f32_16x16x32_bf16 v[12:15], v[146:149], v[230:233], v[12:15]
	v_mfma_f32_16x16x32_bf16 v[12:15], v[174:177], v[234:237], v[12:15]
	v_mfma_f32_16x16x32_bf16 v[8:11], v[178:181], v[230:233], v[8:11]
	v_mfma_f32_16x16x32_bf16 v[8:11], v[182:185], v[234:237], v[8:11]
	s_setprio 0
	s_setprio 1
	v_mfma_f32_16x16x32_bf16 v[52:55], v[186:189], v[206:209], v[52:55]
	v_mfma_f32_16x16x32_bf16 v[52:55], v[194:197], v[210:213], v[52:55]
	v_lshl_add_u64 v[190:191], v[240:241], 0, s[20:21]
	s_mov_b32 m0, s57
	s_nop 0
	global_load_lds_dwordx4 v[190:191], off
	v_mfma_f32_16x16x32_bf16 v[48:51], v[198:201], v[206:209], v[48:51]
	v_mfma_f32_16x16x32_bf16 v[48:51], v[202:205], v[210:213], v[48:51]
	v_mfma_f32_16x16x32_bf16 v[36:39], v[186:189], v[214:217], v[36:39]
	v_mfma_f32_16x16x32_bf16 v[36:39], v[194:197], v[218:221], v[36:39]
	v_mfma_f32_16x16x32_bf16 v[32:35], v[198:201], v[214:217], v[32:35]
	v_mfma_f32_16x16x32_bf16 v[32:35], v[202:205], v[218:221], v[32:35]
	v_lshl_add_u64 v[190:191], v[242:243], 0, s[20:21]
	s_mov_b32 m0, s58
	s_nop 0
	global_load_lds_dwordx4 v[190:191], off
	v_mfma_f32_16x16x32_bf16 v[20:23], v[186:189], v[222:225], v[20:23]
	v_mfma_f32_16x16x32_bf16 v[20:23], v[194:197], v[226:229], v[20:23]
	v_mfma_f32_16x16x32_bf16 v[16:19], v[198:201], v[222:225], v[16:19]
	v_mfma_f32_16x16x32_bf16 v[16:19], v[202:205], v[226:229], v[16:19]
	v_mfma_f32_16x16x32_bf16 v[4:7], v[186:189], v[230:233], v[4:7]
	v_mfma_f32_16x16x32_bf16 v[4:7], v[194:197], v[234:237], v[4:7]
	v_mfma_f32_16x16x32_bf16 v[0:3], v[198:201], v[230:233], v[0:3]
	v_mfma_f32_16x16x32_bf16 v[0:3], v[202:205], v[234:237], v[0:3]
	s_setprio 0
	s_barrier
	s_add_i32 s38, s38, 2
	s_add_u32 s4, s4, 0x100
	s_addc_u32 s5, s5, 0
	s_add_u32 s27, s27, 0x100
	s_addc_u32 s29, s29, 0
	s_cmp_gt_u32 s38, 29
	s_cbranch_scc0 .LBB0_1094
	s_and_b64 vcc, exec, s[22:23]
	s_cbranch_vccz .LBB0_1097
	s_barrier

; #define PG8_STAGE(bufoff, gbase, voff) do { _Pragma("unroll") for (int _i = 0; _i < 2; ++_i) \
;         __builtin_amdgcn_global_load_lds((const unsigned*)((const char*)(gbase) + (voff)[_i]), (LAS unsigned*)(lds + (bufoff) + ldsw + _i * 8192), 16, 0, 0); } while (0)
; #define PG8_LDA(dst, b, h) do { _Pragma("unroll") for (int m = 0; m < 4; ++m) _Pragma("unroll") for (int k = 0; k < 2; ++k) dst[m][k] = *(const LAS bf16x8*)(lds + PG8_SA(b, h) + aoff + m * 2048 + k * 1024); } while (0)
; #define PG8_LDB(dst, b, h) do { _Pragma("unroll") for (int n = 0; n < 2; ++n) _Pragma("unroll") for (int k = 0; k < 2; ++k) dst[n][k] = *(const LAS bf16x8*)(lds + PG8_SB(b, h) + boff + n * 2048 + k * 1024); } while (0)
; #define PG8_MMA(ai, bj, At, Bt) do { __builtin_amdgcn_s_setprio(1); _Pragma("unroll") for (int m = 0; m < 4; ++m) _Pragma("unroll") for (int n = 0; n < 2; ++n) _Pragma("unroll") for (int k = 0; k < 2; ++k) \
;         acc[ai][bj][m][n] = __builtin_amdgcn_mfma_f32_16x16x32_bf16(Bt[n][k], At[m][k], acc[ai][bj][m][n], 0, 0, 0); __builtin_amdgcn_s_setprio(0); } while (0)
; #define PG8_WAIT_V(n) asm volatile("s_waitcnt vmcnt(" #n ")" ::: "memory")
; #define PG8_WAIT_L(n) asm volatile("s_waitcnt lgkmcnt(" #n ")" ::: "memory")
; #define PG8_BAR __builtin_amdgcn_s_barrier()
; #define PG8_SCHED __builtin_amdgcn_sched_barrier(0)
; template <class Epi, bool ALIGN_EPI>
; __device__ __forceinline__ void gemm_phase(LAS unsigned char* lds, const Gemm g, const StaticOrder& S, const Epi& E) {
;     ...
;             const char* a1 = cA + (size_t)(t + 1) * kstep;
;             const char* a2 = last ? nA : cA + (size_t)(t + 2) * kstep; const char* b2 = last ? nB : cB + (size_t)(t + 2) * kstep;
;             const char* a3 = a2 + kstep; const char* b3 = b2 + kstep;
;             PG8_LDB(B0, 0, 0); PG8_LDB(B1, 0, 1); PG8_SCHED; PG8_LDA(At, 0, 0); PG8_STAGE(PG8_SA(1, 1), a1 + hA, voffA);
;             PG8_WAIT_V(8); PG8_WAIT_L(0); PG8_BAR; PG8_MMA(0, 0, At, B0); PG8_MMA(0, 1, At, B1); PG8_BAR; PG8_SCHED;
;             PG8_LDA(At, 0, 1); PG8_STAGE(PG8_SB(0, 0), b2, voffB); PG8_STAGE(PG8_SB(0, 1), b2 + hB, voffB); PG8_STAGE(PG8_SA(0, 0), a2, voffA);
;             PG8_WAIT_V(8); PG8_WAIT_L(0); PG8_BAR; PG8_MMA(1, 0, At, B0); PG8_MMA(1, 1, At, B1); PG8_BAR; PG8_SCHED;
.LBB0_1585:
	ds_read_b128 v[128:131], v175
	ds_read_b128 v[132:135], v175 offset:1024
	ds_read_b128 v[136:139], v175 offset:2048
	ds_read_b128 v[140:143], v175 offset:3072
	ds_read_b128 v[160:163], v176
	ds_read_b128 v[164:167], v176 offset:1024
	ds_read_b128 v[168:171], v176 offset:2048
	ds_read_b128 v[180:183], v176 offset:3072
	s_add_u32 s40, s36, 0xfff80080
	s_addc_u32 s41, s37, -1
	s_cmp_eq_u32 s57, 28
	s_cselect_b32 s43, s25, s41
	s_cselect_b32 s42, s31, s40
	s_cselect_b32 s41, s23, s56
	s_cselect_b32 s40, s54, s55
	v_lshl_add_u64 v[218:219], s[36:37], 0, v[152:153]
	s_add_i32 m0, s35, 0xc000
	ds_read_b128 v[184:187], v177
	ds_read_b128 v[188:191], v177 offset:1024
	ds_read_b128 v[194:197], v177 offset:2048
	ds_read_b128 v[198:201], v177 offset:3072
	ds_read_b128 v[202:205], v177 offset:4096
	ds_read_b128 v[206:209], v177 offset:5120
	ds_read_b128 v[210:213], v177 offset:6144
	ds_read_b128 v[214:217], v177 offset:7168
	global_load_lds_dwordx4 v[218:219], off
	v_lshl_add_u64 v[218:219], s[36:37], 0, v[154:155]
	s_add_i32 m0, s35, 0xe000
	s_nop 0
	global_load_lds_dwordx4 v[218:219], off
	s_waitcnt vmcnt(8)
	s_waitcnt lgkmcnt(0)
	s_barrier
	s_setprio 1
	s_waitcnt lgkmcnt(0)
	v_mfma_f32_16x16x32_bf16 v[124:127], v[128:131], v[184:187], v[124:127]
	v_mfma_f32_16x16x32_bf16 v[124:127], v[132:135], v[188:191], v[124:127]
	v_mfma_f32_16x16x32_bf16 v[120:123], v[136:139], v[184:187], v[120:123]
	v_mfma_f32_16x16x32_bf16 v[120:123], v[140:143], v[188:191], v[120:123]
	v_mfma_f32_16x16x32_bf16 v[112:115], v[128:131], v[194:197], v[112:115]
	v_mfma_f32_16x16x32_bf16 v[112:115], v[132:135], v[198:201], v[112:115]
	v_mfma_f32_16x16x32_bf16 v[104:107], v[136:139], v[194:197], v[104:107]
	v_mfma_f32_16x16x32_bf16 v[104:107], v[140:143], v[198:201], v[104:107]
	v_mfma_f32_16x16x32_bf16 v[92:95], v[128:131], v[202:205], v[92:95]
	v_mfma_f32_16x16x32_bf16 v[92:95], v[132:135], v[206:209], v[92:95]
	v_mfma_f32_16x16x32_bf16 v[88:91], v[136:139], v[202:205], v[88:91]
	v_mfma_f32_16x16x32_bf16 v[88:91], v[140:143], v[206:209], v[88:91]
	v_mfma_f32_16x16x32_bf16 v[76:79], v[128:131], v[210:213], v[76:79]
	v_mfma_f32_16x16x32_bf16 v[76:79], v[132:135], v[214:217], v[76:79]
	v_mfma_f32_16x16x32_bf16 v[72:75], v[136:139], v[210:213], v[72:75]
	v_mfma_f32_16x16x32_bf16 v[72:75], v[140:143], v[214:217], v[72:75]
	s_setprio 0
	s_setprio 1
	v_mfma_f32_16x16x32_bf16 v[116:119], v[160:163], v[184:187], v[116:119]
	v_mfma_f32_16x16x32_bf16 v[116:119], v[164:167], v[188:191], v[116:119]
	v_mfma_f32_16x16x32_bf16 v[108:111], v[168:171], v[184:187], v[108:111]
	v_mfma_f32_16x16x32_bf16 v[108:111], v[180:183], v[188:191], v[108:111]
	v_mfma_f32_16x16x32_bf16 v[100:103], v[160:163], v[194:197], v[100:103]
	v_mfma_f32_16x16x32_bf16 v[100:103], v[164:167], v[198:201], v[100:103]
	v_mfma_f32_16x16x32_bf16 v[96:99], v[168:171], v[194:197], v[96:99]
	v_mfma_f32_16x16x32_bf16 v[96:99], v[180:183], v[198:201], v[96:99]
	v_mfma_f32_16x16x32_bf16 v[84:87], v[160:163], v[202:205], v[84:87]
	v_mfma_f32_16x16x32_bf16 v[84:87], v[164:167], v[206:209], v[84:87]
	v_mfma_f32_16x16x32_bf16 v[80:83], v[168:171], v[202:205], v[80:83]
	v_mfma_f32_16x16x32_bf16 v[80:83], v[180:183], v[206:209], v[80:83]
	v_mfma_f32_16x16x32_bf16 v[68:71], v[160:163], v[210:213], v[68:71]
	v_mfma_f32_16x16x32_bf16 v[68:71], v[164:167], v[214:217], v[68:71]
	v_mfma_f32_16x16x32_bf16 v[64:67], v[168:171], v[210:213], v[64:67]
	v_mfma_f32_16x16x32_bf16 v[64:67], v[180:183], v[214:217], v[64:67]
	s_setprio 0
	s_barrier
	s_add_i32 s58, s51, s33
	v_lshl_add_u64 v[218:219], s[40:41], 0, v[146:147]
	s_mov_b32 m0, s58
	ds_read_b128 v[184:187], v177 offset:16384
	ds_read_b128 v[188:191], v177 offset:17408
	ds_read_b128 v[194:197], v177 offset:18432
	ds_read_b128 v[198:201], v177 offset:19456
	ds_read_b128 v[202:205], v177 offset:20480
	ds_read_b128 v[206:209], v177 offset:21504
	ds_read_b128 v[210:213], v177 offset:22528
	ds_read_b128 v[214:217], v177 offset:23552
	global_load_lds_dwordx4 v[218:219], off
	s_add_i32 m0, s58, 0x2000
	s_add_u32 s58, s40, 0x80000
	v_lshl_add_u64 v[220:221], s[40:41], 0, v[150:151]
	s_addc_u32 s59, s41, 0
	s_add_i32 s60, s52, s33
	global_load_lds_dwordx4 v[220:221], off
	s_waitcnt vmcnt(4)
	s_waitcnt lgkmcnt(0)
	s_barrier
	s_setprio 1
	s_waitcnt lgkmcnt(0)
	v_mfma_f32_16x16x32_bf16 v[60:63], v[128:131], v[184:187], v[60:63]
	v_mfma_f32_16x16x32_bf16 v[60:63], v[132:135], v[188:191], v[60:63]
	v_mfma_f32_16x16x32_bf16 v[56:59], v[136:139], v[184:187], v[56:59]
	v_mfma_f32_16x16x32_bf16 v[56:59], v[140:143], v[188:191], v[56:59]
	v_lshl_add_u64 v[222:223], s[58:59], 0, v[146:147]
	s_mov_b32 m0, s60
	v_lshl_add_u64 v[224:225], s[42:43], 0, v[148:149]
	global_load_lds_dwordx4 v[222:223], off
	v_mfma_f32_16x16x32_bf16 v[44:47], v[128:131], v[194:197], v[44:47]
	v_mfma_f32_16x16x32_bf16 v[44:47], v[132:135], v[198:201], v[44:47]
	v_mfma_f32_16x16x32_bf16 v[40:43], v[136:139], v[194:197], v[40:43]
	v_mfma_f32_16x16x32_bf16 v[40:43], v[140:143], v[198:201], v[40:43]
	v_mfma_f32_16x16x32_bf16 v[28:31], v[128:131], v[202:205], v[28:31]
	v_mfma_f32_16x16x32_bf16 v[28:31], v[132:135], v[206:209], v[28:31]
	v_lshl_add_u64 v[222:223], s[58:59], 0, v[150:151]
	s_add_i32 m0, s60, 0x2000
	s_nop 0
	global_load_lds_dwordx4 v[222:223], off
	v_mfma_f32_16x16x32_bf16 v[24:27], v[136:139], v[202:205], v[24:27]
	v_mfma_f32_16x16x32_bf16 v[24:27], v[140:143], v[206:209], v[24:27]
	v_mfma_f32_16x16x32_bf16 v[12:15], v[128:131], v[210:213], v[12:15]
	v_mfma_f32_16x16x32_bf16 v[12:15], v[132:135], v[214:217], v[12:15]
	v_mfma_f32_16x16x32_bf16 v[8:11], v[136:139], v[210:213], v[8:11]
	v_mfma_f32_16x16x32_bf16 v[8:11], v[140:143], v[214:217], v[8:11]
	s_setprio 0
	s_setprio 1
	v_mfma_f32_16x16x32_bf16 v[52:55], v[160:163], v[184:187], v[52:55]
	v_mfma_f32_16x16x32_bf16 v[52:55], v[164:167], v[188:191], v[52:55]
	v_lshl_add_u64 v[222:223], s[42:43], 0, v[144:145]
	s_mov_b32 m0, s35
	s_nop 0
	global_load_lds_dwordx4 v[222:223], off
	v_mfma_f32_16x16x32_bf16 v[48:51], v[168:171], v[184:187], v[48:51]
	v_mfma_f32_16x16x32_bf16 v[48:51], v[180:183], v[188:191], v[48:51]
	v_mfma_f32_16x16x32_bf16 v[36:39], v[160:163], v[194:197], v[36:39]
	v_mfma_f32_16x16x32_bf16 v[36:39], v[164:167], v[198:201], v[36:39]
	v_mfma_f32_16x16x32_bf16 v[32:35], v[168:171], v[194:197], v[32:35]
	v_mfma_f32_16x16x32_bf16 v[32:35], v[180:183], v[198:201], v[32:35]
	s_mov_b32 m0, s38
	s_nop 0
	global_load_lds_dwordx4 v[224:225], off
	v_mfma_f32_16x16x32_bf16 v[20:23], v[160:163], v[202:205], v[20:23]
	v_mfma_f32_16x16x32_bf16 v[20:23], v[164:167], v[206:209], v[20:23]
	v_mfma_f32_16x16x32_bf16 v[16:19], v[168:171], v[202:205], v[16:19]
	v_mfma_f32_16x16x32_bf16 v[16:19], v[180:183], v[206:209], v[16:19]
	v_mfma_f32_16x16x32_bf16 v[4:7], v[160:163], v[210:213], v[4:7]
	v_mfma_f32_16x16x32_bf16 v[4:7], v[164:167], v[214:217], v[4:7]
	v_mfma_f32_16x16x32_bf16 v[0:3], v[168:171], v[210:213], v[0:3]
	v_mfma_f32_16x16x32_bf16 v[0:3], v[180:183], v[214:217], v[0:3]
	s_setprio 0
	s_barrier
; #define PG8_STAGE(bufoff, gbase, voff) do { _Pragma("unroll") for (int _i = 0; _i < 2; ++_i) \
;         __builtin_amdgcn_global_load_lds((const unsigned*)((const char*)(gbase) + (voff)[_i]), (LAS unsigned*)(lds + (bufoff) + ldsw + _i * 8192), 16, 0, 0); } while (0)
; #define PG8_LDA(dst, b, h) do { _Pragma("unroll") for (int m = 0; m < 4; ++m) _Pragma("unroll") for (int k = 0; k < 2; ++k) dst[m][k] = *(const LAS bf16x8*)(lds + PG8_SA(b, h) + aoff + m * 2048 + k * 1024); } while (0)
; #define PG8_LDB(dst, b, h) do { _Pragma("unroll") for (int n = 0; n < 2; ++n) _Pragma("unroll") for (int k = 0; k < 2; ++k) dst[n][k] = *(const LAS bf16x8*)(lds + PG8_SB(b, h) + boff + n * 2048 + k * 1024); } while (0)
; #define PG8_MMA(ai, bj, At, Bt) do { __builtin_amdgcn_s_setprio(1); _Pragma("unroll") for (int m = 0; m < 4; ++m) _Pragma("unroll") for (int n = 0; n < 2; ++n) _Pragma("unroll") for (int k = 0; k < 2; ++k) \
;         acc[ai][bj][m][n] = __builtin_amdgcn_mfma_f32_16x16x32_bf16(Bt[n][k], At[m][k], acc[ai][bj][m][n], 0, 0, 0); __builtin_amdgcn_s_setprio(0); } while (0)
; #define PG8_WAIT_V(n) asm volatile("s_waitcnt vmcnt(" #n ")" ::: "memory")
; #define PG8_WAIT_L(n) asm volatile("s_waitcnt lgkmcnt(" #n ")" ::: "memory")
; #define PG8_BAR __builtin_amdgcn_s_barrier()
; #define PG8_SCHED __builtin_amdgcn_sched_barrier(0)
; template <class Epi, bool ALIGN_EPI>
; __device__ __forceinline__ void gemm_phase(LAS unsigned char* lds, const Gemm g, const StaticOrder& S, const Epi& E) {
;     ...
;             PG8_LDB(B0, 1, 0); PG8_LDB(B1, 1, 1); PG8_SCHED; PG8_LDA(At, 1, 0); PG8_STAGE(PG8_SA(0, 1), a2 + hA, voffA);
;             PG8_WAIT_V(8); PG8_WAIT_L(0); PG8_BAR; PG8_MMA(0, 0, At, B0); PG8_MMA(0, 1, At, B1); PG8_BAR; PG8_SCHED;
	s_add_i32 s58, 0, 0x18000
	s_add_i32 s59, 0, 0x1c000
	v_add_u32_e32 v140, s58, v173
	v_add_u32_e32 v179, s59, v173
	ds_read_b128 v[128:131], v140
	ds_read_b128 v[132:135], v140 offset:1024
	ds_read_b128 v[136:139], v140 offset:2048
	ds_read_b128 v[140:143], v140 offset:3072
	ds_read_b128 v[160:163], v179
	ds_read_b128 v[164:167], v179 offset:1024
	ds_read_b128 v[168:171], v179 offset:2048
	ds_read_b128 v[180:183], v179 offset:3072
	s_add_u32 s42, s42, 0x80000
	s_addc_u32 s43, s43, 0
	s_mov_b32 m0, s39
	v_lshl_add_u64 v[226:227], s[42:43], 0, v[144:145]
	ds_read_b128 v[184:187], v177 offset:32768
	ds_read_b128 v[188:191], v177 offset:33792
	ds_read_b128 v[194:197], v177 offset:34816
	ds_read_b128 v[198:201], v177 offset:35840
	ds_read_b128 v[202:205], v177 offset:36864
	ds_read_b128 v[206:209], v177 offset:37888
	ds_read_b128 v[210:213], v177 offset:38912
	ds_read_b128 v[214:217], v177 offset:39936
	global_load_lds_dwordx4 v[226:227], off
	v_lshl_add_u64 v[226:227], s[42:43], 0, v[148:149]
	s_mov_b32 m0, s44
	s_nop 0
	global_load_lds_dwordx4 v[226:227], off
	s_waitcnt vmcnt(8)
	s_waitcnt lgkmcnt(0)
	s_barrier
	s_setprio 1
	s_waitcnt lgkmcnt(0)
	v_mfma_f32_16x16x32_bf16 v[124:127], v[128:131], v[184:187], v[124:127]
	v_mfma_f32_16x16x32_bf16 v[124:127], v[132:135], v[188:191], v[124:127]
	v_mfma_f32_16x16x32_bf16 v[120:123], v[136:139], v[184:187], v[120:123]
	v_mfma_f32_16x16x32_bf16 v[120:123], v[140:143], v[188:191], v[120:123]
	v_mfma_f32_16x16x32_bf16 v[112:115], v[128:131], v[194:197], v[112:115]
	v_mfma_f32_16x16x32_bf16 v[112:115], v[132:135], v[198:201], v[112:115]
	v_mfma_f32_16x16x32_bf16 v[104:107], v[136:139], v[194:197], v[104:107]
	v_mfma_f32_16x16x32_bf16 v[104:107], v[140:143], v[198:201], v[104:107]
	v_mfma_f32_16x16x32_bf16 v[92:95], v[128:131], v[202:205], v[92:95]
	v_mfma_f32_16x16x32_bf16 v[92:95], v[132:135], v[206:209], v[92:95]
	v_mfma_f32_16x16x32_bf16 v[88:91], v[136:139], v[202:205], v[88:91]
	v_mfma_f32_16x16x32_bf16 v[88:91], v[140:143], v[206:209], v[88:91]
	v_mfma_f32_16x16x32_bf16 v[76:79], v[128:131], v[210:213], v[76:79]
	v_mfma_f32_16x16x32_bf16 v[76:79], v[132:135], v[214:217], v[76:79]
	v_mfma_f32_16x16x32_bf16 v[72:75], v[136:139], v[210:213], v[72:75]
	v_mfma_f32_16x16x32_bf16 v[72:75], v[140:143], v[214:217], v[72:75]
	s_setprio 0
	s_setprio 1
	v_mfma_f32_16x16x32_bf16 v[116:119], v[160:163], v[184:187], v[116:119]
	v_mfma_f32_16x16x32_bf16 v[116:119], v[164:167], v[188:191], v[116:119]
	v_mfma_f32_16x16x32_bf16 v[108:111], v[168:171], v[184:187], v[108:111]
	v_mfma_f32_16x16x32_bf16 v[108:111], v[180:183], v[188:191], v[108:111]
	v_mfma_f32_16x16x32_bf16 v[100:103], v[160:163], v[194:197], v[100:103]
	v_mfma_f32_16x16x32_bf16 v[100:103], v[164:167], v[198:201], v[100:103]
	v_mfma_f32_16x16x32_bf16 v[96:99], v[168:171], v[194:197], v[96:99]
	v_mfma_f32_16x16x32_bf16 v[96:99], v[180:183], v[198:201], v[96:99]
	v_mfma_f32_16x16x32_bf16 v[84:87], v[160:163], v[202:205], v[84:87]
	v_mfma_f32_16x16x32_bf16 v[84:87], v[164:167], v[206:209], v[84:87]
	v_mfma_f32_16x16x32_bf16 v[80:83], v[168:171], v[202:205], v[80:83]
	v_mfma_f32_16x16x32_bf16 v[80:83], v[180:183], v[206:209], v[80:83]
	v_mfma_f32_16x16x32_bf16 v[68:71], v[160:163], v[210:213], v[68:71]
	v_mfma_f32_16x16x32_bf16 v[68:71], v[164:167], v[214:217], v[68:71]
	v_mfma_f32_16x16x32_bf16 v[64:67], v[168:171], v[210:213], v[64:67]
	v_mfma_f32_16x16x32_bf16 v[64:67], v[180:183], v[214:217], v[64:67]
	s_setprio 0
	s_barrier
; #define PG8_STAGE(bufoff, gbase, voff) do { _Pragma("unroll") for (int _i = 0; _i < 2; ++_i) \
;         __builtin_amdgcn_global_load_lds((const unsigned*)((const char*)(gbase) + (voff)[_i]), (LAS unsigned*)(lds + (bufoff) + ldsw + _i * 8192), 16, 0, 0); } while (0)
; #define PG8_LDA(dst, b, h) do { _Pragma("unroll") for (int m = 0; m < 4; ++m) _Pragma("unroll") for (int k = 0; k < 2; ++k) dst[m][k] = *(const LAS bf16x8*)(lds + PG8_SA(b, h) + aoff + m * 2048 + k * 1024); } while (0)
; #define PG8_MMA(ai, bj, At, Bt) do { __builtin_amdgcn_s_setprio(1); _Pragma("unroll") for (int m = 0; m < 4; ++m) _Pragma("unroll") for (int n = 0; n < 2; ++n) _Pragma("unroll") for (int k = 0; k < 2; ++k) \
;         acc[ai][bj][m][n] = __builtin_amdgcn_mfma_f32_16x16x32_bf16(Bt[n][k], At[m][k], acc[ai][bj][m][n], 0, 0, 0); __builtin_amdgcn_s_setprio(0); } while (0)
; #define PG8_WAIT_V(n) asm volatile("s_waitcnt vmcnt(" #n ")" ::: "memory")
; #define PG8_WAIT_L(n) asm volatile("s_waitcnt lgkmcnt(" #n ")" ::: "memory")
; #define PG8_BAR __builtin_amdgcn_s_barrier()
; #define PG8_SCHED __builtin_amdgcn_sched_barrier(0)
; template <class Epi, bool ALIGN_EPI>
; __device__ __forceinline__ void gemm_phase(LAS unsigned char* lds, const Gemm g, const StaticOrder& S, const Epi& E) {
;     ...
;             PG8_LDA(At, 1, 1); PG8_STAGE(PG8_SB(1, 0), b3, voffB); PG8_STAGE(PG8_SB(1, 1), b3 + hB, voffB); PG8_STAGE(PG8_SA(1, 0), a3, voffA);
;             PG8_WAIT_V(8); PG8_WAIT_L(0); PG8_BAR; PG8_MMA(1, 0, At, B0); PG8_MMA(1, 1, At, B1); PG8_BAR; PG8_SCHED;
;         }
	s_add_i32 s42, s58, s33
	v_lshl_add_u64 v[218:219], v[218:219], 0, s[18:19]
	s_mov_b32 m0, s42
	ds_read_b128 v[184:187], v177 offset:49152
	ds_read_b128 v[188:191], v177 offset:50176
	ds_read_b128 v[194:197], v177 offset:51200
	ds_read_b128 v[198:201], v177 offset:52224
	ds_read_b128 v[202:205], v177 offset:53248
	ds_read_b128 v[206:209], v177 offset:54272
	ds_read_b128 v[210:213], v177 offset:55296
	ds_read_b128 v[214:217], v177 offset:56320
	global_load_lds_dwordx4 v[218:219], off
	s_add_i32 m0, s42, 0x2000
	s_add_u32 s40, s40, 0x80080
	v_lshl_add_u64 v[218:219], v[220:221], 0, s[18:19]
	s_addc_u32 s41, s41, 0
	s_add_i32 s42, s59, s33
	global_load_lds_dwordx4 v[218:219], off
	s_waitcnt vmcnt(4)
	s_waitcnt lgkmcnt(0)
	s_barrier
	s_setprio 1
	s_waitcnt lgkmcnt(0)
	v_mfma_f32_16x16x32_bf16 v[60:63], v[128:131], v[184:187], v[60:63]
	v_mfma_f32_16x16x32_bf16 v[60:63], v[132:135], v[188:191], v[60:63]
	v_mfma_f32_16x16x32_bf16 v[56:59], v[136:139], v[184:187], v[56:59]
	v_mfma_f32_16x16x32_bf16 v[56:59], v[140:143], v[188:191], v[56:59]
	v_lshl_add_u64 v[218:219], s[40:41], 0, v[146:147]
	s_mov_b32 m0, s42
	s_nop 0
	global_load_lds_dwordx4 v[218:219], off
	v_mfma_f32_16x16x32_bf16 v[44:47], v[128:131], v[194:197], v[44:47]
	v_mfma_f32_16x16x32_bf16 v[44:47], v[132:135], v[198:201], v[44:47]
	v_mfma_f32_16x16x32_bf16 v[40:43], v[136:139], v[194:197], v[40:43]
	v_mfma_f32_16x16x32_bf16 v[40:43], v[140:143], v[198:201], v[40:43]
	v_mfma_f32_16x16x32_bf16 v[28:31], v[128:131], v[202:205], v[28:31]
	v_mfma_f32_16x16x32_bf16 v[28:31], v[132:135], v[206:209], v[28:31]
	v_lshl_add_u64 v[218:219], s[40:41], 0, v[150:151]
	s_add_i32 m0, s42, 0x2000
	s_nop 0
	global_load_lds_dwordx4 v[218:219], off
	v_mfma_f32_16x16x32_bf16 v[24:27], v[136:139], v[202:205], v[24:27]
	v_mfma_f32_16x16x32_bf16 v[24:27], v[140:143], v[206:209], v[24:27]
	v_mfma_f32_16x16x32_bf16 v[12:15], v[128:131], v[210:213], v[12:15]
	v_mfma_f32_16x16x32_bf16 v[12:15], v[132:135], v[214:217], v[12:15]
	v_mfma_f32_16x16x32_bf16 v[8:11], v[136:139], v[210:213], v[8:11]
	v_mfma_f32_16x16x32_bf16 v[8:11], v[140:143], v[214:217], v[8:11]
	s_setprio 0
	s_setprio 1
	v_mfma_f32_16x16x32_bf16 v[52:55], v[160:163], v[184:187], v[52:55]
	v_mfma_f32_16x16x32_bf16 v[52:55], v[164:167], v[188:191], v[52:55]
	v_lshl_add_u64 v[218:219], v[222:223], 0, s[18:19]
	s_mov_b32 m0, s48
	s_nop 0
	global_load_lds_dwordx4 v[218:219], off
	v_mfma_f32_16x16x32_bf16 v[48:51], v[168:171], v[184:187], v[48:51]
	v_mfma_f32_16x16x32_bf16 v[48:51], v[180:183], v[188:191], v[48:51]
	v_mfma_f32_16x16x32_bf16 v[36:39], v[160:163], v[194:197], v[36:39]
	v_mfma_f32_16x16x32_bf16 v[36:39], v[164:167], v[198:201], v[36:39]
	v_mfma_f32_16x16x32_bf16 v[32:35], v[168:171], v[194:197], v[32:35]
	v_mfma_f32_16x16x32_bf16 v[32:35], v[180:183], v[198:201], v[32:35]
	v_lshl_add_u64 v[218:219], v[224:225], 0, s[18:19]
	s_mov_b32 m0, s49
	s_nop 0
	global_load_lds_dwordx4 v[218:219], off
	v_mfma_f32_16x16x32_bf16 v[20:23], v[160:163], v[202:205], v[20:23]
	v_mfma_f32_16x16x32_bf16 v[20:23], v[164:167], v[206:209], v[20:23]
	v_mfma_f32_16x16x32_bf16 v[16:19], v[168:171], v[202:205], v[16:19]
	v_mfma_f32_16x16x32_bf16 v[16:19], v[180:183], v[206:209], v[16:19]
	v_mfma_f32_16x16x32_bf16 v[4:7], v[160:163], v[210:213], v[4:7]
	v_mfma_f32_16x16x32_bf16 v[4:7], v[164:167], v[214:217], v[4:7]
	v_mfma_f32_16x16x32_bf16 v[0:3], v[168:171], v[210:213], v[0:3]
	v_mfma_f32_16x16x32_bf16 v[0:3], v[180:183], v[214:217], v[0:3]
	s_setprio 0
	s_barrier
	s_add_i32 s57, s57, 2
	s_add_u32 s36, s36, 0x100
	s_addc_u32 s37, s37, 0
	s_add_u32 s55, s55, 0x100
	s_addc_u32 s56, s56, 0
	s_cmp_gt_u32 s57, 29
	s_cbranch_scc0 .LBB0_1585
	s_and_b64 vcc, exec, s[20:21]
	s_cbranch_vccz .LBB0_1588
	s_barrier

; #define PG8_STAGE(bufoff, gbase, voff) do { _Pragma("unroll") for (int _i = 0; _i < 2; ++_i) \
;         __builtin_amdgcn_global_load_lds((const unsigned*)((const char*)(gbase) + (voff)[_i]), (LAS unsigned*)(lds + (bufoff) + ldsw + _i * 8192), 16, 0, 0); } while (0)
; #define PG8_LDA(dst, b, h) do { _Pragma("unroll") for (int m = 0; m < 4; ++m) _Pragma("unroll") for (int k = 0; k < 2; ++k) dst[m][k] = *(const LAS bf16x8*)(lds + PG8_SA(b, h) + aoff + m * 2048 + k * 1024); } while (0)
; #define PG8_LDB(dst, b, h) do { _Pragma("unroll") for (int n = 0; n < 2; ++n) _Pragma("unroll") for (int k = 0; k < 2; ++k) dst[n][k] = *(const LAS bf16x8*)(lds + PG8_SB(b, h) + boff + n * 2048 + k * 1024); } while (0)
; #define PG8_MMA(ai, bj, At, Bt) do { __builtin_amdgcn_s_setprio(1); _Pragma("unroll") for (int m = 0; m < 4; ++m) _Pragma("unroll") for (int n = 0; n < 2; ++n) _Pragma("unroll") for (int k = 0; k < 2; ++k) \
;         acc[ai][bj][m][n] = __builtin_amdgcn_mfma_f32_16x16x32_bf16(Bt[n][k], At[m][k], acc[ai][bj][m][n], 0, 0, 0); __builtin_amdgcn_s_setprio(0); } while (0)
; #define PG8_WAIT_V(n) asm volatile("s_waitcnt vmcnt(" #n ")" ::: "memory")
; #define PG8_WAIT_L(n) asm volatile("s_waitcnt lgkmcnt(" #n ")" ::: "memory")
; #define PG8_BAR __builtin_amdgcn_s_barrier()
; #define PG8_SCHED __builtin_amdgcn_sched_barrier(0)
; template <class Epi, bool ALIGN_EPI>
; __device__ __forceinline__ void gemm_phase(LAS unsigned char* lds, const Gemm g, const StaticOrder& S, const Epi& E) {
;     ...
;             const char* a1 = cA + (size_t)(t + 1) * kstep;
;             const char* a2 = last ? nA : cA + (size_t)(t + 2) * kstep; const char* b2 = last ? nB : cB + (size_t)(t + 2) * kstep;
;             const char* a3 = a2 + kstep; const char* b3 = b2 + kstep;
;             PG8_LDB(B0, 0, 0); PG8_LDB(B1, 0, 1); PG8_SCHED; PG8_LDA(At, 0, 0); PG8_STAGE(PG8_SA(1, 1), a1 + hA, voffA);
;             PG8_WAIT_V(8); PG8_WAIT_L(0); PG8_BAR; PG8_MMA(0, 0, At, B0); PG8_MMA(0, 1, At, B1); PG8_BAR; PG8_SCHED;
;             PG8_LDA(At, 0, 1); PG8_STAGE(PG8_SB(0, 0), b2, voffB); PG8_STAGE(PG8_SB(0, 1), b2 + hB, voffB); PG8_STAGE(PG8_SA(0, 0), a2, voffA);
;             PG8_WAIT_V(8); PG8_WAIT_L(0); PG8_BAR; PG8_MMA(1, 0, At, B0); PG8_MMA(1, 1, At, B1); PG8_BAR; PG8_SCHED;
.LBB0_1755:
	ds_read_b128 v[128:131], v183
	ds_read_b128 v[132:135], v183 offset:1024
	ds_read_b128 v[152:155], v183 offset:2048
	ds_read_b128 v[156:159], v183 offset:3072
	ds_read_b128 v[160:163], v184
	ds_read_b128 v[164:167], v184 offset:1024
	ds_read_b128 v[168:171], v184 offset:2048
	ds_read_b128 v[172:175], v184 offset:3072
	s_add_u32 s30, s28, 0xffe00080
	s_addc_u32 s31, s29, -1
	s_cmpk_eq_i32 s51, 0x7c
	s_cselect_b32 s35, s5, s31
	s_cselect_b32 s34, s21, s30
	s_cselect_b32 s31, s19, s50
	s_cselect_b32 s30, s48, s49
	v_lshl_add_u64 v[214:215], s[28:29], 0, v[144:145]
	s_add_i32 m0, s27, 0xc000
	ds_read_b128 v[176:179], v185
	ds_read_b128 v[186:189], v185 offset:1024
	ds_read_b128 v[190:193], v185 offset:2048
	ds_read_b128 v[194:197], v185 offset:3072
	ds_read_b128 v[198:201], v185 offset:4096
	ds_read_b128 v[202:205], v185 offset:5120
	ds_read_b128 v[206:209], v185 offset:6144
	ds_read_b128 v[210:213], v185 offset:7168
	global_load_lds_dwordx4 v[214:215], off
	v_lshl_add_u64 v[214:215], s[28:29], 0, v[146:147]
	s_add_i32 m0, s27, 0xe000
	s_nop 0
	global_load_lds_dwordx4 v[214:215], off
	s_waitcnt vmcnt(8)
	s_waitcnt lgkmcnt(0)
	s_barrier
	s_setprio 1
	s_waitcnt lgkmcnt(0)
	v_mfma_f32_16x16x32_bf16 v[120:123], v[128:131], v[176:179], v[120:123]
	v_mfma_f32_16x16x32_bf16 v[120:123], v[132:135], v[186:189], v[120:123]
	v_mfma_f32_16x16x32_bf16 v[124:127], v[152:155], v[176:179], v[124:127]
	v_mfma_f32_16x16x32_bf16 v[124:127], v[156:159], v[186:189], v[124:127]
	v_mfma_f32_16x16x32_bf16 v[104:107], v[128:131], v[190:193], v[104:107]
	v_mfma_f32_16x16x32_bf16 v[104:107], v[132:135], v[194:197], v[104:107]
	v_mfma_f32_16x16x32_bf16 v[108:111], v[152:155], v[190:193], v[108:111]
	v_mfma_f32_16x16x32_bf16 v[108:111], v[156:159], v[194:197], v[108:111]
	v_mfma_f32_16x16x32_bf16 v[88:91], v[128:131], v[198:201], v[88:91]
	v_mfma_f32_16x16x32_bf16 v[88:91], v[132:135], v[202:205], v[88:91]
	v_mfma_f32_16x16x32_bf16 v[92:95], v[152:155], v[198:201], v[92:95]
	v_mfma_f32_16x16x32_bf16 v[92:95], v[156:159], v[202:205], v[92:95]
	v_mfma_f32_16x16x32_bf16 v[72:75], v[128:131], v[206:209], v[72:75]
	v_mfma_f32_16x16x32_bf16 v[72:75], v[132:135], v[210:213], v[72:75]
	v_mfma_f32_16x16x32_bf16 v[76:79], v[152:155], v[206:209], v[76:79]
	v_mfma_f32_16x16x32_bf16 v[76:79], v[156:159], v[210:213], v[76:79]
	s_setprio 0
	s_setprio 1
	v_mfma_f32_16x16x32_bf16 v[112:115], v[160:163], v[176:179], v[112:115]
	v_mfma_f32_16x16x32_bf16 v[112:115], v[164:167], v[186:189], v[112:115]
	v_mfma_f32_16x16x32_bf16 v[116:119], v[168:171], v[176:179], v[116:119]
	v_mfma_f32_16x16x32_bf16 v[116:119], v[172:175], v[186:189], v[116:119]
	v_mfma_f32_16x16x32_bf16 v[96:99], v[160:163], v[190:193], v[96:99]
	v_mfma_f32_16x16x32_bf16 v[96:99], v[164:167], v[194:197], v[96:99]
	v_mfma_f32_16x16x32_bf16 v[100:103], v[168:171], v[190:193], v[100:103]
	v_mfma_f32_16x16x32_bf16 v[100:103], v[172:175], v[194:197], v[100:103]
	v_mfma_f32_16x16x32_bf16 v[80:83], v[160:163], v[198:201], v[80:83]
	v_mfma_f32_16x16x32_bf16 v[80:83], v[164:167], v[202:205], v[80:83]
	v_mfma_f32_16x16x32_bf16 v[84:87], v[168:171], v[198:201], v[84:87]
	v_mfma_f32_16x16x32_bf16 v[84:87], v[172:175], v[202:205], v[84:87]
	v_mfma_f32_16x16x32_bf16 v[64:67], v[160:163], v[206:209], v[64:67]
	v_mfma_f32_16x16x32_bf16 v[64:67], v[164:167], v[210:213], v[64:67]
	v_mfma_f32_16x16x32_bf16 v[68:71], v[168:171], v[206:209], v[68:71]
	v_mfma_f32_16x16x32_bf16 v[68:71], v[172:175], v[210:213], v[68:71]
	s_setprio 0
	s_barrier
	s_add_i32 s52, s46, s37
	v_lshl_add_u64 v[214:215], s[30:31], 0, v[138:139]
	s_mov_b32 m0, s52
	ds_read_b128 v[176:179], v185 offset:16384
	ds_read_b128 v[186:189], v185 offset:17408
	ds_read_b128 v[190:193], v185 offset:18432
	ds_read_b128 v[194:197], v185 offset:19456
	ds_read_b128 v[198:201], v185 offset:20480
	ds_read_b128 v[202:205], v185 offset:21504
	ds_read_b128 v[206:209], v185 offset:22528
	ds_read_b128 v[210:213], v185 offset:23552
	global_load_lds_dwordx4 v[214:215], off
	s_add_i32 m0, s52, 0x2000
	s_add_u32 s52, s30, 0x200000
	v_lshl_add_u64 v[216:217], s[30:31], 0, v[142:143]
	s_addc_u32 s53, s31, 0
	s_add_i32 s54, s47, s37
	global_load_lds_dwordx4 v[216:217], off
	s_waitcnt vmcnt(4)
	s_waitcnt lgkmcnt(0)
	s_barrier
	s_setprio 1
	s_waitcnt lgkmcnt(0)
	v_mfma_f32_16x16x32_bf16 v[56:59], v[128:131], v[176:179], v[56:59]
	v_mfma_f32_16x16x32_bf16 v[56:59], v[132:135], v[186:189], v[56:59]
	v_mfma_f32_16x16x32_bf16 v[60:63], v[152:155], v[176:179], v[60:63]
	v_mfma_f32_16x16x32_bf16 v[60:63], v[156:159], v[186:189], v[60:63]
	v_lshl_add_u64 v[218:219], s[52:53], 0, v[138:139]
	s_mov_b32 m0, s54
	v_lshl_add_u64 v[220:221], s[34:35], 0, v[140:141]
	global_load_lds_dwordx4 v[218:219], off
	v_mfma_f32_16x16x32_bf16 v[40:43], v[128:131], v[190:193], v[40:43]
	v_mfma_f32_16x16x32_bf16 v[40:43], v[132:135], v[194:197], v[40:43]
	v_mfma_f32_16x16x32_bf16 v[44:47], v[152:155], v[190:193], v[44:47]
	v_mfma_f32_16x16x32_bf16 v[44:47], v[156:159], v[194:197], v[44:47]
	v_mfma_f32_16x16x32_bf16 v[24:27], v[128:131], v[198:201], v[24:27]
	v_mfma_f32_16x16x32_bf16 v[24:27], v[132:135], v[202:205], v[24:27]
	v_lshl_add_u64 v[218:219], s[52:53], 0, v[142:143]
	s_add_i32 m0, s54, 0x2000
	s_nop 0
	global_load_lds_dwordx4 v[218:219], off
	v_mfma_f32_16x16x32_bf16 v[28:31], v[152:155], v[198:201], v[28:31]
	v_mfma_f32_16x16x32_bf16 v[28:31], v[156:159], v[202:205], v[28:31]
	v_mfma_f32_16x16x32_bf16 v[8:11], v[128:131], v[206:209], v[8:11]
	v_mfma_f32_16x16x32_bf16 v[8:11], v[132:135], v[210:213], v[8:11]
	v_mfma_f32_16x16x32_bf16 v[12:15], v[152:155], v[206:209], v[12:15]
	v_mfma_f32_16x16x32_bf16 v[12:15], v[156:159], v[210:213], v[12:15]
	s_setprio 0
	s_setprio 1
	v_mfma_f32_16x16x32_bf16 v[48:51], v[160:163], v[176:179], v[48:51]
	v_mfma_f32_16x16x32_bf16 v[48:51], v[164:167], v[186:189], v[48:51]
	v_lshl_add_u64 v[218:219], s[34:35], 0, v[136:137]
	s_mov_b32 m0, s27
	s_nop 0
	global_load_lds_dwordx4 v[218:219], off
	v_mfma_f32_16x16x32_bf16 v[52:55], v[168:171], v[176:179], v[52:55]
	v_mfma_f32_16x16x32_bf16 v[52:55], v[172:175], v[186:189], v[52:55]
	v_mfma_f32_16x16x32_bf16 v[32:35], v[160:163], v[190:193], v[32:35]
	v_mfma_f32_16x16x32_bf16 v[32:35], v[164:167], v[194:197], v[32:35]
	v_mfma_f32_16x16x32_bf16 v[36:39], v[168:171], v[190:193], v[36:39]
	v_mfma_f32_16x16x32_bf16 v[36:39], v[172:175], v[194:197], v[36:39]
	s_mov_b32 m0, s38
	s_nop 0
	global_load_lds_dwordx4 v[220:221], off
	v_mfma_f32_16x16x32_bf16 v[16:19], v[160:163], v[198:201], v[16:19]
	v_mfma_f32_16x16x32_bf16 v[16:19], v[164:167], v[202:205], v[16:19]
	v_mfma_f32_16x16x32_bf16 v[20:23], v[168:171], v[198:201], v[20:23]
	v_mfma_f32_16x16x32_bf16 v[20:23], v[172:175], v[202:205], v[20:23]
	v_mfma_f32_16x16x32_bf16 v[4:7], v[160:163], v[206:209], v[4:7]
	v_mfma_f32_16x16x32_bf16 v[4:7], v[164:167], v[210:213], v[4:7]
	v_mfma_f32_16x16x32_bf16 v[0:3], v[168:171], v[206:209], v[0:3]
	v_mfma_f32_16x16x32_bf16 v[0:3], v[172:175], v[210:213], v[0:3]
	s_setprio 0
	s_barrier
; #define PG8_STAGE(bufoff, gbase, voff) do { _Pragma("unroll") for (int _i = 0; _i < 2; ++_i) \
;         __builtin_amdgcn_global_load_lds((const unsigned*)((const char*)(gbase) + (voff)[_i]), (LAS unsigned*)(lds + (bufoff) + ldsw + _i * 8192), 16, 0, 0); } while (0)
; #define PG8_LDA(dst, b, h) do { _Pragma("unroll") for (int m = 0; m < 4; ++m) _Pragma("unroll") for (int k = 0; k < 2; ++k) dst[m][k] = *(const LAS bf16x8*)(lds + PG8_SA(b, h) + aoff + m * 2048 + k * 1024); } while (0)
; #define PG8_LDB(dst, b, h) do { _Pragma("unroll") for (int n = 0; n < 2; ++n) _Pragma("unroll") for (int k = 0; k < 2; ++k) dst[n][k] = *(const LAS bf16x8*)(lds + PG8_SB(b, h) + boff + n * 2048 + k * 1024); } while (0)
; #define PG8_MMA(ai, bj, At, Bt) do { __builtin_amdgcn_s_setprio(1); _Pragma("unroll") for (int m = 0; m < 4; ++m) _Pragma("unroll") for (int n = 0; n < 2; ++n) _Pragma("unroll") for (int k = 0; k < 2; ++k) \
;         acc[ai][bj][m][n] = __builtin_amdgcn_mfma_f32_16x16x32_bf16(Bt[n][k], At[m][k], acc[ai][bj][m][n], 0, 0, 0); __builtin_amdgcn_s_setprio(0); } while (0)
; #define PG8_WAIT_V(n) asm volatile("s_waitcnt vmcnt(" #n ")" ::: "memory")
; #define PG8_WAIT_L(n) asm volatile("s_waitcnt lgkmcnt(" #n ")" ::: "memory")
; #define PG8_BAR __builtin_amdgcn_s_barrier()
; #define PG8_SCHED __builtin_amdgcn_sched_barrier(0)
; template <class Epi, bool ALIGN_EPI>
; __device__ __forceinline__ void gemm_phase(LAS unsigned char* lds, const Gemm g, const StaticOrder& S, const Epi& E) {
;     ...
;             PG8_LDB(B0, 1, 0); PG8_LDB(B1, 1, 1); PG8_SCHED; PG8_LDA(At, 1, 0); PG8_STAGE(PG8_SA(0, 1), a2 + hA, voffA);
;             PG8_WAIT_V(8); PG8_WAIT_L(0); PG8_BAR; PG8_MMA(0, 0, At, B0); PG8_MMA(0, 1, At, B1); PG8_BAR; PG8_SCHED;
	s_add_i32 s52, 0, 0x18000
	s_add_i32 s53, 0, 0x1c000
	v_add_u32_e32 v156, s52, v181
	v_add_u32_e32 v172, s53, v181
	ds_read_b128 v[128:131], v156
	ds_read_b128 v[132:135], v156 offset:1024
	ds_read_b128 v[152:155], v156 offset:2048
	ds_read_b128 v[156:159], v156 offset:3072
	ds_read_b128 v[160:163], v172
	ds_read_b128 v[164:167], v172 offset:1024
	ds_read_b128 v[168:171], v172 offset:2048
	ds_read_b128 v[172:175], v172 offset:3072
	s_add_u32 s34, s34, 0x200000
	s_addc_u32 s35, s35, 0
	s_mov_b32 m0, s39
	v_lshl_add_u64 v[222:223], s[34:35], 0, v[136:137]
	ds_read_b128 v[176:179], v185 offset:32768
	ds_read_b128 v[186:189], v185 offset:33792
	ds_read_b128 v[190:193], v185 offset:34816
	ds_read_b128 v[194:197], v185 offset:35840
	ds_read_b128 v[198:201], v185 offset:36864
	ds_read_b128 v[202:205], v185 offset:37888
	ds_read_b128 v[206:209], v185 offset:38912
	ds_read_b128 v[210:213], v185 offset:39936
	global_load_lds_dwordx4 v[222:223], off
	v_lshl_add_u64 v[222:223], s[34:35], 0, v[140:141]
	s_mov_b32 m0, s40
	s_nop 0
	global_load_lds_dwordx4 v[222:223], off
	s_waitcnt vmcnt(8)
	s_waitcnt lgkmcnt(0)
	s_barrier
	s_setprio 1
	s_waitcnt lgkmcnt(0)
	v_mfma_f32_16x16x32_bf16 v[120:123], v[128:131], v[176:179], v[120:123]
	v_mfma_f32_16x16x32_bf16 v[120:123], v[132:135], v[186:189], v[120:123]
	v_mfma_f32_16x16x32_bf16 v[124:127], v[152:155], v[176:179], v[124:127]
	v_mfma_f32_16x16x32_bf16 v[124:127], v[156:159], v[186:189], v[124:127]
	v_mfma_f32_16x16x32_bf16 v[104:107], v[128:131], v[190:193], v[104:107]
	v_mfma_f32_16x16x32_bf16 v[104:107], v[132:135], v[194:197], v[104:107]
	v_mfma_f32_16x16x32_bf16 v[108:111], v[152:155], v[190:193], v[108:111]
	v_mfma_f32_16x16x32_bf16 v[108:111], v[156:159], v[194:197], v[108:111]
	v_mfma_f32_16x16x32_bf16 v[88:91], v[128:131], v[198:201], v[88:91]
	v_mfma_f32_16x16x32_bf16 v[88:91], v[132:135], v[202:205], v[88:91]
	v_mfma_f32_16x16x32_bf16 v[92:95], v[152:155], v[198:201], v[92:95]
	v_mfma_f32_16x16x32_bf16 v[92:95], v[156:159], v[202:205], v[92:95]
	v_mfma_f32_16x16x32_bf16 v[72:75], v[128:131], v[206:209], v[72:75]
	v_mfma_f32_16x16x32_bf16 v[72:75], v[132:135], v[210:213], v[72:75]
	v_mfma_f32_16x16x32_bf16 v[76:79], v[152:155], v[206:209], v[76:79]
	v_mfma_f32_16x16x32_bf16 v[76:79], v[156:159], v[210:213], v[76:79]
	s_setprio 0
	s_setprio 1
	v_mfma_f32_16x16x32_bf16 v[112:115], v[160:163], v[176:179], v[112:115]
	v_mfma_f32_16x16x32_bf16 v[112:115], v[164:167], v[186:189], v[112:115]
	v_mfma_f32_16x16x32_bf16 v[116:119], v[168:171], v[176:179], v[116:119]
	v_mfma_f32_16x16x32_bf16 v[116:119], v[172:175], v[186:189], v[116:119]
	v_mfma_f32_16x16x32_bf16 v[96:99], v[160:163], v[190:193], v[96:99]
	v_mfma_f32_16x16x32_bf16 v[96:99], v[164:167], v[194:197], v[96:99]
	v_mfma_f32_16x16x32_bf16 v[100:103], v[168:171], v[190:193], v[100:103]
	v_mfma_f32_16x16x32_bf16 v[100:103], v[172:175], v[194:197], v[100:103]
	v_mfma_f32_16x16x32_bf16 v[80:83], v[160:163], v[198:201], v[80:83]
	v_mfma_f32_16x16x32_bf16 v[80:83], v[164:167], v[202:205], v[80:83]
	v_mfma_f32_16x16x32_bf16 v[84:87], v[168:171], v[198:201], v[84:87]
	v_mfma_f32_16x16x32_bf16 v[84:87], v[172:175], v[202:205], v[84:87]
	v_mfma_f32_16x16x32_bf16 v[64:67], v[160:163], v[206:209], v[64:67]
	v_mfma_f32_16x16x32_bf16 v[64:67], v[164:167], v[210:213], v[64:67]
	v_mfma_f32_16x16x32_bf16 v[68:71], v[168:171], v[206:209], v[68:71]
	v_mfma_f32_16x16x32_bf16 v[68:71], v[172:175], v[210:213], v[68:71]
	s_setprio 0
	s_barrier
; #define PG8_STAGE(bufoff, gbase, voff) do { _Pragma("unroll") for (int _i = 0; _i < 2; ++_i) \
;         __builtin_amdgcn_global_load_lds((const unsigned*)((const char*)(gbase) + (voff)[_i]), (LAS unsigned*)(lds + (bufoff) + ldsw + _i * 8192), 16, 0, 0); } while (0)
; #define PG8_LDA(dst, b, h) do { _Pragma("unroll") for (int m = 0; m < 4; ++m) _Pragma("unroll") for (int k = 0; k < 2; ++k) dst[m][k] = *(const LAS bf16x8*)(lds + PG8_SA(b, h) + aoff + m * 2048 + k * 1024); } while (0)
; #define PG8_MMA(ai, bj, At, Bt) do { __builtin_amdgcn_s_setprio(1); _Pragma("unroll") for (int m = 0; m < 4; ++m) _Pragma("unroll") for (int n = 0; n < 2; ++n) _Pragma("unroll") for (int k = 0; k < 2; ++k) \
;         acc[ai][bj][m][n] = __builtin_amdgcn_mfma_f32_16x16x32_bf16(Bt[n][k], At[m][k], acc[ai][bj][m][n], 0, 0, 0); __builtin_amdgcn_s_setprio(0); } while (0)
; #define PG8_WAIT_V(n) asm volatile("s_waitcnt vmcnt(" #n ")" ::: "memory")
; #define PG8_WAIT_L(n) asm volatile("s_waitcnt lgkmcnt(" #n ")" ::: "memory")
; #define PG8_BAR __builtin_amdgcn_s_barrier()
; #define PG8_SCHED __builtin_amdgcn_sched_barrier(0)
; template <class Epi, bool ALIGN_EPI>
; __device__ __forceinline__ void gemm_phase(LAS unsigned char* lds, const Gemm g, const StaticOrder& S, const Epi& E) {
;     ...
;             PG8_LDA(At, 1, 1); PG8_STAGE(PG8_SB(1, 0), b3, voffB); PG8_STAGE(PG8_SB(1, 1), b3 + hB, voffB); PG8_STAGE(PG8_SA(1, 0), a3, voffA);
;             PG8_WAIT_V(8); PG8_WAIT_L(0); PG8_BAR; PG8_MMA(1, 0, At, B0); PG8_MMA(1, 1, At, B1); PG8_BAR; PG8_SCHED;
;         }
	s_add_i32 s34, s52, s37
	v_lshl_add_u64 v[214:215], v[214:215], 0, s[12:13]
	s_mov_b32 m0, s34
	ds_read_b128 v[176:179], v185 offset:49152
	ds_read_b128 v[186:189], v185 offset:50176
	ds_read_b128 v[190:193], v185 offset:51200
	ds_read_b128 v[194:197], v185 offset:52224
	ds_read_b128 v[198:201], v185 offset:53248
	ds_read_b128 v[202:205], v185 offset:54272
	ds_read_b128 v[206:209], v185 offset:55296
	ds_read_b128 v[210:213], v185 offset:56320
	global_load_lds_dwordx4 v[214:215], off
	s_add_i32 m0, s34, 0x2000
	s_add_u32 s30, s30, 0x200080
	v_lshl_add_u64 v[214:215], v[216:217], 0, s[12:13]
	s_addc_u32 s31, s31, 0
	s_add_i32 s34, s53, s37
	global_load_lds_dwordx4 v[214:215], off
	s_waitcnt vmcnt(4)
	s_waitcnt lgkmcnt(0)
	s_barrier
	s_setprio 1
	s_waitcnt lgkmcnt(0)
	v_mfma_f32_16x16x32_bf16 v[56:59], v[128:131], v[176:179], v[56:59]
	v_mfma_f32_16x16x32_bf16 v[56:59], v[132:135], v[186:189], v[56:59]
	v_mfma_f32_16x16x32_bf16 v[60:63], v[152:155], v[176:179], v[60:63]
	v_mfma_f32_16x16x32_bf16 v[60:63], v[156:159], v[186:189], v[60:63]
	v_lshl_add_u64 v[214:215], s[30:31], 0, v[138:139]
	s_mov_b32 m0, s34
	s_nop 0
	global_load_lds_dwordx4 v[214:215], off
	v_mfma_f32_16x16x32_bf16 v[40:43], v[128:131], v[190:193], v[40:43]
	v_mfma_f32_16x16x32_bf16 v[40:43], v[132:135], v[194:197], v[40:43]
	v_mfma_f32_16x16x32_bf16 v[44:47], v[152:155], v[190:193], v[44:47]
	v_mfma_f32_16x16x32_bf16 v[44:47], v[156:159], v[194:197], v[44:47]
	v_mfma_f32_16x16x32_bf16 v[24:27], v[128:131], v[198:201], v[24:27]
	v_mfma_f32_16x16x32_bf16 v[24:27], v[132:135], v[202:205], v[24:27]
	v_lshl_add_u64 v[214:215], s[30:31], 0, v[142:143]
	s_add_i32 m0, s34, 0x2000
	s_nop 0
	global_load_lds_dwordx4 v[214:215], off
	v_mfma_f32_16x16x32_bf16 v[28:31], v[152:155], v[198:201], v[28:31]
	v_mfma_f32_16x16x32_bf16 v[28:31], v[156:159], v[202:205], v[28:31]
	v_mfma_f32_16x16x32_bf16 v[8:11], v[128:131], v[206:209], v[8:11]
	v_mfma_f32_16x16x32_bf16 v[8:11], v[132:135], v[210:213], v[8:11]
	v_mfma_f32_16x16x32_bf16 v[12:15], v[152:155], v[206:209], v[12:15]
	v_mfma_f32_16x16x32_bf16 v[12:15], v[156:159], v[210:213], v[12:15]
	s_setprio 0
	s_setprio 1
	v_mfma_f32_16x16x32_bf16 v[48:51], v[160:163], v[176:179], v[48:51]
	v_mfma_f32_16x16x32_bf16 v[48:51], v[164:167], v[186:189], v[48:51]
	v_lshl_add_u64 v[214:215], v[218:219], 0, s[12:13]
	s_mov_b32 m0, s44
	s_nop 0
	global_load_lds_dwordx4 v[214:215], off
	v_mfma_f32_16x16x32_bf16 v[52:55], v[168:171], v[176:179], v[52:55]
	v_mfma_f32_16x16x32_bf16 v[52:55], v[172:175], v[186:189], v[52:55]
	v_mfma_f32_16x16x32_bf16 v[32:35], v[160:163], v[190:193], v[32:35]
	v_mfma_f32_16x16x32_bf16 v[32:35], v[164:167], v[194:197], v[32:35]
	v_mfma_f32_16x16x32_bf16 v[36:39], v[168:171], v[190:193], v[36:39]
	v_mfma_f32_16x16x32_bf16 v[36:39], v[172:175], v[194:197], v[36:39]
	v_lshl_add_u64 v[214:215], v[220:221], 0, s[12:13]
	s_mov_b32 m0, s45
	s_nop 0
	global_load_lds_dwordx4 v[214:215], off
	v_mfma_f32_16x16x32_bf16 v[16:19], v[160:163], v[198:201], v[16:19]
	v_mfma_f32_16x16x32_bf16 v[16:19], v[164:167], v[202:205], v[16:19]
	v_mfma_f32_16x16x32_bf16 v[20:23], v[168:171], v[198:201], v[20:23]
	v_mfma_f32_16x16x32_bf16 v[20:23], v[172:175], v[202:205], v[20:23]
	v_mfma_f32_16x16x32_bf16 v[4:7], v[160:163], v[206:209], v[4:7]
	v_mfma_f32_16x16x32_bf16 v[4:7], v[164:167], v[210:213], v[4:7]
	v_mfma_f32_16x16x32_bf16 v[0:3], v[168:171], v[206:209], v[0:3]
	v_mfma_f32_16x16x32_bf16 v[0:3], v[172:175], v[210:213], v[0:3]
	s_setprio 0
	s_barrier
	s_add_i32 s51, s51, 2
	s_add_u32 s28, s28, 0x100
	s_addc_u32 s29, s29, 0
	s_add_u32 s49, s49, 0x100
	s_addc_u32 s50, s50, 0
	s_cmpk_gt_u32 s51, 0x7d
	s_cbranch_scc0 .LBB0_1755
	s_and_b64 vcc, exec, s[14:15]
	s_cbranch_vccz .LBB0_1758
	s_barrier
